# adds: QK/QS frag pipelining in scan, combine L2 prefetch, write-through sc1 on GEMM epilogue stores
# speedup vs baseline: 1.0030x; 1.0030x over previous
.LBB0_92:
	s_or_b64 exec, exec, s[4:5]
	v_mov_b32_e32 v131, v148
	s_movk_i32 s1, 0x60
	v_and_b32_e32 v128, 15, v131
	v_lshrrev_b32_e32 v130, 1, v131
	v_lshrrev_b32_e32 v133, 2, v131
	v_and_or_b32 v132, v130, s1, v128
	v_ashrrev_i32_e32 v130, 2, v131
	v_and_b32_e32 v133, 12, v133
	s_mov_b32 s1, 0x7fffffc0
	v_and_or_b32 v133, v130, s1, v133
	v_cvt_pk_bf16_f32 v124, v124, v125
	v_cvt_pk_bf16_f32 v125, v126, v127
	v_mul_u32_u24_e32 v126, 0x110, v132
	v_lshl_add_u32 v126, v133, 1, v126
	s_add_i32 s1, s0, 0x3fff0000
	v_cvt_pk_bf16_f32 v120, v120, v121
	v_cvt_pk_bf16_f32 v121, v122, v123
	v_cvt_pk_bf16_f32 v116, v116, v117
	v_cvt_pk_bf16_f32 v117, v118, v119
	v_cvt_pk_bf16_f32 v112, v112, v113
	v_cvt_pk_bf16_f32 v113, v114, v115
	v_add_u32_e32 v122, 0x1000, v126
	v_lshlrev_b32_e32 v130, 4, v128
	v_lshlrev_b32_e32 v128, 3, v131
	s_lshr_b32 s1, s1, 8
	v_readlane_b32 s4, v255, 33
	ds_write2_b64 v126, v[124:125], v[116:117] offset1:4
	ds_write2_b64 v122, v[120:121], v[112:113] offset0:32 offset1:36
	v_cvt_pk_bf16_f32 v104, v104, v105
	v_cvt_pk_bf16_f32 v105, v106, v107
	v_cvt_pk_bf16_f32 v96, v96, v97
	v_cvt_pk_bf16_f32 v97, v98, v99
	v_ashrrev_i32_e32 v123, 4, v131
	v_and_b32_e32 v128, 64, v128
	s_ashr_i32 s4, s4, 5
	v_mov_b32_e32 v136, s0
	s_movk_i32 s5, 0x1f40
	ds_write2_b64 v122, v[104:105], v[96:97] offset0:40 offset1:44
	v_add_u32_e32 v96, s78, v123
	s_movk_i32 s8, 0xc00
	v_mov_b32_e32 v97, s1
	s_movk_i32 s1, 0x110
	v_or_b32_e32 v134, s0, v128
	v_or_b32_e32 v135, 0x2000, v128
	v_bitop3_b32 v128, v128, s5, v136 bitop3:0xc8
	v_cvt_pk_bf16_f32 v108, v108, v109
	v_cvt_pk_bf16_f32 v109, v110, v111
	v_cvt_pk_bf16_f32 v100, v100, v101
	v_cvt_pk_bf16_f32 v101, v102, v103
	v_cmp_gt_i32_e32 vcc, s8, v96
	v_mov_b32_e32 v133, s4
	v_mad_u64_u32 v[98:99], s[4:5], v123, s1, v[130:131]
	ds_write2_b64 v126, v[108:109], v[100:101] offset0:8 offset1:12
	v_cmp_gt_i32_e64 s[6:7], s51, v134
	v_cndmask_b32_e32 v99, v146, v147, vcc
	v_cndmask_b32_e32 v108, v153, v154, vcc
	v_cndmask_b32_e64 v97, v97, v133, s[6:7]
	v_and_b32_e32 v99, v99, v96
	v_cndmask_b32_e32 v101, v149, v152, vcc
	v_and_b32_e32 v96, v108, v96
	v_mov_b32_e32 v124, s57
	v_mov_b32_e32 v125, s69
	v_mov_b32_e32 v127, s56
	v_mov_b32_e32 v132, s68
	v_cndmask_b32_e64 v100, v135, v128, s[6:7]
	v_add3_u32 v99, v99, v101, v96
	v_lshlrev_b32_e32 v135, 10, v97
	v_cndmask_b32_e32 v107, v124, v125, vcc
	v_cndmask_b32_e32 v106, v127, v132, vcc
	v_add_u32_e32 v96, v99, v135
	v_mad_i64_i32 v[96:97], s[4:5], v96, s3, v[106:107]
	v_lshlrev_b32_e32 v128, 1, v100
	v_lshl_add_u64 v[100:101], v[96:97], 0, v[128:129]
	v_lshlrev_b32_e32 v96, 4, v131
	v_and_b32_e32 v96, 0x70, v96
	v_mov_b32_e32 v97, v129
	s_waitcnt vmcnt(0) lgkmcnt(0)
	s_barrier
	ds_read_b128 v[102:105], v98
	v_lshl_add_u64 v[108:109], v[100:101], 0, v[96:97]
	v_add_u32_e32 v100, 0x200, v131
	v_ashrrev_i32_e32 v136, 4, v100
	v_mad_u64_u32 v[100:101], s[4:5], v136, s1, v[130:131]
	v_add_u32_e32 v101, s78, v136
	v_cmp_gt_i32_e32 vcc, s8, v101
	ds_read_b128 v[110:113], v100
	s_waitcnt lgkmcnt(1)
	global_store_dwordx4 v[108:109], v[102:105], off sc1
	v_cndmask_b32_e32 v109, v124, v125, vcc
	v_cndmask_b32_e32 v108, v127, v132, vcc
	v_cndmask_b32_e32 v102, v146, v147, vcc
	v_cndmask_b32_e32 v104, v153, v154, vcc
	v_and_b32_e32 v102, v102, v101
	v_cndmask_b32_e32 v103, v149, v152, vcc
	v_and_b32_e32 v101, v104, v101
	v_add3_u32 v101, v102, v103, v101
	v_add_u32_e32 v102, v101, v135
	v_mad_i64_i32 v[102:103], s[4:5], v102, s3, v[108:109]
	v_lshl_add_u64 v[102:103], v[102:103], 0, v[128:129]
	v_lshl_add_u64 v[102:103], v[102:103], 0, v[96:97]
	s_waitcnt lgkmcnt(0)
	global_store_dwordx4 v[102:103], v[110:113], off sc1
	v_add_u32_e32 v102, 0x400, v131
	v_ashrrev_i32_e32 v137, 4, v102
	v_add_u32_e32 v104, s78, v137
	v_cmp_gt_i32_e32 vcc, s8, v104
	v_mad_u64_u32 v[102:103], s[4:5], v137, s1, v[130:131]
	s_nop 0
	v_cndmask_b32_e32 v103, v146, v147, vcc
	v_cndmask_b32_e32 v114, v153, v154, vcc
	v_and_b32_e32 v103, v103, v104
	v_cndmask_b32_e32 v105, v149, v152, vcc
	v_and_b32_e32 v104, v114, v104
	v_add3_u32 v103, v103, v105, v104
	v_cndmask_b32_e32 v119, v124, v125, vcc
	v_cndmask_b32_e32 v118, v127, v132, vcc
	v_add_u32_e32 v104, v103, v135
	v_mad_i64_i32 v[104:105], s[4:5], v104, s3, v[118:119]
	v_lshl_add_u64 v[104:105], v[104:105], 0, v[128:129]
	ds_read_b128 v[110:113], v102
	v_lshl_add_u64 v[120:121], v[104:105], 0, v[96:97]
	v_add_u32_e32 v104, 0x600, v131
	v_ashrrev_i32_e32 v131, 4, v104
	v_mad_u64_u32 v[104:105], s[4:5], v131, s1, v[130:131]
	v_add_u32_e32 v105, s78, v131
	v_cmp_gt_i32_e32 vcc, s8, v105
	ds_read_b128 v[114:117], v104
	s_waitcnt lgkmcnt(1)
	global_store_dwordx4 v[120:121], v[110:113], off sc1
	v_cndmask_b32_e32 v120, v153, v154, vcc
	v_cvt_pk_bf16_f32 v92, v92, v93
	v_cndmask_b32_e32 v112, v146, v147, vcc
	v_and_b32_e32 v112, v112, v105
	v_cndmask_b32_e32 v113, v149, v152, vcc
	v_and_b32_e32 v105, v120, v105
	v_add3_u32 v105, v112, v113, v105
	v_cndmask_b32_e32 v111, v124, v125, vcc
	v_cndmask_b32_e32 v110, v127, v132, vcc
	v_add_u32_e32 v112, v105, v135
	v_mad_i64_i32 v[112:113], s[4:5], v112, s3, v[110:111]
	v_lshl_add_u64 v[112:113], v[112:113], 0, v[128:129]
	v_lshl_add_u64 v[112:113], v[112:113], 0, v[96:97]
	v_cvt_pk_bf16_f32 v93, v94, v95
	v_cvt_pk_bf16_f32 v88, v88, v89
	v_cvt_pk_bf16_f32 v89, v90, v91
	v_cvt_pk_bf16_f32 v84, v84, v85
	v_cvt_pk_bf16_f32 v85, v86, v87
	v_cvt_pk_bf16_f32 v80, v80, v81
	v_cvt_pk_bf16_f32 v81, v82, v83
	s_waitcnt lgkmcnt(0)
	global_store_dwordx4 v[112:113], v[114:117], off sc1
	s_barrier
	ds_write2_b64 v126, v[92:93], v[84:85] offset1:4
	ds_write2_b64 v122, v[88:89], v[80:81] offset0:32 offset1:36
	v_cvt_pk_bf16_f32 v76, v76, v77
	v_cvt_pk_bf16_f32 v77, v78, v79
	v_cvt_pk_bf16_f32 v68, v68, v69
	v_cvt_pk_bf16_f32 v69, v70, v71
	s_or_b32 s1, s78, 0x80
	ds_write2_b64 v126, v[76:77], v[68:69] offset0:8 offset1:12
	v_add_u32_e32 v68, s1, v123
	v_cmp_gt_i32_e32 vcc, s8, v68
	v_cvt_pk_bf16_f32 v72, v72, v73
	v_cvt_pk_bf16_f32 v73, v74, v75
	v_cvt_pk_bf16_f32 v64, v64, v65
	v_cvt_pk_bf16_f32 v65, v66, v67
	v_cndmask_b32_e32 v69, v146, v147, vcc
	v_cndmask_b32_e32 v71, v153, v154, vcc
	ds_write2_b64 v122, v[72:73], v[64:65] offset0:40 offset1:44
	v_and_b32_e32 v69, v69, v68
	v_cndmask_b32_e32 v70, v149, v152, vcc
	v_and_b32_e32 v68, v71, v68
	s_waitcnt lgkmcnt(0)
	s_barrier
	ds_read_b128 v[64:67], v98
	v_add3_u32 v80, v69, v70, v68
	v_cndmask_b32_e32 v73, v124, v125, vcc
	v_cndmask_b32_e32 v72, v127, v132, vcc
	v_add_u32_e32 v68, v80, v135
	v_mad_i64_i32 v[68:69], s[4:5], v68, s3, v[72:73]
	v_lshl_add_u64 v[68:69], v[68:69], 0, v[128:129]
	v_lshl_add_u64 v[74:75], v[68:69], 0, v[96:97]
	ds_read_b128 v[68:71], v100
	s_waitcnt lgkmcnt(1)
	global_store_dwordx4 v[74:75], v[64:67], off sc1
	s_add_i32 s0, s0, 0x3fff0080
	v_cvt_pk_bf16_f32 v60, v60, v61
	v_add_u32_e32 v64, s1, v136
	v_cmp_gt_i32_e32 vcc, s8, v64
	v_cvt_pk_bf16_f32 v61, v62, v63
	v_cvt_pk_bf16_f32 v56, v56, v57
	v_cndmask_b32_e32 v65, v146, v147, vcc
	v_cndmask_b32_e32 v67, v153, v154, vcc
	v_and_b32_e32 v65, v65, v64
	v_cndmask_b32_e32 v66, v149, v152, vcc
	v_and_b32_e32 v64, v67, v64
	v_add3_u32 v81, v65, v66, v64
	v_cndmask_b32_e32 v75, v124, v125, vcc
	v_cndmask_b32_e32 v74, v127, v132, vcc
	v_add_u32_e32 v64, v81, v135
	v_mad_i64_i32 v[64:65], s[4:5], v64, s3, v[74:75]
	v_lshl_add_u64 v[64:65], v[64:65], 0, v[128:129]
	v_lshl_add_u64 v[64:65], v[64:65], 0, v[96:97]
	s_waitcnt lgkmcnt(0)
	global_store_dwordx4 v[64:65], v[68:71], off sc1
	ds_read_b128 v[64:67], v102
	v_cvt_pk_bf16_f32 v57, v58, v59
	v_add_u32_e32 v68, s1, v137
	v_cmp_gt_i32_e32 vcc, s8, v68
	v_cvt_pk_bf16_f32 v52, v52, v53
	v_cvt_pk_bf16_f32 v53, v54, v55
	v_cndmask_b32_e32 v69, v146, v147, vcc
	v_cndmask_b32_e32 v71, v153, v154, vcc
	v_and_b32_e32 v69, v69, v68
	v_cndmask_b32_e32 v70, v149, v152, vcc
	v_and_b32_e32 v68, v71, v68
	v_add3_u32 v82, v69, v70, v68
	v_cndmask_b32_e32 v77, v124, v125, vcc
	v_cndmask_b32_e32 v76, v127, v132, vcc
	v_add_u32_e32 v68, v82, v135
	v_mad_i64_i32 v[68:69], s[4:5], v68, s3, v[76:77]
	v_lshl_add_u64 v[68:69], v[68:69], 0, v[128:129]
	v_lshl_add_u64 v[78:79], v[68:69], 0, v[96:97]
	ds_read_b128 v[68:71], v104
	s_waitcnt lgkmcnt(1)
	global_store_dwordx4 v[78:79], v[64:67], off sc1
	v_cvt_pk_bf16_f32 v48, v48, v49
	v_cvt_pk_bf16_f32 v49, v50, v51
	v_add_u32_e32 v66, s1, v131
	v_cmp_gt_i32_e32 vcc, s8, v66
	s_lshr_b32 s0, s0, 8
	v_cvt_pk_bf16_f32 v40, v40, v41
	v_cndmask_b32_e32 v67, v146, v147, vcc
	v_cndmask_b32_e32 v79, v153, v154, vcc
	v_and_b32_e32 v67, v67, v66
	v_cndmask_b32_e32 v78, v149, v152, vcc
	v_and_b32_e32 v66, v79, v66
	v_add3_u32 v78, v67, v78, v66
	v_cndmask_b32_e32 v65, v124, v125, vcc
	v_cndmask_b32_e32 v64, v127, v132, vcc
	v_add_u32_e32 v66, v78, v135
	v_mad_i64_i32 v[66:67], s[4:5], v66, s3, v[64:65]
	v_lshl_add_u64 v[66:67], v[66:67], 0, v[128:129]
	v_lshl_add_u64 v[66:67], v[66:67], 0, v[96:97]
	s_waitcnt lgkmcnt(0)
	global_store_dwordx4 v[66:67], v[68:71], off sc1
	s_barrier
	v_or_b32_e32 v66, 0x80, v134
	ds_write2_b64 v126, v[60:61], v[52:53] offset1:4
	ds_write2_b64 v122, v[56:57], v[48:49] offset0:32 offset1:36
	v_cvt_pk_bf16_f32 v41, v42, v43
	v_cvt_pk_bf16_f32 v32, v32, v33
	v_cvt_pk_bf16_f32 v33, v34, v35
	s_movk_i32 s1, 0xc0
	v_cvt_pk_bf16_f32 v44, v44, v45
	v_cvt_pk_bf16_f32 v45, v46, v47
	v_cvt_pk_bf16_f32 v36, v36, v37
	v_cvt_pk_bf16_f32 v37, v38, v39
	ds_write2_b64 v122, v[40:41], v[32:33] offset0:40 offset1:44
	v_mov_b32_e32 v32, s0
	v_cmp_gt_i32_e32 vcc, s51, v66
	v_bitop3_b32 v67, v134, s1, v145 bitop3:0xc8
	s_movk_i32 s1, 0x1fc0
	ds_write2_b64 v126, v[44:45], v[36:37] offset0:8 offset1:12
	v_cndmask_b32_e32 v36, v32, v133, vcc
	v_or_b32_e32 v67, 0x2000, v67
	v_bitop3_b32 v68, v134, s1, v145 bitop3:0xc8
	s_waitcnt lgkmcnt(0)
	s_barrier
	ds_read_b128 v[32:35], v98
	v_lshlrev_b32_e32 v42, 10, v36
	v_cndmask_b32_e32 v38, v67, v68, vcc
	v_add_u32_e32 v36, v99, v42
	v_mad_i64_i32 v[36:37], s[0:1], v36, s3, v[106:107]
	v_lshlrev_b32_e32 v128, 1, v38
	v_lshl_add_u64 v[36:37], v[36:37], 0, v[128:129]
	v_lshl_add_u64 v[40:41], v[36:37], 0, v[96:97]
	ds_read_b128 v[36:39], v100
	s_waitcnt lgkmcnt(1)
	global_store_dwordx4 v[40:41], v[32:35], off sc1
	v_cvt_pk_bf16_f32 v28, v28, v29
	v_cvt_pk_bf16_f32 v29, v30, v31
	v_add_u32_e32 v32, v101, v42
	v_mad_i64_i32 v[32:33], s[0:1], v32, s3, v[108:109]
	v_lshl_add_u64 v[32:33], v[32:33], 0, v[128:129]
	v_lshl_add_u64 v[32:33], v[32:33], 0, v[96:97]
	s_waitcnt lgkmcnt(0)
	global_store_dwordx4 v[32:33], v[36:39], off sc1
	ds_read_b128 v[32:35], v102
	v_cvt_pk_bf16_f32 v24, v24, v25
	v_add_u32_e32 v36, v103, v42
	v_mad_i64_i32 v[36:37], s[0:1], v36, s3, v[118:119]
	v_lshl_add_u64 v[36:37], v[36:37], 0, v[128:129]
	v_lshl_add_u64 v[40:41], v[36:37], 0, v[96:97]
	ds_read_b128 v[36:39], v104
	s_waitcnt lgkmcnt(1)
	global_store_dwordx4 v[40:41], v[32:35], off sc1
	v_cvt_pk_bf16_f32 v25, v26, v27
	v_cvt_pk_bf16_f32 v20, v20, v21
	v_add_u32_e32 v32, v105, v42
	v_mad_i64_i32 v[32:33], s[0:1], v32, s3, v[110:111]
	v_lshl_add_u64 v[32:33], v[32:33], 0, v[128:129]
	v_lshl_add_u64 v[32:33], v[32:33], 0, v[96:97]
	v_cvt_pk_bf16_f32 v21, v22, v23
	v_cvt_pk_bf16_f32 v16, v16, v17
	v_cvt_pk_bf16_f32 v17, v18, v19
	s_waitcnt lgkmcnt(0)
	global_store_dwordx4 v[32:33], v[36:39], off sc1
	s_barrier
	ds_write2_b64 v126, v[28:29], v[20:21] offset1:4
	ds_write2_b64 v122, v[24:25], v[16:17] offset0:32 offset1:36
	v_cvt_pk_bf16_f32 v12, v12, v13
	v_cvt_pk_bf16_f32 v13, v14, v15
	v_cvt_pk_bf16_f32 v8, v8, v9
	v_cvt_pk_bf16_f32 v9, v10, v11
	v_cvt_pk_bf16_f32 v4, v4, v5
	v_cvt_pk_bf16_f32 v5, v6, v7
	v_cvt_pk_bf16_f32 v0, v0, v1
	v_cvt_pk_bf16_f32 v1, v2, v3
	ds_write2_b64 v126, v[12:13], v[4:5] offset0:8 offset1:12
	ds_write2_b64 v122, v[8:9], v[0:1] offset0:40 offset1:44
	s_waitcnt lgkmcnt(0)
	s_barrier
	ds_read_b128 v[0:3], v98
	v_add_u32_e32 v4, v80, v42
	v_mad_i64_i32 v[4:5], s[0:1], v4, s3, v[72:73]
	v_lshl_add_u64 v[4:5], v[4:5], 0, v[128:129]
	v_lshl_add_u64 v[8:9], v[4:5], 0, v[96:97]
	ds_read_b128 v[4:7], v100
	s_waitcnt lgkmcnt(1)
	global_store_dwordx4 v[8:9], v[0:3], off sc1
	s_nop 1
	v_add_u32_e32 v0, v81, v42
	v_mad_i64_i32 v[0:1], s[0:1], v0, s3, v[74:75]
	v_lshl_add_u64 v[0:1], v[0:1], 0, v[128:129]
	v_lshl_add_u64 v[0:1], v[0:1], 0, v[96:97]
	s_waitcnt lgkmcnt(0)
	global_store_dwordx4 v[0:1], v[4:7], off sc1
	ds_read_b128 v[0:3], v102
	s_nop 0
	v_add_u32_e32 v4, v82, v42
	v_mad_i64_i32 v[4:5], s[0:1], v4, s3, v[76:77]
	v_lshl_add_u64 v[4:5], v[4:5], 0, v[128:129]
	v_lshl_add_u64 v[8:9], v[4:5], 0, v[96:97]
	ds_read_b128 v[4:7], v104
	s_waitcnt lgkmcnt(1)
	global_store_dwordx4 v[8:9], v[0:3], off sc1
	s_nop 1
	v_add_u32_e32 v0, v78, v42
	v_mad_i64_i32 v[0:1], s[0:1], v0, s3, v[64:65]
	v_lshl_add_u64 v[0:1], v[0:1], 0, v[128:129]
	v_lshl_add_u64 v[0:1], v[0:1], 0, v[96:97]
	s_waitcnt lgkmcnt(0)
	global_store_dwordx4 v[0:1], v[4:7], off sc1
	s_barrier

.LBB0_117:
	s_or_b64 exec, exec, s[0:1]
	v_mov_b32_e32 v161, v148
	s_movk_i32 s0, 0x2020
	v_bfe_u32 v158, v161, 6, 2
	v_lshl_or_b32 v155, v158, 5, s96
	s_cmpk_gt_u32 s96, 0xbff
	v_cmp_gt_i32_e64 s[16:17], s0, v155
	s_movk_i32 s0, 0x7ff
	s_cselect_b64 s[12:13], -1, 0
	s_cmpk_gt_u32 s96, 0xfff
	v_cmp_lt_i32_e64 s[14:15], s0, v155
	s_cselect_b64 s[0:1], -1, 0
	s_cmpk_gt_u32 s96, 0x13ff
	s_cselect_b64 s[6:7], -1, 0
	v_writelane_b32 v255, s6, 34
	s_cmpk_gt_u32 s96, 0x17ff
	v_and_b32_e32 v157, 15, v161
	v_writelane_b32 v255, s7, 35
	s_cselect_b64 s[6:7], -1, 0
	v_writelane_b32 v255, s6, 36
	s_cmpk_lt_u32 s96, 0x2000
	v_ashrrev_i32_e32 v128, 2, v161
	v_writelane_b32 v255, s7, 37
	s_cselect_b64 s[6:7], -1, 0
	v_writelane_b32 v255, s6, 38
	s_cmpk_gt_u32 s96, 0x1fff
	v_and_b32_e32 v160, 0xffffffc0, v128
	v_or_b32_e32 v128, s4, v157
	v_writelane_b32 v255, s7, 39
	s_cselect_b64 s[6:7], -1, 0
	s_cmpk_gt_u32 s96, 0xdff
	v_add_u32_e32 v132, v128, v160
	s_cselect_b64 s[70:71], -1, 0
	v_mov_b32_e32 v128, 0x3db504f3
	v_writelane_b32 v255, s6, 40
	v_cndmask_b32_e64 v130, v128, 1.0, s[70:71]
	v_and_b32_e32 v128, 64, v161
	v_writelane_b32 v255, s7, 41
	v_cmp_eq_u32_e64 s[6:7], 0, v128
	v_bfe_u32 v159, v161, 4, 2
	s_movk_i32 s5, 0x3ff
	v_writelane_b32 v255, s6, 42
	v_lshlrev_b32_e32 v156, 2, v159
	v_mov_b32_e32 v131, v130
	v_cmp_lt_i32_e64 s[10:11], s5, v155
	v_writelane_b32 v255, s7, 43
	v_mov_b32_e32 v136, 0
	s_and_saveexec_b64 s[18:19], s[16:17]
	s_cbranch_execz .LBB0_149
	v_cmp_gt_i32_e64 s[8:9], s51, v132
	s_and_saveexec_b64 s[6:7], s[14:15]
	s_xor_b64 s[6:7], exec, s[6:7]
	s_cbranch_execz .LBB0_140
	s_andn2_b64 vcc, exec, s[12:13]
	s_cbranch_vccnz .LBB0_140
	s_mov_b64 s[20:21], -1
	s_and_b64 vcc, exec, s[0:1]
	s_cbranch_vccz .LBB0_135
	v_readlane_b32 s20, v255, 34
	v_readlane_b32 s21, v255, 35
	s_andn2_b64 vcc, exec, s[20:21]
	v_mov_b32_e32 v135, v127
	v_mov_b32_e32 v134, v126
	v_mov_b32_e32 v137, v125
	v_mov_b32_e32 v136, v124
	v_mov_b32_e32 v139, v123
	v_mov_b32_e32 v138, v122
	v_mov_b32_e32 v141, v121
	v_mov_b32_e32 v140, v120
	s_cbranch_vccnz .LBB0_134
	v_readlane_b32 s22, v255, 36
	v_readlane_b32 s23, v255, 37
	s_mov_b64 s[20:21], -1
	s_and_b64 vcc, exec, s[22:23]
	s_cbranch_vccz .LBB0_130
	v_readlane_b32 s22, v255, 40
	v_readlane_b32 s23, v255, 41
	s_and_b64 vcc, exec, s[22:23]
	s_cbranch_vccz .LBB0_125
	v_ashrrev_i32_e32 v133, 31, v132
	v_readlane_b32 s20, v255, 23
	v_lshlrev_b64 v[134:135], 7, v[132:133]
	v_readlane_b32 s21, v255, 24
	v_lshlrev_b32_e32 v128, 2, v156
	s_nop 0
	v_lshl_add_u64 v[134:135], s[20:21], 0, v[134:135]
	v_lshl_add_u64 v[134:135], v[134:135], 0, v[128:129]
	global_store_dwordx4 v[134:135], v[124:127], off sc1
	global_store_dwordx4 v[134:135], v[120:123], off offset:64 sc1
	s_mov_b64 s[20:21], 0

.LBB0_149:
	s_or_b64 exec, exec, s[18:19]
	v_or_b32_e32 v128, v160, v157
	s_movk_i32 s5, 0x110
	v_mul_lo_u32 v128, v128, s5
	v_cvt_pk_bf16_f32 v124, v124, v125
	v_cvt_pk_bf16_f32 v125, v126, v127
	v_lshlrev_b32_e32 v126, 6, v158
	v_lshl_add_u32 v127, v159, 3, v128
	v_add_u32_e32 v138, v127, v126
	v_cvt_pk_bf16_f32 v120, v120, v121
	v_cvt_pk_bf16_f32 v121, v122, v123
	s_waitcnt vmcnt(0)
	ds_write2_b64 v138, v[124:125], v[120:121] offset1:4
	v_or_b32_e32 v120, 16, v132
	s_and_saveexec_b64 s[18:19], s[16:17]
	s_cbranch_execz .LBB0_181
	v_cmp_gt_i32_e64 s[8:9], s51, v120
	s_and_saveexec_b64 s[6:7], s[14:15]
	s_xor_b64 s[20:21], exec, s[6:7]
	s_cbranch_execz .LBB0_172
	s_andn2_b64 vcc, exec, s[12:13]
	s_cbranch_vccnz .LBB0_172
	s_andn2_b64 vcc, exec, s[0:1]
	s_mov_b64 s[6:7], -1
	s_cbranch_vccnz .LBB0_167
	v_readlane_b32 s6, v255, 34
	v_readlane_b32 s7, v255, 35
	s_andn2_b64 vcc, exec, s[6:7]
	v_mov_b32_e32 v123, v119
	v_mov_b32_e32 v122, v118
	v_mov_b32_e32 v125, v117
	v_mov_b32_e32 v124, v116
	v_mov_b32_e32 v127, v115
	v_mov_b32_e32 v126, v114
	v_mov_b32_e32 v135, v113
	v_mov_b32_e32 v134, v112
	s_cbranch_vccnz .LBB0_166
	v_readlane_b32 s6, v255, 36
	v_readlane_b32 s7, v255, 37
	s_andn2_b64 vcc, exec, s[6:7]
	s_mov_b64 s[6:7], -1
	s_cbranch_vccnz .LBB0_162
	v_readlane_b32 s6, v255, 40
	v_readlane_b32 s7, v255, 41
	s_andn2_b64 vcc, exec, s[6:7]
	s_mov_b64 s[6:7], -1
	s_cbranch_vccnz .LBB0_157
	v_ashrrev_i32_e32 v121, 31, v120
	v_readlane_b32 s6, v255, 23
	v_lshlrev_b64 v[122:123], 7, v[120:121]
	v_readlane_b32 s7, v255, 24
	v_lshlrev_b32_e32 v128, 2, v156
	s_nop 0
	v_lshl_add_u64 v[122:123], s[6:7], 0, v[122:123]
	v_lshl_add_u64 v[122:123], v[122:123], 0, v[128:129]
	s_mov_b64 s[6:7], 0
	global_store_dwordx4 v[122:123], v[116:119], off sc1
	global_store_dwordx4 v[122:123], v[112:115], off offset:64 sc1

.LBB0_181:
	s_or_b64 exec, exec, s[18:19]
	v_cvt_pk_bf16_f32 v116, v116, v117
	v_cvt_pk_bf16_f32 v117, v118, v119
	v_cvt_pk_bf16_f32 v112, v112, v113
	v_cvt_pk_bf16_f32 v113, v114, v115
	v_add_u32_e32 v139, 0x1000, v138
	ds_write2_b64 v139, v[116:117], v[112:113] offset0:32 offset1:36
	v_or_b32_e32 v112, 32, v132
	s_and_saveexec_b64 s[18:19], s[16:17]
	s_cbranch_execz .LBB0_213
	v_cmp_gt_i32_e64 s[8:9], s51, v112
	s_and_saveexec_b64 s[6:7], s[14:15]
	s_xor_b64 s[20:21], exec, s[6:7]
	s_cbranch_execz .LBB0_204
	s_andn2_b64 vcc, exec, s[12:13]
	s_cbranch_vccnz .LBB0_204
	s_andn2_b64 vcc, exec, s[0:1]
	s_mov_b64 s[6:7], -1
	s_cbranch_vccnz .LBB0_199
	v_readlane_b32 s6, v255, 34
	v_readlane_b32 s7, v255, 35
	s_andn2_b64 vcc, exec, s[6:7]
	v_mov_b32_e32 v115, v111
	v_mov_b32_e32 v114, v110
	v_mov_b32_e32 v117, v109
	v_mov_b32_e32 v116, v108
	v_mov_b32_e32 v119, v107
	v_mov_b32_e32 v118, v106
	v_mov_b32_e32 v123, v105
	v_mov_b32_e32 v122, v104
	s_cbranch_vccnz .LBB0_198
	v_readlane_b32 s6, v255, 36
	v_readlane_b32 s7, v255, 37
	s_andn2_b64 vcc, exec, s[6:7]
	s_mov_b64 s[6:7], -1
	s_cbranch_vccnz .LBB0_194
	v_readlane_b32 s6, v255, 40
	v_readlane_b32 s7, v255, 41
	s_andn2_b64 vcc, exec, s[6:7]
	s_mov_b64 s[6:7], -1
	s_cbranch_vccnz .LBB0_189
	v_ashrrev_i32_e32 v113, 31, v112
	v_readlane_b32 s6, v255, 23
	v_lshlrev_b64 v[114:115], 7, v[112:113]
	v_readlane_b32 s7, v255, 24
	v_lshlrev_b32_e32 v128, 2, v156
	s_nop 0
	v_lshl_add_u64 v[114:115], s[6:7], 0, v[114:115]
	v_lshl_add_u64 v[114:115], v[114:115], 0, v[128:129]
	s_mov_b64 s[6:7], 0
	global_store_dwordx4 v[114:115], v[108:111], off sc1
	global_store_dwordx4 v[114:115], v[104:107], off offset:64 sc1

.LBB0_213:
	s_or_b64 exec, exec, s[18:19]
	v_cvt_pk_bf16_f32 v108, v108, v109
	v_cvt_pk_bf16_f32 v109, v110, v111
	v_cvt_pk_bf16_f32 v104, v104, v105
	v_cvt_pk_bf16_f32 v105, v106, v107
	v_add_u32_e32 v141, 0x2000, v138
	ds_write2_b64 v141, v[108:109], v[104:105] offset0:64 offset1:68
	v_or_b32_e32 v104, 48, v132
	s_and_saveexec_b64 s[18:19], s[16:17]
	s_cbranch_execz .LBB0_245
	v_cmp_gt_i32_e64 s[8:9], s51, v104
	s_and_saveexec_b64 s[6:7], s[14:15]
	s_xor_b64 s[20:21], exec, s[6:7]
	s_cbranch_execz .LBB0_236
	s_andn2_b64 vcc, exec, s[12:13]
	s_cbranch_vccnz .LBB0_236
	s_andn2_b64 vcc, exec, s[0:1]
	s_mov_b64 s[6:7], -1
	s_cbranch_vccnz .LBB0_231
	v_readlane_b32 s6, v255, 34
	v_readlane_b32 s7, v255, 35
	s_andn2_b64 vcc, exec, s[6:7]
	v_mov_b32_e32 v107, v103
	v_mov_b32_e32 v106, v102
	v_mov_b32_e32 v109, v101
	v_mov_b32_e32 v108, v100
	v_mov_b32_e32 v111, v99
	v_mov_b32_e32 v110, v98
	v_mov_b32_e32 v115, v97
	v_mov_b32_e32 v114, v96
	s_cbranch_vccnz .LBB0_230
	v_readlane_b32 s6, v255, 36
	v_readlane_b32 s7, v255, 37
	s_andn2_b64 vcc, exec, s[6:7]
	s_mov_b64 s[6:7], -1
	s_cbranch_vccnz .LBB0_226
	v_readlane_b32 s6, v255, 40
	v_readlane_b32 s7, v255, 41
	s_andn2_b64 vcc, exec, s[6:7]
	s_mov_b64 s[6:7], -1
	s_cbranch_vccnz .LBB0_221
	v_ashrrev_i32_e32 v105, 31, v104
	v_readlane_b32 s6, v255, 23
	v_lshlrev_b64 v[106:107], 7, v[104:105]
	v_readlane_b32 s7, v255, 24
	v_lshlrev_b32_e32 v128, 2, v156
	s_nop 0
	v_lshl_add_u64 v[106:107], s[6:7], 0, v[106:107]
	v_lshl_add_u64 v[106:107], v[106:107], 0, v[128:129]
	s_mov_b64 s[6:7], 0
	global_store_dwordx4 v[106:107], v[100:103], off sc1
	global_store_dwordx4 v[106:107], v[96:99], off offset:64 sc1

.LBB0_269:
	s_or_b64 exec, exec, s[6:7]
	v_lshlrev_b32_e32 v100, 3, v161
	v_and_b32_e32 v100, 56, v100
	v_cmp_ne_u64_e32 vcc, 0, v[106:107]
	v_lshlrev_b32_e32 v100, 1, v100
	s_and_saveexec_b64 s[6:7], vcc
	s_cbranch_execz .LBB0_271
	v_mov_b32_e32 v101, v129
	v_lshl_add_u64 v[106:107], v[106:107], 0, v[100:101]
	s_waitcnt lgkmcnt(0)
	global_store_dwordx4 v[106:107], v[96:99], off sc1

.LBB0_288:
	v_mov_b32_e32 v101, v129
	v_lshl_add_u64 v[108:109], v[108:109], 0, v[100:101]
	s_waitcnt lgkmcnt(0)
	global_store_dwordx4 v[108:109], v[96:99], off sc1

.LBB0_306:
	v_mov_b32_e32 v101, v129
	v_lshl_add_u64 v[114:115], v[114:115], 0, v[100:101]
	s_waitcnt lgkmcnt(0)
	global_store_dwordx4 v[114:115], v[96:99], off sc1

.LBB0_324:
	v_mov_b32_e32 v101, v129
	v_lshl_add_u64 v[124:125], v[124:125], 0, v[100:101]
	s_waitcnt lgkmcnt(0)
	global_store_dwordx4 v[124:125], v[96:99], off sc1
.LBB0_325:
	s_or_b64 exec, exec, s[6:7]
	v_or_b32_e32 v134, 0x80, v155
	s_movk_i32 s5, 0x2020
	v_cmp_gt_i32_e64 s[20:21], s5, v134
	s_movk_i32 s5, 0x7ff
	v_cmp_lt_i32_e64 s[18:19], s5, v134
	s_movk_i32 s5, 0x3ff
	v_cmp_lt_i32_e64 s[12:13], s5, v134
	s_waitcnt lgkmcnt(0)
	v_mov_b32_e32 v97, 0
	s_barrier
	s_and_saveexec_b64 s[34:35], s[20:21]
	s_cbranch_execz .LBB0_357
	v_cmp_gt_i32_e64 s[28:29], s51, v132
	s_and_saveexec_b64 s[6:7], s[18:19]
	s_xor_b64 s[6:7], exec, s[6:7]
	s_cbranch_execz .LBB0_348
	s_and_b64 vcc, exec, s[8:9]
	s_cbranch_vccnz .LBB0_348
	s_andn2_b64 vcc, exec, s[0:1]
	s_mov_b64 s[60:61], -1
	s_cbranch_vccnz .LBB0_343
	v_readlane_b32 s60, v255, 34
	v_readlane_b32 s61, v255, 35
	s_andn2_b64 vcc, exec, s[60:61]
	v_mov_b32_e32 v97, v95
	v_mov_b32_e32 v96, v94
	v_mov_b32_e32 v99, v93
	v_mov_b32_e32 v98, v92
	v_mov_b32_e32 v125, v91
	v_mov_b32_e32 v124, v90
	v_mov_b32_e32 v127, v89
	v_mov_b32_e32 v126, v88
	s_cbranch_vccnz .LBB0_342
	v_readlane_b32 s60, v255, 36
	v_readlane_b32 s61, v255, 37
	s_andn2_b64 vcc, exec, s[60:61]
	s_mov_b64 s[60:61], -1
	s_cbranch_vccnz .LBB0_338
	v_readlane_b32 s60, v255, 40
	v_readlane_b32 s61, v255, 41
	s_andn2_b64 vcc, exec, s[60:61]
	s_mov_b64 s[60:61], -1
	s_cbranch_vccnz .LBB0_333
	v_ashrrev_i32_e32 v133, 31, v132
	v_readlane_b32 s60, v255, 23
	v_lshlrev_b64 v[96:97], 7, v[132:133]
	v_readlane_b32 s61, v255, 24
	v_lshlrev_b32_e32 v98, 2, v156
	v_mov_b32_e32 v99, v129
	v_lshl_add_u64 v[96:97], s[60:61], 0, v[96:97]
	v_lshl_add_u64 v[96:97], v[96:97], 0, v[98:99]
	s_mov_b64 s[60:61], 0
	global_store_dwordx4 v[96:97], v[92:95], off sc1
	global_store_dwordx4 v[96:97], v[88:91], off offset:64 sc1

.LBB0_357:
	s_or_b64 exec, exec, s[34:35]
	v_cvt_pk_bf16_f32 v92, v92, v93
	v_cvt_pk_bf16_f32 v93, v94, v95
	v_cvt_pk_bf16_f32 v88, v88, v89
	v_cvt_pk_bf16_f32 v89, v90, v91
	ds_write2_b64 v138, v[92:93], v[88:89] offset1:4
	s_and_saveexec_b64 s[34:35], s[20:21]
	s_cbranch_execz .LBB0_390
	v_cmp_gt_i32_e64 s[28:29], s51, v120
	s_and_saveexec_b64 s[6:7], s[18:19]
	s_xor_b64 s[6:7], exec, s[6:7]
	s_cbranch_execz .LBB0_381
	s_and_b64 vcc, exec, s[8:9]
	s_cbranch_vccnz .LBB0_380
	s_andn2_b64 vcc, exec, s[0:1]
	s_mov_b64 s[60:61], -1
	s_cbranch_vccnz .LBB0_375
	v_readlane_b32 s60, v255, 34
	v_readlane_b32 s61, v255, 35
	s_andn2_b64 vcc, exec, s[60:61]
	v_mov_b32_e32 v89, v87
	v_mov_b32_e32 v88, v86
	v_mov_b32_e32 v91, v85
	v_mov_b32_e32 v90, v84
	v_mov_b32_e32 v93, v83
	v_mov_b32_e32 v92, v82
	v_mov_b32_e32 v95, v81
	v_mov_b32_e32 v94, v80
	s_cbranch_vccnz .LBB0_374
	v_readlane_b32 s60, v255, 36
	v_readlane_b32 s61, v255, 37
	s_andn2_b64 vcc, exec, s[60:61]
	s_mov_b64 s[60:61], -1
	s_cbranch_vccnz .LBB0_370
	v_readlane_b32 s60, v255, 40
	v_readlane_b32 s61, v255, 41
	s_andn2_b64 vcc, exec, s[60:61]
	s_mov_b64 s[60:61], -1
	s_cbranch_vccnz .LBB0_365
	v_ashrrev_i32_e32 v121, 31, v120
	v_readlane_b32 s60, v255, 23
	v_lshlrev_b64 v[88:89], 7, v[120:121]
	v_readlane_b32 s61, v255, 24
	v_lshlrev_b32_e32 v90, 2, v156
	v_mov_b32_e32 v91, v129
	v_lshl_add_u64 v[88:89], s[60:61], 0, v[88:89]
	v_lshl_add_u64 v[88:89], v[88:89], 0, v[90:91]
	s_mov_b64 s[60:61], 0
	global_store_dwordx4 v[88:89], v[84:87], off sc1
	global_store_dwordx4 v[88:89], v[80:83], off offset:64 sc1

.LBB0_390:
	s_or_b64 exec, exec, s[34:35]
	v_cvt_pk_bf16_f32 v84, v84, v85
	v_cvt_pk_bf16_f32 v85, v86, v87
	v_cvt_pk_bf16_f32 v80, v80, v81
	v_cvt_pk_bf16_f32 v81, v82, v83
	ds_write2_b64 v139, v[84:85], v[80:81] offset0:32 offset1:36
	s_and_saveexec_b64 s[34:35], s[20:21]
	s_cbranch_execz .LBB0_423
	v_cmp_gt_i32_e64 s[28:29], s51, v112
	s_and_saveexec_b64 s[6:7], s[18:19]
	s_xor_b64 s[6:7], exec, s[6:7]
	s_cbranch_execz .LBB0_414
	s_and_b64 vcc, exec, s[8:9]
	s_cbranch_vccnz .LBB0_413
	s_andn2_b64 vcc, exec, s[0:1]
	s_mov_b64 s[60:61], -1
	s_cbranch_vccnz .LBB0_408
	v_readlane_b32 s60, v255, 34
	v_readlane_b32 s61, v255, 35
	s_andn2_b64 vcc, exec, s[60:61]
	v_mov_b32_e32 v81, v79
	v_mov_b32_e32 v80, v78
	v_mov_b32_e32 v83, v77
	v_mov_b32_e32 v82, v76
	v_mov_b32_e32 v85, v75
	v_mov_b32_e32 v84, v74
	v_mov_b32_e32 v87, v73
	v_mov_b32_e32 v86, v72
	s_cbranch_vccnz .LBB0_407
	v_readlane_b32 s60, v255, 36
	v_readlane_b32 s61, v255, 37
	s_andn2_b64 vcc, exec, s[60:61]
	s_mov_b64 s[60:61], -1
	s_cbranch_vccnz .LBB0_403
	v_readlane_b32 s60, v255, 40
	v_readlane_b32 s61, v255, 41
	s_andn2_b64 vcc, exec, s[60:61]
	s_mov_b64 s[60:61], -1
	s_cbranch_vccnz .LBB0_398
	v_ashrrev_i32_e32 v113, 31, v112
	v_readlane_b32 s60, v255, 23
	v_lshlrev_b64 v[80:81], 7, v[112:113]
	v_readlane_b32 s61, v255, 24
	v_lshlrev_b32_e32 v82, 2, v156
	v_mov_b32_e32 v83, v129
	v_lshl_add_u64 v[80:81], s[60:61], 0, v[80:81]
	v_lshl_add_u64 v[80:81], v[80:81], 0, v[82:83]
	s_mov_b64 s[60:61], 0
	global_store_dwordx4 v[80:81], v[76:79], off sc1
	global_store_dwordx4 v[80:81], v[72:75], off offset:64 sc1

.LBB0_423:
	s_or_b64 exec, exec, s[34:35]
	v_cvt_pk_bf16_f32 v76, v76, v77
	v_cvt_pk_bf16_f32 v77, v78, v79
	v_cvt_pk_bf16_f32 v72, v72, v73
	v_cvt_pk_bf16_f32 v73, v74, v75
	ds_write2_b64 v141, v[76:77], v[72:73] offset0:64 offset1:68
	s_and_saveexec_b64 s[34:35], s[20:21]
	s_cbranch_execz .LBB0_456
	v_cmp_gt_i32_e64 s[28:29], s51, v104
	s_and_saveexec_b64 s[6:7], s[18:19]
	s_xor_b64 s[6:7], exec, s[6:7]
	s_cbranch_execz .LBB0_447
	s_and_b64 vcc, exec, s[8:9]
	s_cbranch_vccnz .LBB0_446
	s_andn2_b64 vcc, exec, s[0:1]
	s_mov_b64 s[60:61], -1
	s_cbranch_vccnz .LBB0_441
	v_readlane_b32 s60, v255, 34
	v_readlane_b32 s61, v255, 35
	s_andn2_b64 vcc, exec, s[60:61]
	v_mov_b32_e32 v73, v71
	v_mov_b32_e32 v72, v70
	v_mov_b32_e32 v75, v69
	v_mov_b32_e32 v74, v68
	v_mov_b32_e32 v77, v67
	v_mov_b32_e32 v76, v66
	v_mov_b32_e32 v79, v65
	v_mov_b32_e32 v78, v64
	s_cbranch_vccnz .LBB0_440
	v_readlane_b32 s60, v255, 36
	v_readlane_b32 s61, v255, 37
	s_andn2_b64 vcc, exec, s[60:61]
	s_mov_b64 s[60:61], -1
	s_cbranch_vccnz .LBB0_436
	v_readlane_b32 s60, v255, 40
	v_readlane_b32 s61, v255, 41
	s_andn2_b64 vcc, exec, s[60:61]
	s_mov_b64 s[60:61], -1
	s_cbranch_vccnz .LBB0_431
	v_ashrrev_i32_e32 v105, 31, v104
	v_readlane_b32 s60, v255, 23
	v_lshlrev_b64 v[72:73], 7, v[104:105]
	v_readlane_b32 s61, v255, 24
	v_lshlrev_b32_e32 v74, 2, v156
	v_mov_b32_e32 v75, v129
	v_lshl_add_u64 v[72:73], s[60:61], 0, v[72:73]
	v_lshl_add_u64 v[72:73], v[72:73], 0, v[74:75]
	s_mov_b64 s[60:61], 0
	global_store_dwordx4 v[72:73], v[68:71], off sc1
	global_store_dwordx4 v[72:73], v[64:67], off offset:64 sc1

.LBB0_480:
	s_or_b64 exec, exec, s[6:7]
	v_cmp_ne_u64_e32 vcc, 0, v[68:69]
	s_and_saveexec_b64 s[6:7], vcc
	s_cbranch_execz .LBB0_482
	v_mov_b32_e32 v101, v129
	v_lshl_add_u64 v[68:69], v[68:69], 0, v[100:101]
	s_waitcnt lgkmcnt(0)
	global_store_dwordx4 v[68:69], v[64:67], off sc1

.LBB0_524:
	v_mov_b32_e32 v101, v129
	v_lshl_add_u64 v[68:69], v[68:69], 0, v[100:101]
	s_waitcnt lgkmcnt(0)
	global_store_dwordx4 v[68:69], v[64:67], off sc1

.LBB0_577:
	s_or_b64 exec, exec, s[6:7]
	s_waitcnt lgkmcnt(0)
	v_add_u32_e32 v64, 0x80, v132
	s_barrier
	s_and_saveexec_b64 s[38:39], s[16:17]
	s_cbranch_execz .LBB0_609
	v_cmp_gt_i32_e64 s[36:37], s51, v64
	s_and_saveexec_b64 s[6:7], s[14:15]
	s_xor_b64 s[6:7], exec, s[6:7]
	s_cbranch_execz .LBB0_600
	s_and_b64 vcc, exec, s[8:9]
	s_cbranch_vccnz .LBB0_600
	s_andn2_b64 vcc, exec, s[0:1]
	s_mov_b64 s[40:41], -1
	s_cbranch_vccnz .LBB0_595
	v_readlane_b32 s40, v255, 34
	v_readlane_b32 s41, v255, 35
	s_andn2_b64 vcc, exec, s[40:41]
	v_mov_b32_e32 v67, v63
	v_mov_b32_e32 v66, v62
	v_mov_b32_e32 v69, v61
	v_mov_b32_e32 v68, v60
	v_mov_b32_e32 v71, v59
	v_mov_b32_e32 v70, v58
	v_mov_b32_e32 v73, v57
	v_mov_b32_e32 v72, v56
	s_cbranch_vccnz .LBB0_594
	v_readlane_b32 s40, v255, 36
	v_readlane_b32 s41, v255, 37
	s_andn2_b64 vcc, exec, s[40:41]
	s_mov_b64 s[40:41], -1
	s_cbranch_vccnz .LBB0_590
	v_readlane_b32 s40, v255, 40
	v_readlane_b32 s41, v255, 41
	s_andn2_b64 vcc, exec, s[40:41]
	s_mov_b64 s[40:41], -1
	s_cbranch_vccnz .LBB0_585
	v_ashrrev_i32_e32 v65, 31, v64
	v_readlane_b32 s40, v255, 23
	v_lshlrev_b64 v[66:67], 7, v[64:65]
	v_readlane_b32 s41, v255, 24
	v_lshlrev_b32_e32 v68, 2, v156
	v_mov_b32_e32 v69, v129
	v_lshl_add_u64 v[66:67], s[40:41], 0, v[66:67]
	v_lshl_add_u64 v[66:67], v[66:67], 0, v[68:69]
	s_mov_b64 s[40:41], 0
	global_store_dwordx4 v[66:67], v[60:63], off sc1
	global_store_dwordx4 v[66:67], v[56:59], off offset:64 sc1

.LBB0_609:
	s_or_b64 exec, exec, s[38:39]
	v_cvt_pk_bf16_f32 v60, v60, v61
	v_cvt_pk_bf16_f32 v61, v62, v63
	v_cvt_pk_bf16_f32 v56, v56, v57
	v_cvt_pk_bf16_f32 v57, v58, v59
	ds_write2_b64 v138, v[60:61], v[56:57] offset1:4
	v_add_u32_e32 v56, 0x90, v132
	s_and_saveexec_b64 s[38:39], s[16:17]
	s_cbranch_execz .LBB0_641
	v_cmp_gt_i32_e64 s[36:37], s51, v56
	s_and_saveexec_b64 s[6:7], s[14:15]
	s_xor_b64 s[6:7], exec, s[6:7]
	s_cbranch_execz .LBB0_632
	s_and_b64 vcc, exec, s[8:9]
	s_cbranch_vccnz .LBB0_632
	s_andn2_b64 vcc, exec, s[0:1]
	s_mov_b64 s[40:41], -1
	s_cbranch_vccnz .LBB0_627
	v_readlane_b32 s40, v255, 34
	v_readlane_b32 s41, v255, 35
	s_andn2_b64 vcc, exec, s[40:41]
	v_mov_b32_e32 v59, v55
	v_mov_b32_e32 v58, v54
	v_mov_b32_e32 v61, v53
	v_mov_b32_e32 v60, v52
	v_mov_b32_e32 v63, v51
	v_mov_b32_e32 v62, v50
	v_mov_b32_e32 v67, v49
	v_mov_b32_e32 v66, v48
	s_cbranch_vccnz .LBB0_626
	v_readlane_b32 s40, v255, 36
	v_readlane_b32 s41, v255, 37
	s_andn2_b64 vcc, exec, s[40:41]
	s_mov_b64 s[40:41], -1
	s_cbranch_vccnz .LBB0_622
	v_readlane_b32 s40, v255, 40
	v_readlane_b32 s41, v255, 41
	s_andn2_b64 vcc, exec, s[40:41]
	s_mov_b64 s[40:41], -1
	s_cbranch_vccnz .LBB0_617
	v_ashrrev_i32_e32 v57, 31, v56
	v_readlane_b32 s40, v255, 23
	v_lshlrev_b64 v[58:59], 7, v[56:57]
	v_readlane_b32 s41, v255, 24
	v_lshlrev_b32_e32 v60, 2, v156
	v_mov_b32_e32 v61, v129
	v_lshl_add_u64 v[58:59], s[40:41], 0, v[58:59]
	v_lshl_add_u64 v[58:59], v[58:59], 0, v[60:61]
	s_mov_b64 s[40:41], 0
	global_store_dwordx4 v[58:59], v[52:55], off sc1
	global_store_dwordx4 v[58:59], v[48:51], off offset:64 sc1

.LBB0_641:
	s_or_b64 exec, exec, s[38:39]
	v_cvt_pk_bf16_f32 v52, v52, v53
	v_cvt_pk_bf16_f32 v53, v54, v55
	v_cvt_pk_bf16_f32 v48, v48, v49
	v_cvt_pk_bf16_f32 v49, v50, v51
	ds_write2_b64 v139, v[52:53], v[48:49] offset0:32 offset1:36
	v_add_u32_e32 v48, 0xa0, v132
	s_and_saveexec_b64 s[38:39], s[16:17]
	s_cbranch_execz .LBB0_673
	v_cmp_gt_i32_e64 s[36:37], s51, v48
	s_and_saveexec_b64 s[6:7], s[14:15]
	s_xor_b64 s[6:7], exec, s[6:7]
	s_cbranch_execz .LBB0_664
	s_and_b64 vcc, exec, s[8:9]
	s_cbranch_vccnz .LBB0_664
	s_andn2_b64 vcc, exec, s[0:1]
	s_mov_b64 s[40:41], -1
	s_cbranch_vccnz .LBB0_659
	v_readlane_b32 s40, v255, 34
	v_readlane_b32 s41, v255, 35
	s_andn2_b64 vcc, exec, s[40:41]
	v_mov_b32_e32 v51, v47
	v_mov_b32_e32 v50, v46
	v_mov_b32_e32 v53, v45
	v_mov_b32_e32 v52, v44
	v_mov_b32_e32 v55, v43
	v_mov_b32_e32 v54, v42
	v_mov_b32_e32 v59, v41
	v_mov_b32_e32 v58, v40
	s_cbranch_vccnz .LBB0_658
	v_readlane_b32 s40, v255, 36
	v_readlane_b32 s41, v255, 37
	s_andn2_b64 vcc, exec, s[40:41]
	s_mov_b64 s[40:41], -1
	s_cbranch_vccnz .LBB0_654
	v_readlane_b32 s40, v255, 40
	v_readlane_b32 s41, v255, 41
	s_andn2_b64 vcc, exec, s[40:41]
	s_mov_b64 s[40:41], -1
	s_cbranch_vccnz .LBB0_649
	v_ashrrev_i32_e32 v49, 31, v48
	v_readlane_b32 s40, v255, 23
	v_lshlrev_b64 v[50:51], 7, v[48:49]
	v_readlane_b32 s41, v255, 24
	v_lshlrev_b32_e32 v52, 2, v156
	v_mov_b32_e32 v53, v129
	v_lshl_add_u64 v[50:51], s[40:41], 0, v[50:51]
	v_lshl_add_u64 v[50:51], v[50:51], 0, v[52:53]
	s_mov_b64 s[40:41], 0
	global_store_dwordx4 v[50:51], v[44:47], off sc1
	global_store_dwordx4 v[50:51], v[40:43], off offset:64 sc1

.LBB0_673:
	s_or_b64 exec, exec, s[38:39]
	v_cvt_pk_bf16_f32 v44, v44, v45
	v_cvt_pk_bf16_f32 v45, v46, v47
	v_cvt_pk_bf16_f32 v40, v40, v41
	v_cvt_pk_bf16_f32 v41, v42, v43
	ds_write2_b64 v141, v[44:45], v[40:41] offset0:64 offset1:68
	v_add_u32_e32 v40, 0xb0, v132
	s_and_saveexec_b64 s[36:37], s[16:17]
	s_cbranch_execz .LBB0_705
	v_cmp_gt_i32_e64 s[16:17], s51, v40
	s_and_saveexec_b64 s[6:7], s[14:15]
	s_xor_b64 s[6:7], exec, s[6:7]
	s_cbranch_execz .LBB0_696
	s_and_b64 vcc, exec, s[8:9]
	s_cbranch_vccnz .LBB0_696
	s_andn2_b64 vcc, exec, s[0:1]
	s_mov_b64 s[14:15], -1
	s_cbranch_vccnz .LBB0_691
	v_readlane_b32 s14, v255, 34
	v_readlane_b32 s15, v255, 35
	s_andn2_b64 vcc, exec, s[14:15]
	v_mov_b32_e32 v43, v39
	v_mov_b32_e32 v42, v38
	v_mov_b32_e32 v45, v37
	v_mov_b32_e32 v44, v36
	v_mov_b32_e32 v47, v35
	v_mov_b32_e32 v46, v34
	v_mov_b32_e32 v51, v33
	v_mov_b32_e32 v50, v32
	s_cbranch_vccnz .LBB0_690
	v_readlane_b32 s14, v255, 36
	v_readlane_b32 s15, v255, 37
	s_andn2_b64 vcc, exec, s[14:15]
	s_mov_b64 s[14:15], -1
	s_cbranch_vccnz .LBB0_686
	v_readlane_b32 s14, v255, 40
	v_readlane_b32 s15, v255, 41
	s_andn2_b64 vcc, exec, s[14:15]
	s_mov_b64 s[14:15], -1
	s_cbranch_vccnz .LBB0_681
	v_ashrrev_i32_e32 v41, 31, v40
	v_readlane_b32 s14, v255, 23
	v_lshlrev_b64 v[42:43], 7, v[40:41]
	v_readlane_b32 s15, v255, 24
	v_lshlrev_b32_e32 v44, 2, v156
	v_mov_b32_e32 v45, v129
	v_lshl_add_u64 v[42:43], s[14:15], 0, v[42:43]
	v_lshl_add_u64 v[42:43], v[42:43], 0, v[44:45]
	s_mov_b64 s[14:15], 0
	global_store_dwordx4 v[42:43], v[36:39], off sc1
	global_store_dwordx4 v[42:43], v[32:35], off offset:64 sc1

.LBB0_722:
	v_mov_b32_e32 v101, v129
	v_lshl_add_u64 v[38:39], v[38:39], 0, v[100:101]
	s_waitcnt lgkmcnt(0)
	global_store_dwordx4 v[38:39], v[32:35], off sc1

.LBB0_740:
	v_mov_b32_e32 v101, v129
	v_lshl_add_u64 v[42:43], v[42:43], 0, v[100:101]
	s_waitcnt lgkmcnt(0)
	global_store_dwordx4 v[42:43], v[32:35], off sc1

.LBB0_758:
	v_mov_b32_e32 v101, v129
	v_lshl_add_u64 v[44:45], v[44:45], 0, v[100:101]
	s_waitcnt lgkmcnt(0)
	global_store_dwordx4 v[44:45], v[32:35], off sc1

.LBB0_776:
	v_mov_b32_e32 v101, v129
	v_lshl_add_u64 v[58:59], v[58:59], 0, v[100:101]
	s_waitcnt lgkmcnt(0)
	global_store_dwordx4 v[58:59], v[32:35], off sc1
.LBB0_777:
	s_or_b64 exec, exec, s[6:7]
	s_waitcnt lgkmcnt(0)
	s_barrier
	s_and_saveexec_b64 s[26:27], s[20:21]
	s_cbranch_execz .LBB0_810
	v_cmp_gt_i32_e64 s[22:23], s51, v64
	s_and_saveexec_b64 s[6:7], s[18:19]
	s_xor_b64 s[30:31], exec, s[6:7]
	s_cbranch_execz .LBB0_801
	s_and_b64 vcc, exec, s[8:9]
	s_cbranch_vccnz .LBB0_800
	s_andn2_b64 vcc, exec, s[0:1]
	s_mov_b64 s[6:7], -1
	s_cbranch_vccnz .LBB0_795
	v_readlane_b32 s6, v255, 34
	v_readlane_b32 s7, v255, 35
	s_andn2_b64 vcc, exec, s[6:7]
	v_mov_b32_e32 v33, v31
	v_mov_b32_e32 v32, v30
	v_mov_b32_e32 v35, v29
	v_mov_b32_e32 v34, v28
	v_mov_b32_e32 v59, v27
	v_mov_b32_e32 v58, v26
	v_mov_b32_e32 v61, v25
	v_mov_b32_e32 v60, v24
	s_cbranch_vccnz .LBB0_794
	v_readlane_b32 s6, v255, 36
	v_readlane_b32 s7, v255, 37
	s_andn2_b64 vcc, exec, s[6:7]
	s_mov_b64 s[6:7], -1
	s_cbranch_vccnz .LBB0_790
	v_readlane_b32 s6, v255, 40
	v_readlane_b32 s7, v255, 41
	s_andn2_b64 vcc, exec, s[6:7]
	s_mov_b64 s[6:7], -1
	s_cbranch_vccnz .LBB0_785
	v_ashrrev_i32_e32 v65, 31, v64
	v_readlane_b32 s6, v255, 23
	v_lshlrev_b64 v[32:33], 7, v[64:65]
	v_readlane_b32 s7, v255, 24
	v_lshlrev_b32_e32 v34, 2, v156
	v_mov_b32_e32 v35, v129
	v_lshl_add_u64 v[32:33], s[6:7], 0, v[32:33]
	v_lshl_add_u64 v[32:33], v[32:33], 0, v[34:35]
	s_mov_b64 s[6:7], 0
	global_store_dwordx4 v[32:33], v[28:31], off sc1
	global_store_dwordx4 v[32:33], v[24:27], off offset:64 sc1

.LBB0_810:
	s_or_b64 exec, exec, s[26:27]
	v_cvt_pk_bf16_f32 v28, v28, v29
	v_cvt_pk_bf16_f32 v29, v30, v31
	v_cvt_pk_bf16_f32 v24, v24, v25
	v_cvt_pk_bf16_f32 v25, v26, v27
	ds_write2_b64 v138, v[28:29], v[24:25] offset1:4
	s_and_saveexec_b64 s[26:27], s[20:21]
	s_cbranch_execz .LBB0_843
	v_cmp_gt_i32_e64 s[22:23], s51, v56
	s_and_saveexec_b64 s[6:7], s[18:19]
	s_xor_b64 s[6:7], exec, s[6:7]
	s_cbranch_execz .LBB0_834
	s_and_b64 vcc, exec, s[8:9]
	s_cbranch_vccnz .LBB0_833
	s_andn2_b64 vcc, exec, s[0:1]
	s_mov_b64 s[30:31], -1
	s_cbranch_vccnz .LBB0_828
	v_readlane_b32 s30, v255, 34
	v_readlane_b32 s31, v255, 35
	s_andn2_b64 vcc, exec, s[30:31]
	v_mov_b32_e32 v25, v23
	v_mov_b32_e32 v24, v22
	v_mov_b32_e32 v27, v21
	v_mov_b32_e32 v26, v20
	v_mov_b32_e32 v29, v19
	v_mov_b32_e32 v28, v18
	v_mov_b32_e32 v31, v17
	v_mov_b32_e32 v30, v16
	s_cbranch_vccnz .LBB0_827
	v_readlane_b32 s30, v255, 36
	v_readlane_b32 s31, v255, 37
	s_andn2_b64 vcc, exec, s[30:31]
	s_mov_b64 s[30:31], -1
	s_cbranch_vccnz .LBB0_823
	v_readlane_b32 s30, v255, 40
	v_readlane_b32 s31, v255, 41
	s_andn2_b64 vcc, exec, s[30:31]
	s_mov_b64 s[30:31], -1
	s_cbranch_vccnz .LBB0_818
	v_ashrrev_i32_e32 v57, 31, v56
	v_readlane_b32 s30, v255, 23
	v_lshlrev_b64 v[24:25], 7, v[56:57]
	v_readlane_b32 s31, v255, 24
	v_lshlrev_b32_e32 v26, 2, v156
	v_mov_b32_e32 v27, v129
	v_lshl_add_u64 v[24:25], s[30:31], 0, v[24:25]
	v_lshl_add_u64 v[24:25], v[24:25], 0, v[26:27]
	s_mov_b64 s[30:31], 0
	global_store_dwordx4 v[24:25], v[20:23], off sc1
	global_store_dwordx4 v[24:25], v[16:19], off offset:64 sc1

.LBB0_843:
	s_or_b64 exec, exec, s[26:27]
	v_cvt_pk_bf16_f32 v20, v20, v21
	v_cvt_pk_bf16_f32 v21, v22, v23
	v_cvt_pk_bf16_f32 v16, v16, v17
	v_cvt_pk_bf16_f32 v17, v18, v19
	ds_write2_b64 v139, v[20:21], v[16:17] offset0:32 offset1:36
	s_and_saveexec_b64 s[26:27], s[20:21]
	s_cbranch_execz .LBB0_876
	v_cmp_gt_i32_e64 s[22:23], s51, v48
	s_and_saveexec_b64 s[6:7], s[18:19]
	s_xor_b64 s[6:7], exec, s[6:7]
	s_cbranch_execz .LBB0_867
	s_and_b64 vcc, exec, s[8:9]
	s_cbranch_vccnz .LBB0_866
	s_andn2_b64 vcc, exec, s[0:1]
	s_mov_b64 s[30:31], -1
	s_cbranch_vccnz .LBB0_861
	v_readlane_b32 s30, v255, 34
	v_readlane_b32 s31, v255, 35
	s_andn2_b64 vcc, exec, s[30:31]
	v_mov_b32_e32 v17, v15
	v_mov_b32_e32 v16, v14
	v_mov_b32_e32 v19, v13
	v_mov_b32_e32 v18, v12
	v_mov_b32_e32 v21, v11
	v_mov_b32_e32 v20, v10
	v_mov_b32_e32 v23, v9
	v_mov_b32_e32 v22, v8
	s_cbranch_vccnz .LBB0_860
	v_readlane_b32 s30, v255, 36
	v_readlane_b32 s31, v255, 37
	s_andn2_b64 vcc, exec, s[30:31]
	s_mov_b64 s[30:31], -1
	s_cbranch_vccnz .LBB0_856
	v_readlane_b32 s30, v255, 40
	v_readlane_b32 s31, v255, 41
	s_andn2_b64 vcc, exec, s[30:31]
	s_mov_b64 s[30:31], -1
	s_cbranch_vccnz .LBB0_851
	v_ashrrev_i32_e32 v49, 31, v48
	v_readlane_b32 s30, v255, 23
	v_lshlrev_b64 v[16:17], 7, v[48:49]
	v_readlane_b32 s31, v255, 24
	v_lshlrev_b32_e32 v18, 2, v156
	v_mov_b32_e32 v19, v129
	v_lshl_add_u64 v[16:17], s[30:31], 0, v[16:17]
	v_lshl_add_u64 v[16:17], v[16:17], 0, v[18:19]
	s_mov_b64 s[30:31], 0
	global_store_dwordx4 v[16:17], v[12:15], off sc1
	global_store_dwordx4 v[16:17], v[8:11], off offset:64 sc1

.LBB0_876:
	s_or_b64 exec, exec, s[26:27]
	v_cvt_pk_bf16_f32 v12, v12, v13
	v_cvt_pk_bf16_f32 v13, v14, v15
	v_cvt_pk_bf16_f32 v8, v8, v9
	v_cvt_pk_bf16_f32 v9, v10, v11
	ds_write2_b64 v141, v[12:13], v[8:9] offset0:64 offset1:68
	s_and_saveexec_b64 s[22:23], s[20:21]
	s_cbranch_execz .LBB0_909
	v_cmp_gt_i32_e64 s[20:21], s51, v40
	s_and_saveexec_b64 s[6:7], s[18:19]
	s_xor_b64 s[18:19], exec, s[6:7]
	s_cbranch_execz .LBB0_900
	s_and_b64 vcc, exec, s[8:9]
	s_cbranch_vccnz .LBB0_899
	s_andn2_b64 vcc, exec, s[0:1]
	s_mov_b64 s[6:7], -1
	s_cbranch_vccnz .LBB0_894
	v_readlane_b32 s6, v255, 34
	v_readlane_b32 s7, v255, 35
	s_andn2_b64 vcc, exec, s[6:7]
	v_mov_b32_e32 v9, v7
	v_mov_b32_e32 v8, v6
	v_mov_b32_e32 v11, v5
	v_mov_b32_e32 v10, v4
	v_mov_b32_e32 v13, v3
	v_mov_b32_e32 v12, v2
	v_mov_b32_e32 v15, v1
	v_mov_b32_e32 v14, v0
	s_cbranch_vccnz .LBB0_893
	v_readlane_b32 s6, v255, 36
	v_readlane_b32 s7, v255, 37
	s_andn2_b64 vcc, exec, s[6:7]
	s_mov_b64 s[6:7], -1
	s_cbranch_vccnz .LBB0_889
	v_readlane_b32 s6, v255, 40
	v_readlane_b32 s7, v255, 41
	s_andn2_b64 vcc, exec, s[6:7]
	s_mov_b64 s[6:7], -1
	s_cbranch_vccnz .LBB0_884
	v_ashrrev_i32_e32 v41, 31, v40
	v_readlane_b32 s6, v255, 23
	v_lshlrev_b64 v[8:9], 7, v[40:41]
	v_readlane_b32 s7, v255, 24
	v_lshlrev_b32_e32 v10, 2, v156
	v_mov_b32_e32 v11, v129
	v_lshl_add_u64 v[8:9], s[6:7], 0, v[8:9]
	v_lshl_add_u64 v[8:9], v[8:9], 0, v[10:11]
	s_mov_b64 s[6:7], 0
	global_store_dwordx4 v[8:9], v[4:7], off sc1
	global_store_dwordx4 v[8:9], v[0:3], off offset:64 sc1

.LBB0_966:
	v_mov_b32_e32 v101, v129
	v_lshl_add_u64 v[4:5], v[4:5], 0, v[100:101]
	s_waitcnt lgkmcnt(0)
	global_store_dwordx4 v[4:5], v[0:3], off sc1

.LBB0_1162:
	s_andn2_b64 vcc, exec, s[82:83]
	s_cbranch_vccnz .LBB0_1172
	s_and_saveexec_b64 s[44:45], s[8:9]
	s_xor_b64 s[44:45], exec, s[44:45]
	s_cbranch_execz .LBB0_1165
	v_add_u32_e32 v0, v184, v177
	ds_read_b128 v[12:15], v0
	ds_read_b128 v[112:115], v0 offset:8192
	v_add_u32_e32 v0, v185, v177
	ds_read_b128 v[116:119], v0
	ds_read_b128 v[120:123], v0 offset:8192
	v_add_u32_e32 v0, v186, v177
	ds_read_b128 v[124:127], v0
	v_cvt_pk_bf16_f32 v2, v64, v65
	v_cvt_pk_bf16_f32 v3, v66, v67
	v_cvt_pk_bf16_f32 v4, v68, v69
	v_cvt_pk_bf16_f32 v5, v70, v71
	s_waitcnt lgkmcnt(4)
	s_nop 0
	v_mfma_f32_32x32x16_bf16 v[80:95], v[2:5], v[12:15], 0
	ds_read_b128 v[12:15], v0 offset:8192
	s_waitcnt lgkmcnt(4)
	v_mfma_f32_32x32x16_bf16 v[96:111], v[2:5], v[112:115], 0
	v_add_u32_e32 v0, v187, v177
	ds_read_b128 v[112:115], v0
	v_cvt_pk_bf16_f32 v2, v72, v73
	v_cvt_pk_bf16_f32 v3, v74, v75
	v_cvt_pk_bf16_f32 v4, v76, v77
	v_cvt_pk_bf16_f32 v5, v78, v79
	s_waitcnt lgkmcnt(4)
	s_nop 0
	v_mfma_f32_32x32x16_bf16 v[80:95], v[2:5], v[116:119], v[80:95]
	ds_read_b128 v[116:119], v0 offset:8192
	s_waitcnt lgkmcnt(4)
	v_mfma_f32_32x32x16_bf16 v[96:111], v[2:5], v[120:123], v[96:111]
	v_add_u32_e32 v0, v188, v177
	ds_read_b128 v[120:123], v0
	v_cvt_pk_bf16_f32 v2, v48, v49
	v_cvt_pk_bf16_f32 v3, v50, v51
	v_cvt_pk_bf16_f32 v4, v52, v53
	v_cvt_pk_bf16_f32 v5, v54, v55
	s_waitcnt lgkmcnt(4)
	s_nop 0
	v_mfma_f32_32x32x16_bf16 v[80:95], v[2:5], v[124:127], v[80:95]
	ds_read_b128 v[124:127], v0 offset:8192
	s_waitcnt lgkmcnt(4)
	v_mfma_f32_32x32x16_bf16 v[96:111], v[2:5], v[12:15], v[96:111]
	v_add_u32_e32 v0, v189, v177
	ds_read_b128 v[12:15], v0
	v_cvt_pk_bf16_f32 v2, v56, v57
	v_cvt_pk_bf16_f32 v3, v58, v59
	v_cvt_pk_bf16_f32 v4, v60, v61
	v_cvt_pk_bf16_f32 v5, v62, v63
	s_waitcnt lgkmcnt(4)
	s_nop 0
	v_mfma_f32_32x32x16_bf16 v[80:95], v[2:5], v[112:115], v[80:95]
	ds_read_b128 v[112:115], v0 offset:8192
	s_waitcnt lgkmcnt(4)
	v_mfma_f32_32x32x16_bf16 v[96:111], v[2:5], v[116:119], v[96:111]
	v_add_u32_e32 v0, v190, v177
	ds_read_b128 v[116:119], v0
	v_cvt_pk_bf16_f32 v2, v32, v33
	v_cvt_pk_bf16_f32 v3, v34, v35
	v_cvt_pk_bf16_f32 v4, v36, v37
	v_cvt_pk_bf16_f32 v5, v38, v39
	s_waitcnt lgkmcnt(4)
	s_nop 0
	v_mfma_f32_32x32x16_bf16 v[80:95], v[2:5], v[120:123], v[80:95]
	ds_read_b128 v[120:123], v0 offset:8192
	s_waitcnt lgkmcnt(4)
	v_mfma_f32_32x32x16_bf16 v[96:111], v[2:5], v[124:127], v[96:111]
	v_add_u32_e32 v0, v191, v177
	ds_read_b128 v[124:127], v0
	v_cvt_pk_bf16_f32 v2, v40, v41
	v_cvt_pk_bf16_f32 v3, v42, v43
	v_cvt_pk_bf16_f32 v4, v44, v45
	v_cvt_pk_bf16_f32 v5, v46, v47
	s_waitcnt lgkmcnt(4)
	s_nop 0
	v_mfma_f32_32x32x16_bf16 v[80:95], v[2:5], v[12:15], v[80:95]
	ds_read_b128 v[12:15], v0 offset:8192
	s_waitcnt lgkmcnt(4)
	v_mfma_f32_32x32x16_bf16 v[96:111], v[2:5], v[112:115], v[96:111]
	v_cvt_pk_bf16_f32 v2, v16, v17
	v_cvt_pk_bf16_f32 v3, v18, v19
	v_cvt_pk_bf16_f32 v4, v20, v21
	v_cvt_pk_bf16_f32 v5, v22, v23
	s_waitcnt lgkmcnt(3)
	s_nop 0
	v_mfma_f32_32x32x16_bf16 v[80:95], v[2:5], v[116:119], v[80:95]
	s_waitcnt lgkmcnt(2)
	v_mfma_f32_32x32x16_bf16 v[96:111], v[2:5], v[120:123], v[96:111]
	v_cvt_pk_bf16_f32 v2, v24, v25
	v_cvt_pk_bf16_f32 v3, v26, v27
	v_cvt_pk_bf16_f32 v4, v28, v29
	v_cvt_pk_bf16_f32 v5, v30, v31
	s_waitcnt lgkmcnt(1)
	s_nop 0
	v_mfma_f32_32x32x16_bf16 v[80:95], v[2:5], v[124:127], v[80:95]
	s_waitcnt lgkmcnt(0)
	v_mfma_f32_32x32x16_bf16 v[96:111], v[2:5], v[12:15], v[96:111]
.LBB0_1165:
	s_andn2_saveexec_b64 s[44:45], s[44:45]
	s_cbranch_execz .LBB0_1169
	v_mov_b32_e32 v112, 0
	v_mov_b32_e32 v113, 0
	v_mov_b32_e32 v114, 0
	v_mov_b32_e32 v115, 0
	v_mov_b32_e32 v116, 0
	v_mov_b32_e32 v117, 0
	v_mov_b32_e32 v118, 0
	v_mov_b32_e32 v119, 0
	v_mov_b32_e32 v120, 0
	v_mov_b32_e32 v121, 0
	v_mov_b32_e32 v122, 0
	v_mov_b32_e32 v123, 0
	v_mov_b32_e32 v124, 0
	v_mov_b32_e32 v125, 0
	v_mov_b32_e32 v126, 0
	v_mov_b32_e32 v127, 0
	s_and_saveexec_b64 s[60:61], s[78:79]
	s_cbranch_execz .LBB0_1168
	v_add_u32_e32 v0, v178, v184
	ds_read_b128 v[16:19], v0
	v_add_u32_e32 v0, v179, v184
	ds_read_b128 v[20:23], v0 offset:16384
	v_add_u32_e32 v0, v178, v185
	ds_read_b128 v[24:27], v0
	v_add_u32_e32 v0, v179, v185
	ds_read_b128 v[28:31], v0 offset:16384
	v_add_u32_e32 v0, v178, v186
	ds_read_b128 v[32:35], v0
	v_add_u32_e32 v0, v179, v186
	ds_read_b128 v[36:39], v0 offset:16384
	v_add_u32_e32 v0, v178, v187
	ds_read_b128 v[40:43], v0
	v_add_u32_e32 v0, v179, v187
	ds_read_b128 v[44:47], v0 offset:16384
	v_add_u32_e32 v0, v178, v188
	ds_read_b128 v[48:51], v0
	v_add_u32_e32 v0, v179, v188
	ds_read_b128 v[52:55], v0 offset:16384
	v_add_u32_e32 v0, v178, v189
	ds_read_b128 v[56:59], v0
	v_add_u32_e32 v0, v179, v189
	ds_read_b128 v[60:63], v0 offset:16384
	v_add_u32_e32 v0, v178, v190
	ds_read_b128 v[64:67], v0
	v_add_u32_e32 v0, v179, v190
	ds_read_b128 v[68:71], v0 offset:16384
	v_add_u32_e32 v0, v178, v191
	ds_read_b128 v[72:75], v0
	v_add_u32_e32 v0, v179, v191
	ds_read_b128 v[76:79], v0 offset:16384
	s_waitcnt lgkmcnt(14)
	v_mfma_f32_32x32x16_bf16 v[112:127], v[16:19], v[20:23], 0
	s_waitcnt lgkmcnt(12)
	v_mfma_f32_32x32x16_bf16 v[112:127], v[24:27], v[28:31], v[112:127]
	s_waitcnt lgkmcnt(10)
	v_mfma_f32_32x32x16_bf16 v[112:127], v[32:35], v[36:39], v[112:127]
	s_waitcnt lgkmcnt(8)
	v_mfma_f32_32x32x16_bf16 v[112:127], v[40:43], v[44:47], v[112:127]
	s_waitcnt lgkmcnt(6)
	v_mfma_f32_32x32x16_bf16 v[112:127], v[48:51], v[52:55], v[112:127]
	s_waitcnt lgkmcnt(4)
	v_mfma_f32_32x32x16_bf16 v[112:127], v[56:59], v[60:63], v[112:127]
	s_waitcnt lgkmcnt(2)
	v_mfma_f32_32x32x16_bf16 v[112:127], v[64:67], v[68:71], v[112:127]
	s_waitcnt lgkmcnt(0)
	v_mfma_f32_32x32x16_bf16 v[112:127], v[72:75], v[76:79], v[112:127]

.LBB0_1184:
	s_or_b64 exec, exec, s[4:5]
	v_mov_b32_e32 v128, v148
	s_andn2_b64 vcc, exec, s[10:11]
	v_and_b32_e32 v141, 15, v128
	v_ashrrev_i32_e32 v130, 2, v128
	v_lshrrev_b32_e32 v131, 1, v128
	v_and_b32_e32 v140, 0xffffffc0, v130
	v_or_b32_e32 v130, s14, v141
	v_and_b32_e32 v131, 0x60, v131
	v_lshrrev_b32_e32 v132, 2, v128
	v_add_u32_e32 v130, v130, v140
	v_and_or_b32 v149, v132, 12, v131
	v_or_b32_e32 v132, s16, v149
	v_ashrrev_i32_e32 v131, 31, v130
	v_or_b32_e32 v136, 16, v130
	v_ashrrev_i32_e32 v133, 31, v132
	v_lshlrev_b64 v[134:135], 12, v[130:131]
	v_ashrrev_i32_e32 v137, 31, v136
	v_lshl_add_u64 v[134:135], s[52:53], 0, v[134:135]
	v_lshlrev_b64 v[132:133], 1, v[132:133]
	v_lshlrev_b64 v[136:137], 12, v[136:137]
	v_lshl_add_u64 v[134:135], v[134:135], 0, v[132:133]
	v_lshl_add_u64 v[136:137], s[52:53], 0, v[136:137]
	global_load_dwordx2 v[142:143], v[134:135], off
	global_load_dwordx2 v[144:145], v[134:135], off offset:32
	v_lshl_add_u64 v[138:139], v[136:137], 0, v[132:133]
	global_load_dwordx2 v[146:147], v[138:139], off
	global_load_dwordx2 v[152:153], v[138:139], off offset:32
	v_or_b32_e32 v131, v140, v141
	v_mul_lo_u32 v131, v131, s26
	v_lshlrev_b32_e32 v137, 1, v149
	v_add_u32_e32 v140, v131, v137
	v_or_b32_e32 v136, 32, v130
	v_add_u32_e32 v131, 0x1000, v140
	v_ashrrev_i32_e32 v137, 31, v136
	v_lshlrev_b64 v[136:137], 12, v[136:137]
	v_lshl_add_u64 v[136:137], s[52:53], 0, v[136:137]
	v_lshl_add_u64 v[136:137], v[136:137], 0, v[132:133]
	v_add_u32_e32 v149, 0x400, v128
	s_waitcnt vmcnt(0)
	v_lshlrev_b32_e32 v154, 16, v142
	v_and_b32_e32 v155, 0xffff0000, v142
	v_lshlrev_b32_e32 v142, 16, v143
	v_and_b32_e32 v143, 0xffff0000, v143
	v_lshlrev_b32_e32 v156, 16, v144
	v_and_b32_e32 v157, 0xffff0000, v144
	v_lshlrev_b32_e32 v144, 16, v145
	v_and_b32_e32 v145, 0xffff0000, v145
	v_pk_mul_f32 v[122:123], v[122:123], v[142:143]
	v_pk_mul_f32 v[126:127], v[126:127], v[144:145]
	v_lshlrev_b32_e32 v142, 16, v146
	v_and_b32_e32 v143, 0xffff0000, v146
	v_lshlrev_b32_e32 v144, 16, v147
	v_and_b32_e32 v145, 0xffff0000, v147
	v_lshlrev_b32_e32 v146, 16, v152
	v_and_b32_e32 v147, 0xffff0000, v152
	v_lshlrev_b32_e32 v152, 16, v153
	v_and_b32_e32 v153, 0xffff0000, v153
	v_pk_mul_f32 v[112:113], v[112:113], v[142:143]
	v_pk_mul_f32 v[114:115], v[114:115], v[144:145]
	v_pk_mul_f32 v[116:117], v[116:117], v[146:147]
	v_pk_mul_f32 v[118:119], v[118:119], v[152:153]
	v_cvt_pk_bf16_f32 v112, v112, v113
	v_cvt_pk_bf16_f32 v113, v114, v115
	v_cvt_pk_bf16_f32 v114, v116, v117
	v_cvt_pk_bf16_f32 v115, v118, v119
	v_pk_mul_f32 v[120:121], v[120:121], v[154:155]
	v_pk_mul_f32 v[124:125], v[124:125], v[156:157]
	ds_write2_b64 v131, v[112:113], v[114:115] offset0:32 offset1:36
	v_or_b32_e32 v112, 48, v130
	v_cvt_pk_bf16_f32 v120, v120, v121
	v_cvt_pk_bf16_f32 v121, v122, v123
	v_cvt_pk_bf16_f32 v122, v124, v125
	v_cvt_pk_bf16_f32 v123, v126, v127
	v_ashrrev_i32_e32 v113, 31, v112
	ds_write2_b64 v140, v[120:121], v[122:123] offset1:4
	v_lshlrev_b64 v[112:113], 12, v[112:113]
	v_lshl_add_u64 v[112:113], s[52:53], 0, v[112:113]
	global_load_dwordx2 v[122:123], v[136:137], off
	global_load_dwordx2 v[124:125], v[136:137], off offset:32
	v_lshl_add_u64 v[118:119], v[112:113], 0, v[132:133]
	global_load_dwordx2 v[126:127], v[118:119], off
	global_load_dwordx2 v[142:143], v[118:119], off offset:32
	v_add_u32_e32 v121, 0x2000, v140
	v_cndmask_b32_e64 v112, 0, 1, s[10:11]
	v_lshlrev_b32_e32 v113, 3, v128
	v_add_u32_e32 v120, 0x3000, v140
	v_cmp_ne_u32_e64 s[4:5], 1, v112
	v_and_or_b32 v112, v113, 64, s16
	v_ashrrev_i32_e32 v115, 4, v128
	v_add_u32_e32 v117, 0x200, v128
	v_add_u32_e32 v156, 0x600, v128
	v_and_b32_e32 v128, 56, v113
	v_ashrrev_i32_e32 v113, 31, v112
	v_lshlrev_b32_e32 v114, 4, v141
	v_add_u32_e32 v116, s14, v115
	v_lshlrev_b64 v[112:113], 1, v[112:113]
	v_lshlrev_b32_e32 v128, 1, v128
	s_waitcnt vmcnt(3)
	v_lshlrev_b32_e32 v144, 16, v122
	v_and_b32_e32 v145, 0xffff0000, v122
	v_lshlrev_b32_e32 v122, 16, v123
	v_and_b32_e32 v123, 0xffff0000, v123
	s_waitcnt vmcnt(2)
	v_lshlrev_b32_e32 v146, 16, v124
	v_and_b32_e32 v147, 0xffff0000, v124
	v_lshlrev_b32_e32 v124, 16, v125
	v_and_b32_e32 v125, 0xffff0000, v125
	s_waitcnt vmcnt(1)
	v_lshlrev_b32_e32 v152, 16, v126
	v_and_b32_e32 v153, 0xffff0000, v126
	v_lshlrev_b32_e32 v126, 16, v127
	v_and_b32_e32 v127, 0xffff0000, v127
	s_waitcnt vmcnt(0)
	v_lshlrev_b32_e32 v154, 16, v142
	v_and_b32_e32 v155, 0xffff0000, v142
	v_lshlrev_b32_e32 v142, 16, v143
	v_and_b32_e32 v143, 0xffff0000, v143
	v_pk_mul_f32 v[96:97], v[96:97], v[144:145]
	v_pk_mul_f32 v[98:99], v[98:99], v[122:123]
	v_pk_mul_f32 v[100:101], v[100:101], v[146:147]
	v_pk_mul_f32 v[102:103], v[102:103], v[124:125]
	v_pk_mul_f32 v[104:105], v[104:105], v[152:153]
	v_pk_mul_f32 v[106:107], v[106:107], v[126:127]
	v_pk_mul_f32 v[108:109], v[108:109], v[154:155]
	v_pk_mul_f32 v[110:111], v[110:111], v[142:143]
	v_cvt_pk_bf16_f32 v96, v96, v97
	v_cvt_pk_bf16_f32 v97, v98, v99
	v_cvt_pk_bf16_f32 v98, v100, v101
	v_cvt_pk_bf16_f32 v99, v102, v103
	v_cvt_pk_bf16_f32 v100, v104, v105
	v_cvt_pk_bf16_f32 v101, v106, v107
	v_cvt_pk_bf16_f32 v102, v108, v109
	v_cvt_pk_bf16_f32 v103, v110, v111
	ds_write2_b64 v121, v[96:97], v[98:99] offset0:64 offset1:68
	ds_write2_b64 v120, v[100:101], v[102:103] offset0:96 offset1:100
	v_ashrrev_i32_e32 v98, 4, v117
	v_ashrrev_i32_e32 v97, 4, v149
	v_ashrrev_i32_e32 v96, 4, v156
	s_waitcnt lgkmcnt(0)
	s_barrier
	s_cbranch_vccnz .LBB0_1186
	v_ashrrev_i32_e32 v117, 31, v116
	v_lshlrev_b64 v[100:101], 12, v[116:117]
	v_lshl_add_u64 v[100:101], s[52:53], 0, v[100:101]
	v_lshl_add_u64 v[104:105], v[100:101], 0, v[112:113]
	v_mad_u64_u32 v[100:101], s[16:17], v115, s26, v[114:115]
	ds_read_b128 v[100:103], v100
	v_lshl_add_u64 v[108:109], v[104:105], 0, v[128:129]
	v_mad_u64_u32 v[104:105], s[16:17], v98, s26, v[114:115]
	ds_read_b128 v[104:107], v104
	s_waitcnt lgkmcnt(1)
	global_store_dwordx4 v[108:109], v[100:103], off sc1
	s_nop 1
	v_add_u32_e32 v100, s14, v98
	v_ashrrev_i32_e32 v101, 31, v100
	v_lshlrev_b64 v[100:101], 12, v[100:101]
	v_lshl_add_u64 v[100:101], s[52:53], 0, v[100:101]
	v_lshl_add_u64 v[100:101], v[100:101], 0, v[112:113]
	v_lshl_add_u64 v[100:101], v[100:101], 0, v[128:129]
	s_waitcnt lgkmcnt(0)
	global_store_dwordx4 v[100:101], v[104:107], off sc1
	v_add_u32_e32 v100, s14, v97
	v_ashrrev_i32_e32 v101, 31, v100
	v_lshlrev_b64 v[100:101], 12, v[100:101]
	v_lshl_add_u64 v[100:101], s[52:53], 0, v[100:101]
	v_lshl_add_u64 v[104:105], v[100:101], 0, v[112:113]
	v_mad_u64_u32 v[100:101], s[16:17], v97, s26, v[114:115]
	ds_read_b128 v[100:103], v100
	v_lshl_add_u64 v[108:109], v[104:105], 0, v[128:129]
	v_mad_u64_u32 v[104:105], s[16:17], v96, s26, v[114:115]
	ds_read_b128 v[104:107], v104
	s_waitcnt lgkmcnt(1)
	global_store_dwordx4 v[108:109], v[100:103], off sc1
	s_nop 1
	v_add_u32_e32 v100, s14, v96
	v_ashrrev_i32_e32 v101, 31, v100
	v_lshlrev_b64 v[100:101], 12, v[100:101]
	v_lshl_add_u64 v[100:101], s[52:53], 0, v[100:101]
	v_lshl_add_u64 v[100:101], v[100:101], 0, v[112:113]
	v_lshl_add_u64 v[100:101], v[100:101], 0, v[128:129]
	s_waitcnt lgkmcnt(0)
	global_store_dwordx4 v[100:101], v[104:107], off sc1
.LBB0_1186:
	s_barrier
	global_load_dwordx2 v[100:101], v[134:135], off offset:256
	global_load_dwordx2 v[102:103], v[134:135], off offset:288
	global_load_dwordx2 v[104:105], v[138:139], off offset:256
	global_load_dwordx2 v[106:107], v[138:139], off offset:288
	s_and_b64 vcc, exec, s[4:5]
	s_waitcnt vmcnt(3)
	v_lshlrev_b32_e32 v108, 16, v100
	v_and_b32_e32 v109, 0xffff0000, v100
	v_lshlrev_b32_e32 v100, 16, v101
	v_and_b32_e32 v101, 0xffff0000, v101
	s_waitcnt vmcnt(2)
	v_lshlrev_b32_e32 v110, 16, v102
	v_and_b32_e32 v111, 0xffff0000, v102
	v_lshlrev_b32_e32 v102, 16, v103
	v_and_b32_e32 v103, 0xffff0000, v103
	s_waitcnt vmcnt(1)
	v_lshlrev_b32_e32 v122, 16, v104
	v_and_b32_e32 v123, 0xffff0000, v104
	v_lshlrev_b32_e32 v104, 16, v105
	v_and_b32_e32 v105, 0xffff0000, v105
	s_waitcnt vmcnt(0)
	v_lshlrev_b32_e32 v124, 16, v106
	v_and_b32_e32 v125, 0xffff0000, v106
	v_lshlrev_b32_e32 v106, 16, v107
	v_and_b32_e32 v107, 0xffff0000, v107
	v_pk_mul_f32 v[84:85], v[84:85], v[108:109]
	v_pk_mul_f32 v[86:87], v[86:87], v[100:101]
	v_pk_mul_f32 v[88:89], v[88:89], v[110:111]
	v_pk_mul_f32 v[90:91], v[90:91], v[102:103]
	v_pk_mul_f32 v[92:93], v[92:93], v[122:123]
	v_pk_mul_f32 v[94:95], v[94:95], v[104:105]
	v_pk_mul_f32 v[80:81], v[80:81], v[124:125]
	v_pk_mul_f32 v[82:83], v[82:83], v[106:107]
	v_cvt_pk_bf16_f32 v84, v84, v85
	v_cvt_pk_bf16_f32 v85, v86, v87
	v_cvt_pk_bf16_f32 v86, v88, v89
	v_cvt_pk_bf16_f32 v87, v90, v91
	v_cvt_pk_bf16_f32 v88, v92, v93
	v_cvt_pk_bf16_f32 v89, v94, v95
	v_cvt_pk_bf16_f32 v80, v80, v81
	v_cvt_pk_bf16_f32 v81, v82, v83
	ds_write2_b64 v140, v[84:85], v[86:87] offset1:4
	ds_write2_b64 v131, v[88:89], v[80:81] offset0:32 offset1:36
	global_load_dwordx2 v[80:81], v[136:137], off offset:256
	global_load_dwordx2 v[82:83], v[136:137], off offset:288
	global_load_dwordx2 v[84:85], v[118:119], off offset:256
	global_load_dwordx2 v[86:87], v[118:119], off offset:288
	s_waitcnt vmcnt(3)
	v_lshlrev_b32_e32 v88, 16, v80
	v_and_b32_e32 v89, 0xffff0000, v80
	v_lshlrev_b32_e32 v80, 16, v81
	v_and_b32_e32 v81, 0xffff0000, v81
	s_waitcnt vmcnt(2)
	v_lshlrev_b32_e32 v90, 16, v82
	v_and_b32_e32 v91, 0xffff0000, v82
	v_lshlrev_b32_e32 v82, 16, v83
	v_and_b32_e32 v83, 0xffff0000, v83
	s_waitcnt vmcnt(1)
	v_lshlrev_b32_e32 v92, 16, v84
	v_and_b32_e32 v93, 0xffff0000, v84
	v_lshlrev_b32_e32 v84, 16, v85
	v_and_b32_e32 v85, 0xffff0000, v85
	s_waitcnt vmcnt(0)
	v_lshlrev_b32_e32 v94, 16, v86
	v_and_b32_e32 v95, 0xffff0000, v86
	v_lshlrev_b32_e32 v86, 16, v87
	v_and_b32_e32 v87, 0xffff0000, v87
	v_pk_mul_f32 v[68:69], v[68:69], v[88:89]
	v_pk_mul_f32 v[70:71], v[70:71], v[80:81]
	v_pk_mul_f32 v[72:73], v[72:73], v[90:91]
	v_pk_mul_f32 v[74:75], v[74:75], v[82:83]
	v_pk_mul_f32 v[76:77], v[76:77], v[92:93]
	v_pk_mul_f32 v[78:79], v[78:79], v[84:85]
	v_pk_mul_f32 v[64:65], v[64:65], v[94:95]
	v_pk_mul_f32 v[66:67], v[66:67], v[86:87]
	v_cvt_pk_bf16_f32 v68, v68, v69
	v_cvt_pk_bf16_f32 v69, v70, v71
	v_cvt_pk_bf16_f32 v70, v72, v73
	v_cvt_pk_bf16_f32 v71, v74, v75
	v_cvt_pk_bf16_f32 v72, v76, v77
	v_cvt_pk_bf16_f32 v73, v78, v79
	v_cvt_pk_bf16_f32 v64, v64, v65
	v_cvt_pk_bf16_f32 v65, v66, v67
	ds_write2_b64 v121, v[68:69], v[70:71] offset0:64 offset1:68
	ds_write2_b64 v120, v[72:73], v[64:65] offset0:96 offset1:100
	s_waitcnt lgkmcnt(0)
	s_barrier
	s_cbranch_vccnz .LBB0_1188
	v_ashrrev_i32_e32 v117, 31, v116
	v_lshlrev_b64 v[64:65], 12, v[116:117]
	v_lshl_add_u64 v[64:65], s[52:53], 0, v[64:65]
	v_lshl_add_u64 v[68:69], v[64:65], 0, v[112:113]
	v_mad_u64_u32 v[64:65], s[16:17], v115, s26, v[114:115]
	ds_read_b128 v[64:67], v64
	v_lshl_add_u64 v[72:73], v[68:69], 0, v[128:129]
	v_mad_u64_u32 v[68:69], s[16:17], v98, s26, v[114:115]
	ds_read_b128 v[68:71], v68
	s_waitcnt lgkmcnt(1)
	global_store_dwordx4 v[72:73], v[64:67], off offset:256 sc1
	s_nop 1
	v_add_u32_e32 v64, s14, v98
	v_ashrrev_i32_e32 v65, 31, v64
	v_lshlrev_b64 v[64:65], 12, v[64:65]
	v_lshl_add_u64 v[64:65], s[52:53], 0, v[64:65]
	v_lshl_add_u64 v[64:65], v[64:65], 0, v[112:113]
	v_lshl_add_u64 v[64:65], v[64:65], 0, v[128:129]
	s_waitcnt lgkmcnt(0)
	global_store_dwordx4 v[64:65], v[68:71], off offset:256 sc1
	v_add_u32_e32 v64, s14, v97
	v_ashrrev_i32_e32 v65, 31, v64
	v_lshlrev_b64 v[64:65], 12, v[64:65]
	v_lshl_add_u64 v[64:65], s[52:53], 0, v[64:65]
	v_lshl_add_u64 v[68:69], v[64:65], 0, v[112:113]
	v_mad_u64_u32 v[64:65], s[16:17], v97, s26, v[114:115]
	ds_read_b128 v[64:67], v64
	v_lshl_add_u64 v[72:73], v[68:69], 0, v[128:129]
	v_mad_u64_u32 v[68:69], s[16:17], v96, s26, v[114:115]
	ds_read_b128 v[68:71], v68
	s_waitcnt lgkmcnt(1)
	global_store_dwordx4 v[72:73], v[64:67], off offset:256 sc1
	s_nop 1
	v_add_u32_e32 v64, s14, v96
	v_ashrrev_i32_e32 v65, 31, v64
	v_lshlrev_b64 v[64:65], 12, v[64:65]
	v_lshl_add_u64 v[64:65], s[52:53], 0, v[64:65]
	v_lshl_add_u64 v[64:65], v[64:65], 0, v[112:113]
	v_lshl_add_u64 v[64:65], v[64:65], 0, v[128:129]
	s_waitcnt lgkmcnt(0)
	global_store_dwordx4 v[64:65], v[68:71], off offset:256 sc1
.LBB0_1188:
	v_add_u32_e32 v64, 0x80, v130
	v_ashrrev_i32_e32 v65, 31, v64
	v_lshlrev_b64 v[64:65], 12, v[64:65]
	v_lshl_add_u64 v[64:65], s[52:53], 0, v[64:65]
	v_lshl_add_u64 v[66:67], v[64:65], 0, v[132:133]
	v_add_u32_e32 v64, 0x90, v130
	v_ashrrev_i32_e32 v65, 31, v64
	v_lshlrev_b64 v[64:65], 12, v[64:65]
	v_lshl_add_u64 v[64:65], s[52:53], 0, v[64:65]
	s_barrier
	global_load_dwordx2 v[70:71], v[66:67], off
	global_load_dwordx2 v[72:73], v[66:67], off offset:32
	v_lshl_add_u64 v[68:69], v[64:65], 0, v[132:133]
	global_load_dwordx2 v[74:75], v[68:69], off
	global_load_dwordx2 v[76:77], v[68:69], off offset:32
	v_add_u32_e32 v64, 0xa0, v130
	v_ashrrev_i32_e32 v65, 31, v64
	v_lshlrev_b64 v[64:65], 12, v[64:65]
	v_lshl_add_u64 v[64:65], s[52:53], 0, v[64:65]
	v_lshl_add_u64 v[64:65], v[64:65], 0, v[132:133]
	s_bitset1_b32 s14, 7
	s_and_b64 vcc, exec, s[4:5]
	s_waitcnt vmcnt(3)
	v_lshlrev_b32_e32 v78, 16, v70
	v_and_b32_e32 v79, 0xffff0000, v70
	v_lshlrev_b32_e32 v70, 16, v71
	v_and_b32_e32 v71, 0xffff0000, v71
	s_waitcnt vmcnt(2)
	v_lshlrev_b32_e32 v80, 16, v72
	v_and_b32_e32 v81, 0xffff0000, v72
	v_lshlrev_b32_e32 v72, 16, v73
	v_and_b32_e32 v73, 0xffff0000, v73
	s_waitcnt vmcnt(1)
	v_lshlrev_b32_e32 v82, 16, v74
	v_and_b32_e32 v83, 0xffff0000, v74
	v_lshlrev_b32_e32 v74, 16, v75
	v_and_b32_e32 v75, 0xffff0000, v75
	s_waitcnt vmcnt(0)
	v_lshlrev_b32_e32 v84, 16, v76
	v_and_b32_e32 v85, 0xffff0000, v76
	v_lshlrev_b32_e32 v76, 16, v77
	v_and_b32_e32 v77, 0xffff0000, v77
	v_pk_mul_f32 v[48:49], v[48:49], v[78:79]
	v_pk_mul_f32 v[50:51], v[50:51], v[70:71]
	v_pk_mul_f32 v[52:53], v[52:53], v[80:81]
	v_pk_mul_f32 v[54:55], v[54:55], v[72:73]
	v_pk_mul_f32 v[56:57], v[56:57], v[82:83]
	v_pk_mul_f32 v[58:59], v[58:59], v[74:75]
	v_pk_mul_f32 v[60:61], v[60:61], v[84:85]
	v_pk_mul_f32 v[62:63], v[62:63], v[76:77]
	v_cvt_pk_bf16_f32 v48, v48, v49
	v_cvt_pk_bf16_f32 v49, v50, v51
	v_cvt_pk_bf16_f32 v50, v52, v53
	v_cvt_pk_bf16_f32 v51, v54, v55
	v_cvt_pk_bf16_f32 v52, v56, v57
	v_cvt_pk_bf16_f32 v53, v58, v59
	v_cvt_pk_bf16_f32 v54, v60, v61
	v_cvt_pk_bf16_f32 v55, v62, v63
	ds_write2_b64 v140, v[48:49], v[50:51] offset1:4
	ds_write2_b64 v131, v[52:53], v[54:55] offset0:32 offset1:36
	v_add_u32_e32 v48, 0xb0, v130
	v_ashrrev_i32_e32 v49, 31, v48
	v_lshlrev_b64 v[48:49], 12, v[48:49]
	v_lshl_add_u64 v[48:49], s[52:53], 0, v[48:49]
	global_load_dwordx2 v[50:51], v[64:65], off
	global_load_dwordx2 v[52:53], v[64:65], off offset:32
	v_lshl_add_u64 v[48:49], v[48:49], 0, v[132:133]
	global_load_dwordx2 v[54:55], v[48:49], off
	global_load_dwordx2 v[56:57], v[48:49], off offset:32
	s_waitcnt vmcnt(3)
	v_lshlrev_b32_e32 v58, 16, v50
	v_and_b32_e32 v59, 0xffff0000, v50
	v_lshlrev_b32_e32 v50, 16, v51
	v_and_b32_e32 v51, 0xffff0000, v51
	s_waitcnt vmcnt(2)
	v_lshlrev_b32_e32 v60, 16, v52
	v_and_b32_e32 v61, 0xffff0000, v52
	v_lshlrev_b32_e32 v52, 16, v53
	v_and_b32_e32 v53, 0xffff0000, v53
	s_waitcnt vmcnt(1)
	v_lshlrev_b32_e32 v62, 16, v54
	v_and_b32_e32 v63, 0xffff0000, v54
	v_lshlrev_b32_e32 v54, 16, v55
	v_and_b32_e32 v55, 0xffff0000, v55
	s_waitcnt vmcnt(0)
	v_lshlrev_b32_e32 v70, 16, v56
	v_and_b32_e32 v71, 0xffff0000, v56
	v_lshlrev_b32_e32 v56, 16, v57
	v_and_b32_e32 v57, 0xffff0000, v57
	v_pk_mul_f32 v[36:37], v[36:37], v[58:59]
	v_pk_mul_f32 v[38:39], v[38:39], v[50:51]
	v_pk_mul_f32 v[40:41], v[40:41], v[60:61]
	v_pk_mul_f32 v[42:43], v[42:43], v[52:53]
	v_pk_mul_f32 v[44:45], v[44:45], v[62:63]
	v_pk_mul_f32 v[46:47], v[46:47], v[54:55]
	v_pk_mul_f32 v[32:33], v[32:33], v[70:71]
	v_pk_mul_f32 v[34:35], v[34:35], v[56:57]
	v_cvt_pk_bf16_f32 v36, v36, v37
	v_cvt_pk_bf16_f32 v37, v38, v39
	v_cvt_pk_bf16_f32 v38, v40, v41
	v_cvt_pk_bf16_f32 v39, v42, v43
	v_cvt_pk_bf16_f32 v40, v44, v45
	v_cvt_pk_bf16_f32 v41, v46, v47
	v_cvt_pk_bf16_f32 v32, v32, v33
	v_cvt_pk_bf16_f32 v33, v34, v35
	ds_write2_b64 v121, v[36:37], v[38:39] offset0:64 offset1:68
	ds_write2_b64 v120, v[40:41], v[32:33] offset0:96 offset1:100
	v_add_u32_e32 v32, s14, v115
	s_waitcnt lgkmcnt(0)
	s_barrier
	s_cbranch_vccnz .LBB0_1190
	v_ashrrev_i32_e32 v33, 31, v32
	v_lshlrev_b64 v[34:35], 12, v[32:33]
	v_lshl_add_u64 v[34:35], s[52:53], 0, v[34:35]
	v_lshl_add_u64 v[38:39], v[34:35], 0, v[112:113]
	v_mad_u64_u32 v[34:35], s[16:17], v115, s26, v[114:115]
	ds_read_b128 v[34:37], v34
	v_lshl_add_u64 v[42:43], v[38:39], 0, v[128:129]
	v_mad_u64_u32 v[38:39], s[16:17], v98, s26, v[114:115]
	ds_read_b128 v[38:41], v38
	s_waitcnt lgkmcnt(1)
	global_store_dwordx4 v[42:43], v[34:37], off sc1
	s_nop 1
	v_add_u32_e32 v34, s14, v98
	v_ashrrev_i32_e32 v35, 31, v34
	v_lshlrev_b64 v[34:35], 12, v[34:35]
	v_lshl_add_u64 v[34:35], s[52:53], 0, v[34:35]
	v_lshl_add_u64 v[34:35], v[34:35], 0, v[112:113]
	v_lshl_add_u64 v[34:35], v[34:35], 0, v[128:129]
	s_waitcnt lgkmcnt(0)
	global_store_dwordx4 v[34:35], v[38:41], off sc1
	v_add_u32_e32 v34, s14, v97
	v_ashrrev_i32_e32 v35, 31, v34
	v_lshlrev_b64 v[34:35], 12, v[34:35]
	v_lshl_add_u64 v[34:35], s[52:53], 0, v[34:35]
	v_lshl_add_u64 v[38:39], v[34:35], 0, v[112:113]
	v_mad_u64_u32 v[34:35], s[16:17], v97, s26, v[114:115]
	ds_read_b128 v[34:37], v34
	v_lshl_add_u64 v[42:43], v[38:39], 0, v[128:129]
	v_mad_u64_u32 v[38:39], s[16:17], v96, s26, v[114:115]
	ds_read_b128 v[38:41], v38
	s_waitcnt lgkmcnt(1)
	global_store_dwordx4 v[42:43], v[34:37], off sc1
	s_nop 1
	v_add_u32_e32 v34, s14, v96
	v_ashrrev_i32_e32 v35, 31, v34
	v_lshlrev_b64 v[34:35], 12, v[34:35]
	v_lshl_add_u64 v[34:35], s[52:53], 0, v[34:35]
	v_lshl_add_u64 v[34:35], v[34:35], 0, v[112:113]
	v_lshl_add_u64 v[34:35], v[34:35], 0, v[128:129]
	s_waitcnt lgkmcnt(0)
	global_store_dwordx4 v[34:35], v[38:41], off sc1
.LBB0_1190:
	s_barrier
	global_load_dwordx2 v[34:35], v[66:67], off offset:256
	global_load_dwordx2 v[36:37], v[66:67], off offset:288
	global_load_dwordx2 v[38:39], v[68:69], off offset:256
	global_load_dwordx2 v[40:41], v[68:69], off offset:288
	s_and_b64 vcc, exec, s[4:5]
	s_waitcnt vmcnt(3)
	v_lshlrev_b32_e32 v42, 16, v34
	v_and_b32_e32 v43, 0xffff0000, v34
	v_lshlrev_b32_e32 v34, 16, v35
	v_and_b32_e32 v35, 0xffff0000, v35
	s_waitcnt vmcnt(2)
	v_lshlrev_b32_e32 v44, 16, v36
	v_and_b32_e32 v45, 0xffff0000, v36
	v_lshlrev_b32_e32 v36, 16, v37
	v_and_b32_e32 v37, 0xffff0000, v37
	s_waitcnt vmcnt(1)
	v_lshlrev_b32_e32 v46, 16, v38
	v_and_b32_e32 v47, 0xffff0000, v38
	v_lshlrev_b32_e32 v38, 16, v39
	v_and_b32_e32 v39, 0xffff0000, v39
	s_waitcnt vmcnt(0)
	v_lshlrev_b32_e32 v50, 16, v40
	v_and_b32_e32 v51, 0xffff0000, v40
	v_lshlrev_b32_e32 v40, 16, v41
	v_and_b32_e32 v41, 0xffff0000, v41
	v_pk_mul_f32 v[20:21], v[20:21], v[42:43]
	v_pk_mul_f32 v[22:23], v[22:23], v[34:35]
	v_pk_mul_f32 v[24:25], v[24:25], v[44:45]
	v_pk_mul_f32 v[26:27], v[26:27], v[36:37]
	v_pk_mul_f32 v[28:29], v[28:29], v[46:47]
	v_pk_mul_f32 v[30:31], v[30:31], v[38:39]
	v_pk_mul_f32 v[16:17], v[16:17], v[50:51]
	v_pk_mul_f32 v[18:19], v[18:19], v[40:41]
	v_cvt_pk_bf16_f32 v20, v20, v21
	v_cvt_pk_bf16_f32 v21, v22, v23
	v_cvt_pk_bf16_f32 v22, v24, v25
	v_cvt_pk_bf16_f32 v23, v26, v27
	v_cvt_pk_bf16_f32 v24, v28, v29
	v_cvt_pk_bf16_f32 v25, v30, v31
	v_cvt_pk_bf16_f32 v16, v16, v17
	v_cvt_pk_bf16_f32 v17, v18, v19
	ds_write2_b64 v140, v[20:21], v[22:23] offset1:4
	ds_write2_b64 v131, v[24:25], v[16:17] offset0:32 offset1:36
	global_load_dwordx2 v[16:17], v[64:65], off offset:256
	global_load_dwordx2 v[18:19], v[64:65], off offset:288
	global_load_dwordx2 v[20:21], v[48:49], off offset:256
	global_load_dwordx2 v[22:23], v[48:49], off offset:288
	s_waitcnt vmcnt(3)
	v_lshlrev_b32_e32 v24, 16, v16
	v_and_b32_e32 v25, 0xffff0000, v16
	v_lshlrev_b32_e32 v16, 16, v17
	v_and_b32_e32 v17, 0xffff0000, v17
	s_waitcnt vmcnt(2)
	v_lshlrev_b32_e32 v26, 16, v18
	v_and_b32_e32 v27, 0xffff0000, v18
	v_lshlrev_b32_e32 v18, 16, v19
	v_and_b32_e32 v19, 0xffff0000, v19
	s_waitcnt vmcnt(1)
	v_lshlrev_b32_e32 v28, 16, v20
	v_and_b32_e32 v29, 0xffff0000, v20
	v_lshlrev_b32_e32 v20, 16, v21
	v_and_b32_e32 v21, 0xffff0000, v21
	s_waitcnt vmcnt(0)
	v_lshlrev_b32_e32 v30, 16, v22
	v_and_b32_e32 v31, 0xffff0000, v22
	v_lshlrev_b32_e32 v22, 16, v23
	v_and_b32_e32 v23, 0xffff0000, v23
	v_pk_mul_f32 v[4:5], v[4:5], v[24:25]
	v_pk_mul_f32 v[6:7], v[6:7], v[16:17]
	v_pk_mul_f32 v[8:9], v[8:9], v[26:27]
	v_pk_mul_f32 v[10:11], v[10:11], v[18:19]
	v_pk_mul_f32 v[12:13], v[12:13], v[28:29]
	v_pk_mul_f32 v[14:15], v[14:15], v[20:21]
	v_pk_mul_f32 v[0:1], v[0:1], v[30:31]
	v_pk_mul_f32 v[2:3], v[2:3], v[22:23]
	v_cvt_pk_bf16_f32 v4, v4, v5
	v_cvt_pk_bf16_f32 v5, v6, v7
	v_cvt_pk_bf16_f32 v6, v8, v9
	v_cvt_pk_bf16_f32 v7, v10, v11
	v_cvt_pk_bf16_f32 v8, v12, v13
	v_cvt_pk_bf16_f32 v9, v14, v15
	v_cvt_pk_bf16_f32 v0, v0, v1
	v_cvt_pk_bf16_f32 v1, v2, v3
	ds_write2_b64 v121, v[4:5], v[6:7] offset0:64 offset1:68
	ds_write2_b64 v120, v[8:9], v[0:1] offset0:96 offset1:100
	s_waitcnt lgkmcnt(0)
	s_barrier
	s_cbranch_vccnz .LBB0_1177
	v_ashrrev_i32_e32 v33, 31, v32
	v_lshlrev_b64 v[0:1], 12, v[32:33]
	v_lshl_add_u64 v[0:1], s[52:53], 0, v[0:1]
	v_lshl_add_u64 v[4:5], v[0:1], 0, v[112:113]
	v_mad_u64_u32 v[0:1], s[4:5], v115, s26, v[114:115]
	ds_read_b128 v[0:3], v0
	v_lshl_add_u64 v[8:9], v[4:5], 0, v[128:129]
	v_mad_u64_u32 v[4:5], s[4:5], v98, s26, v[114:115]
	ds_read_b128 v[4:7], v4
	s_waitcnt lgkmcnt(1)
	global_store_dwordx4 v[8:9], v[0:3], off offset:256 sc1
	s_nop 1
	v_add_u32_e32 v0, s14, v98
	v_ashrrev_i32_e32 v1, 31, v0
	v_lshlrev_b64 v[0:1], 12, v[0:1]
	v_lshl_add_u64 v[0:1], s[52:53], 0, v[0:1]
	v_lshl_add_u64 v[0:1], v[0:1], 0, v[112:113]
	v_lshl_add_u64 v[0:1], v[0:1], 0, v[128:129]
	s_waitcnt lgkmcnt(0)
	global_store_dwordx4 v[0:1], v[4:7], off offset:256 sc1
	v_add_u32_e32 v0, s14, v97
	v_ashrrev_i32_e32 v1, 31, v0
	v_lshlrev_b64 v[0:1], 12, v[0:1]
	v_lshl_add_u64 v[0:1], s[52:53], 0, v[0:1]
	v_lshl_add_u64 v[4:5], v[0:1], 0, v[112:113]
	v_mad_u64_u32 v[0:1], s[4:5], v97, s26, v[114:115]
	ds_read_b128 v[0:3], v0
	v_lshl_add_u64 v[8:9], v[4:5], 0, v[128:129]
	v_mad_u64_u32 v[4:5], s[4:5], v96, s26, v[114:115]
	ds_read_b128 v[4:7], v4
	s_waitcnt lgkmcnt(1)
	global_store_dwordx4 v[8:9], v[0:3], off offset:256 sc1
	s_nop 1
	v_add_u32_e32 v0, s14, v96
	v_ashrrev_i32_e32 v1, 31, v0
	v_lshlrev_b64 v[0:1], 12, v[0:1]
	v_lshl_add_u64 v[0:1], s[52:53], 0, v[0:1]
	v_lshl_add_u64 v[0:1], v[0:1], 0, v[112:113]
	v_lshl_add_u64 v[0:1], v[0:1], 0, v[128:129]
	s_waitcnt lgkmcnt(0)
	global_store_dwordx4 v[0:1], v[4:7], off offset:256 sc1
	s_branch .LBB0_1177

.LBB0_1194:
	v_ashrrev_i32_e32 v12, 31, v15
	v_lshrrev_b32_e32 v12, 22, v12
	v_lshl_add_u64 v[16:17], v[14:15], 0, v[12:13]
	v_ashrrev_i64 v[16:17], 10, v[16:17]
	v_lshlrev_b32_e32 v18, 3, v16
	v_ashrrev_i32_e32 v19, 31, v18
	v_lshlrev_b64 v[20:21], 12, v[16:17]
	v_lshlrev_b64 v[22:23], 12, v[18:19]
	v_sub_co_u32_e32 v20, vcc, v22, v20
	v_lshl_add_u64 v[14:15], v[14:15], 0, s[4:5]
	s_nop 0
	v_subb_co_u32_e32 v21, vcc, v23, v21, vcc
	v_lshl_add_u64 v[20:21], v[8:9], 0, v[20:21]
	v_add_co_u32_e32 v22, vcc, s3, v20
	v_lshlrev_b64 v[16:17], 21, v[16:17]
	s_nop 0
	v_addc_co_u32_e32 v23, vcc, 0, v21, vcc
	v_add_co_u32_e32 v24, vcc, s16, v20
	v_lshlrev_b64 v[18:19], 1, v[18:19]
	s_nop 0
	v_addc_co_u32_e32 v25, vcc, 0, v21, vcc
	v_add_co_u32_e32 v26, vcc, s17, v20
	v_lshl_add_u64 v[8:9], v[8:9], 0, s[6:7]
	s_nop 0
	v_addc_co_u32_e32 v27, vcc, 0, v21, vcc
	v_add_co_u32_e32 v28, vcc, s18, v20
	s_nop 1
	v_addc_co_u32_e32 v29, vcc, 0, v21, vcc
	global_load_dword v12, v[20:21], off
	global_load_dword v30, v[22:23], off offset:-4096
	s_nop 0
	global_load_dword v22, v[22:23], off
	s_nop 0
	global_load_dword v23, v[24:25], off offset:-4096
	s_nop 0
	global_load_dword v24, v[24:25], off
	s_nop 0
	global_load_dword v25, v[26:27], off offset:-4096
	s_nop 0
	global_load_dword v26, v[26:27], off
	s_nop 0
	global_load_dword v27, v[28:29], off
	v_cmp_lt_i64_e32 vcc, s[14:15], v[14:15]
	s_or_b64 s[12:13], vcc, s[12:13]
	v_sub_co_u32_e32 v16, vcc, v18, v16
	s_waitcnt vmcnt(2)
	v_cvt_pk_bf16_f32 v18, v24, v25
	v_subb_co_u32_e32 v17, vcc, v19, v17, vcc
	v_lshl_add_u64 v[20:21], v[10:11], 0, v[16:17]
	v_lshl_add_u64 v[10:11], v[10:11], 0, s[10:11]
	v_cvt_pk_bf16_f32 v16, v12, v30
	v_cvt_pk_bf16_f32 v17, v22, v23
	s_waitcnt vmcnt(0)
	v_cvt_pk_bf16_f32 v19, v26, v27
	global_store_dwordx4 v[20:21], v[16:19], off sc1
	s_andn2_b64 exec, exec, s[12:13]
	s_cbranch_execnz .LBB0_1194
	s_or_b64 exec, exec, s[12:13]
	s_mov_b64 s[12:13], 0x1480000
	v_lshl_add_u64 v[8:9], s[80:81], 0, v[2:3]
	v_lshl_add_u64 v[6:7], v[6:7], 0, s[12:13]
	s_mov_b64 s[12:13], 0
	v_mov_b32_e32 v11, 0
	s_movk_i32 s3, 0x2000
	s_movk_i32 s16, 0x4000
	s_movk_i32 s17, 0x6000
	s_movk_i32 s18, 0x7000
	s_mov_b64 s[14:15], 0x1ffff
	v_mov_b64_e32 v[12:13], v[0:1]
.LBB0_1196:
	v_ashrrev_i32_e32 v10, 31, v13
	v_lshrrev_b32_e32 v10, 22, v10
	v_lshl_add_u64 v[14:15], v[12:13], 0, v[10:11]
	v_ashrrev_i64 v[14:15], 10, v[14:15]
	v_lshlrev_b32_e32 v16, 3, v14
	v_ashrrev_i32_e32 v17, 31, v16
	v_lshlrev_b64 v[18:19], 12, v[14:15]
	v_lshlrev_b64 v[20:21], 12, v[16:17]
	v_sub_co_u32_e32 v18, vcc, v20, v18
	v_lshl_add_u64 v[12:13], v[12:13], 0, s[4:5]
	s_nop 0
	v_subb_co_u32_e32 v19, vcc, v21, v19, vcc
	v_lshl_add_u64 v[18:19], v[8:9], 0, v[18:19]
	v_add_co_u32_e32 v20, vcc, s3, v18
	v_lshlrev_b64 v[14:15], 21, v[14:15]
	s_nop 0
	v_addc_co_u32_e32 v21, vcc, 0, v19, vcc
	v_add_co_u32_e32 v22, vcc, s16, v18
	v_lshlrev_b64 v[16:17], 1, v[16:17]
	s_nop 0
	v_addc_co_u32_e32 v23, vcc, 0, v19, vcc
	v_add_co_u32_e32 v24, vcc, s17, v18
	v_lshl_add_u64 v[8:9], v[8:9], 0, s[6:7]
	s_nop 0
	v_addc_co_u32_e32 v25, vcc, 0, v19, vcc
	v_add_co_u32_e32 v26, vcc, s18, v18
	s_nop 1
	v_addc_co_u32_e32 v27, vcc, 0, v19, vcc
	global_load_dword v10, v[18:19], off
	global_load_dword v28, v[20:21], off offset:-4096
	s_nop 0
	global_load_dword v20, v[20:21], off
	s_nop 0
	global_load_dword v21, v[22:23], off offset:-4096
	s_nop 0
	global_load_dword v22, v[22:23], off
	s_nop 0
	global_load_dword v23, v[24:25], off offset:-4096
	s_nop 0
	global_load_dword v24, v[24:25], off
	s_nop 0
	global_load_dword v25, v[26:27], off
	v_cmp_lt_i64_e32 vcc, s[14:15], v[12:13]
	s_or_b64 s[12:13], vcc, s[12:13]
	v_sub_co_u32_e32 v14, vcc, v16, v14
	s_waitcnt vmcnt(2)
	v_cvt_pk_bf16_f32 v16, v22, v23
	v_subb_co_u32_e32 v15, vcc, v17, v15, vcc
	v_lshl_add_u64 v[18:19], v[6:7], 0, v[14:15]
	v_lshl_add_u64 v[6:7], v[6:7], 0, s[10:11]
	v_cvt_pk_bf16_f32 v14, v10, v28
	v_cvt_pk_bf16_f32 v15, v20, v21
	s_waitcnt vmcnt(0)
	v_cvt_pk_bf16_f32 v17, v24, v25
	global_store_dwordx4 v[18:19], v[14:17], off sc1
	s_andn2_b64 exec, exec, s[12:13]
	s_cbranch_execnz .LBB0_1196
	s_or_b64 exec, exec, s[12:13]

.LBB0_1202:
	v_ashrrev_i32_e32 v8, 31, v11
	v_lshrrev_b32_e32 v8, 20, v8
	v_lshl_add_u64 v[12:13], v[10:11], 0, v[8:9]
	v_ashrrev_i64 v[12:13], 12, v[12:13]
	v_lshlrev_b32_e32 v14, 3, v12
	v_ashrrev_i32_e32 v15, 31, v14
	v_lshlrev_b64 v[16:17], 14, v[12:13]
	v_lshlrev_b64 v[18:19], 14, v[14:15]
	v_sub_co_u32_e32 v16, vcc, v18, v16
	v_lshl_add_u64 v[10:11], v[10:11], 0, s[4:5]
	s_nop 0
	v_subb_co_u32_e32 v17, vcc, v19, v17, vcc
	v_lshl_add_u64 v[16:17], v[6:7], 0, v[16:17]
	v_add_co_u32_e32 v18, vcc, s3, v16
	v_lshlrev_b64 v[12:13], 23, v[12:13]
	s_nop 0
	v_addc_co_u32_e32 v19, vcc, 0, v17, vcc
	v_add_co_u32_e32 v20, vcc, s16, v16
	v_lshlrev_b64 v[14:15], 1, v[14:15]
	s_nop 0
	v_addc_co_u32_e32 v21, vcc, 0, v17, vcc
	v_add_co_u32_e32 v22, vcc, s17, v16
	v_lshl_add_u64 v[6:7], v[6:7], 0, s[8:9]
	s_nop 0
	v_addc_co_u32_e32 v23, vcc, 0, v17, vcc
	v_add_co_u32_e32 v24, vcc, s18, v16
	s_nop 1
	v_addc_co_u32_e32 v25, vcc, 0, v17, vcc
	v_add_co_u32_e32 v26, vcc, s19, v16
	s_nop 1
	v_addc_co_u32_e32 v27, vcc, 0, v17, vcc
	v_add_co_u32_e32 v28, vcc, s20, v16
	s_nop 1
	v_addc_co_u32_e32 v29, vcc, 0, v17, vcc
	v_add_co_u32_e32 v30, vcc, s21, v16
	s_nop 1
	v_addc_co_u32_e32 v31, vcc, 0, v17, vcc
	global_load_dword v8, v[16:17], off
	s_nop 0
	global_load_dword v18, v[18:19], off
	s_nop 0
	global_load_dword v19, v[20:21], off
	s_nop 0
	global_load_dword v20, v[22:23], off
	global_load_dword v21, v[24:25], off
	s_nop 0
	global_load_dword v22, v[26:27], off
	global_load_dword v23, v[28:29], off
	global_load_dword v24, v[30:31], off
	v_cmp_lt_i64_e32 vcc, s[14:15], v[10:11]
	s_or_b64 s[10:11], vcc, s[10:11]
	v_sub_co_u32_e32 v12, vcc, v14, v12
	s_waitcnt vmcnt(2)
	v_cvt_pk_bf16_f32 v14, v21, v22
	v_subb_co_u32_e32 v13, vcc, v15, v13, vcc
	v_lshl_add_u64 v[16:17], v[4:5], 0, v[12:13]
	v_lshl_add_u64 v[4:5], v[4:5], 0, s[12:13]
	v_cvt_pk_bf16_f32 v12, v8, v18
	v_cvt_pk_bf16_f32 v13, v19, v20
	s_waitcnt vmcnt(0)
	v_cvt_pk_bf16_f32 v15, v23, v24
	global_store_dwordx4 v[16:17], v[12:15], off sc1
	s_andn2_b64 exec, exec, s[10:11]
	s_cbranch_execnz .LBB0_1202
	s_or_b64 exec, exec, s[10:11]
	v_lshlrev_b64 v[4:5], 13, v[0:1]
	v_lshl_add_u64 v[4:5], s[54:55], 0, v[4:5]
	s_mov_b64 s[10:11], 0x1e80000
	v_lshl_add_u64 v[2:3], s[88:89], 0, v[2:3]
	v_lshl_add_u64 v[4:5], v[4:5], 0, s[10:11]
	s_lshl_b64 s[12:13], s[4:5], 13
	s_mov_b64 s[10:11], 0
	v_mov_b32_e32 v7, 0
	s_movk_i32 s3, 0x2000
	s_movk_i32 s16, 0x4000
	s_movk_i32 s17, 0x6000
	s_movk_i32 s18, 0x7000
	s_mov_b64 s[14:15], 0x7ffff
.LBB0_1204:
	v_ashrrev_i32_e32 v6, 31, v1
	v_lshrrev_b32_e32 v6, 22, v6
	v_lshl_add_u64 v[8:9], v[0:1], 0, v[6:7]
	v_ashrrev_i64 v[8:9], 10, v[8:9]
	v_lshlrev_b32_e32 v10, 3, v8
	v_ashrrev_i32_e32 v11, 31, v10
	v_lshlrev_b64 v[12:13], 12, v[8:9]
	v_lshlrev_b64 v[14:15], 12, v[10:11]
	v_sub_co_u32_e32 v12, vcc, v14, v12
	v_lshl_add_u64 v[0:1], v[0:1], 0, s[4:5]
	s_nop 0
	v_subb_co_u32_e32 v13, vcc, v15, v13, vcc
	v_lshl_add_u64 v[12:13], v[2:3], 0, v[12:13]
	v_add_co_u32_e32 v14, vcc, s3, v12
	v_lshlrev_b64 v[8:9], 23, v[8:9]
	s_nop 0
	v_addc_co_u32_e32 v15, vcc, 0, v13, vcc
	v_add_co_u32_e32 v16, vcc, s16, v12
	v_lshlrev_b64 v[10:11], 1, v[10:11]
	s_nop 0
	v_addc_co_u32_e32 v17, vcc, 0, v13, vcc
	v_add_co_u32_e32 v18, vcc, s17, v12
	v_lshl_add_u64 v[2:3], v[2:3], 0, s[8:9]
	s_nop 0
	v_addc_co_u32_e32 v19, vcc, 0, v13, vcc
	v_add_co_u32_e32 v20, vcc, s18, v12
	s_nop 1
	v_addc_co_u32_e32 v21, vcc, 0, v13, vcc
	global_load_dword v6, v[12:13], off
	global_load_dword v22, v[14:15], off offset:-4096
	s_nop 0
	global_load_dword v14, v[14:15], off
	s_nop 0
	global_load_dword v15, v[16:17], off offset:-4096
	s_nop 0
	global_load_dword v16, v[16:17], off
	s_nop 0
	global_load_dword v17, v[18:19], off offset:-4096
	s_nop 0
	global_load_dword v18, v[18:19], off
	s_nop 0
	global_load_dword v19, v[20:21], off
	v_cmp_lt_i64_e32 vcc, s[14:15], v[0:1]
	s_or_b64 s[10:11], vcc, s[10:11]
	v_sub_co_u32_e32 v8, vcc, v10, v8
	s_waitcnt vmcnt(2)
	v_cvt_pk_bf16_f32 v10, v16, v17
	v_subb_co_u32_e32 v9, vcc, v11, v9, vcc
	v_lshl_add_u64 v[12:13], v[4:5], 0, v[8:9]
	v_lshl_add_u64 v[4:5], v[4:5], 0, s[12:13]
	v_cvt_pk_bf16_f32 v8, v6, v22
	v_cvt_pk_bf16_f32 v9, v14, v15
	s_waitcnt vmcnt(0)
	v_cvt_pk_bf16_f32 v11, v18, v19
	global_store_dwordx4 v[12:13], v[8:11], off sc1
	s_andn2_b64 exec, exec, s[10:11]
	s_cbranch_execnz .LBB0_1204
	s_or_b64 exec, exec, s[10:11]

.LBB0_1218:
	v_add_co_u32_e32 v36, vcc, 0xf8000000, v30
	v_lshl_add_u64 v[32:33], v[30:31], 0, s[10:11]
	s_nop 0
	v_addc_co_u32_e32 v37, vcc, -1, v31, vcc
	global_load_dwordx4 v[16:19], v[30:31], off offset:16
	global_load_dwordx4 v[20:23], v[30:31], off
	global_load_dwordx4 v[0:3], v[28:29], off offset:48
	global_load_dwordx4 v[4:7], v[28:29], off offset:32
	global_load_dwordx4 v[8:11], v[28:29], off offset:16
	global_load_dwordx4 v[12:15], v[28:29], off
	global_load_dwordx4 v[48:51], v[36:37], off
	global_load_dwordx4 v[52:55], v[32:33], off offset:16
	v_add_u32_e32 v56, 24, v24
	v_add_co_u32_e32 v60, vcc, s23, v30
	v_lshl_add_u64 v[34:35], v[30:31], 0, s[12:13]
	v_ashrrev_i32_e32 v57, 31, v56
	v_addc_co_u32_e32 v61, vcc, 0, v31, vcc
	v_lshlrev_b64 v[32:33], 11, v[56:57]
	global_load_dwordx4 v[56:59], v[60:61], off
	s_nop 0
	global_load_dwordx4 v[34:37], v[34:35], off offset:16
	v_lshl_or_b32 v32, v26, 1, v32
	v_lshl_add_u64 v[62:63], s[8:9], 0, v[32:33]
	v_lshl_add_u64 v[64:65], s[68:69], 0, v[32:33]
	v_lshl_add_u64 v[32:33], s[66:67], 0, v[32:33]
	v_add_u32_e32 v24, 16, v24
	v_cmp_le_i32_e64 s[6:7], s26, v24
	v_lshl_add_u64 v[30:31], v[30:31], 0, s[14:15]
	s_or_b64 s[18:19], s[6:7], s[18:19]
	global_load_dwordx4 v[200:203], v[62:63], off
	global_load_dwordx4 v[200:203], v[62:63], off offset:16
	global_load_dwordx4 v[200:203], v[64:65], off
	global_load_dwordx4 v[200:203], v[64:65], off offset:16
	global_load_dwordx4 v[200:203], v[32:33], off
	global_load_dwordx4 v[200:203], v[32:33], off offset:16
	s_waitcnt vmcnt(15)
	v_lshlrev_b32_e32 v70, 16, v16
	s_waitcnt vmcnt(14)
	v_lshlrev_b32_e32 v66, 16, v20
	v_and_b32_e32 v67, 0xffff0000, v20
	v_lshlrev_b32_e32 v20, 16, v21
	v_and_b32_e32 v21, 0xffff0000, v21
	v_lshlrev_b32_e32 v68, 16, v22
	v_and_b32_e32 v69, 0xffff0000, v22
	v_lshlrev_b32_e32 v22, 16, v23
	v_and_b32_e32 v23, 0xffff0000, v23
	v_and_b32_e32 v71, 0xffff0000, v16
	v_lshlrev_b32_e32 v16, 16, v17
	v_and_b32_e32 v17, 0xffff0000, v17
	v_lshlrev_b32_e32 v72, 16, v18
	v_and_b32_e32 v73, 0xffff0000, v18
	v_lshlrev_b32_e32 v18, 16, v19
	v_and_b32_e32 v19, 0xffff0000, v19
	s_waitcnt vmcnt(9)
	v_lshlrev_b32_e32 v74, 16, v48
	v_and_b32_e32 v75, 0xffff0000, v48
	v_lshlrev_b32_e32 v48, 16, v49
	v_and_b32_e32 v49, 0xffff0000, v49
	v_lshlrev_b32_e32 v76, 16, v50
	v_and_b32_e32 v77, 0xffff0000, v50
	v_lshlrev_b32_e32 v50, 16, v51
	v_and_b32_e32 v51, 0xffff0000, v51
	s_waitcnt vmcnt(8)
	v_lshlrev_b32_e32 v78, 16, v52
	v_and_b32_e32 v79, 0xffff0000, v52
	v_lshlrev_b32_e32 v52, 16, v53
	v_and_b32_e32 v53, 0xffff0000, v53
	v_lshlrev_b32_e32 v80, 16, v54
	v_and_b32_e32 v81, 0xffff0000, v54
	v_lshlrev_b32_e32 v54, 16, v55
	v_and_b32_e32 v55, 0xffff0000, v55
	v_pk_add_f32 v[18:19], v[54:55], v[18:19]
	v_pk_add_f32 v[54:55], v[80:81], v[72:73]
	v_pk_add_f32 v[16:17], v[52:53], v[16:17]
	v_pk_add_f32 v[52:53], v[78:79], v[70:71]
	v_pk_add_f32 v[22:23], v[50:51], v[22:23]
	v_pk_add_f32 v[50:51], v[76:77], v[68:69]
	v_pk_add_f32 v[20:21], v[48:49], v[20:21]
	v_pk_add_f32 v[48:49], v[74:75], v[66:67]
	v_mov_b32_e32 v68, v55
	v_mov_b32_e32 v69, v19
	v_mov_b32_e32 v72, v53
	v_mov_b32_e32 v73, v17
	v_mov_b32_e32 v76, v51
	v_mov_b32_e32 v77, v23
	v_pk_mul_f32 v[78:79], v[20:21], v[20:21]
	v_pk_mul_f32 v[80:81], v[48:49], v[48:49]
	v_mov_b32_e32 v66, v54
	v_mov_b32_e32 v67, v18
	v_mov_b32_e32 v70, v52
	v_mov_b32_e32 v71, v16
	v_mov_b32_e32 v74, v50
	v_mov_b32_e32 v75, v22
	v_pk_mul_f32 v[68:69], v[68:69], v[68:69]
	v_pk_mul_f32 v[72:73], v[72:73], v[72:73]
	v_pk_mul_f32 v[76:77], v[76:77], v[76:77]
	v_add_f32_e32 v78, v78, v79
	v_add_f32_e32 v79, v80, v81
	v_pk_fma_f32 v[66:67], v[66:67], v[66:67], v[68:69]
	v_pk_fma_f32 v[68:69], v[70:71], v[70:71], v[72:73]
	v_pk_fma_f32 v[70:71], v[74:75], v[74:75], v[76:77]
	v_add_f32_e32 v72, v79, v78
	v_add_f32_e32 v70, v72, v70
	v_add_f32_e32 v70, v70, v71
	v_add_f32_e32 v68, v70, v68
	v_add_f32_e32 v68, v68, v69
	v_add_f32_e32 v66, v68, v66
	v_add_f32_e32 v66, v66, v67
	ds_bpermute_b32 v67, v44, v66
	s_waitcnt vmcnt(7)
	v_lshlrev_b32_e32 v82, 16, v56
	v_and_b32_e32 v83, 0xffff0000, v56
	v_lshlrev_b32_e32 v56, 16, v57
	v_and_b32_e32 v57, 0xffff0000, v57
	s_waitcnt lgkmcnt(0)
	v_add_f32_e32 v66, v66, v67
	ds_bpermute_b32 v67, v45, v66
	v_lshlrev_b32_e32 v84, 16, v58
	v_and_b32_e32 v85, 0xffff0000, v58
	v_lshlrev_b32_e32 v58, 16, v59
	v_and_b32_e32 v59, 0xffff0000, v59
	s_waitcnt lgkmcnt(0)
	v_add_f32_e32 v66, v66, v67
	ds_bpermute_b32 v67, v46, v66
	s_waitcnt vmcnt(6)
	v_lshlrev_b32_e32 v86, 16, v34
	v_and_b32_e32 v87, 0xffff0000, v34
	v_lshlrev_b32_e32 v34, 16, v35
	v_and_b32_e32 v35, 0xffff0000, v35
	s_waitcnt lgkmcnt(0)
	v_add_f32_e32 v66, v66, v67
	ds_bpermute_b32 v67, v47, v66
	v_lshlrev_b32_e32 v88, 16, v36
	v_and_b32_e32 v89, 0xffff0000, v36
	v_lshlrev_b32_e32 v36, 16, v37
	v_and_b32_e32 v37, 0xffff0000, v37
	s_waitcnt lgkmcnt(0)
	v_add_f32_e32 v66, v66, v67
	v_fmamk_f32 v66, v66, 0x3b800000, v27
	v_mul_f32_e32 v67, 0x4b800000, v66
	v_cmp_gt_f32_e32 vcc, s24, v66
	s_nop 1
	v_cndmask_b32_e32 v66, v66, v67, vcc
	v_rsq_f32_e32 v66, v66
	s_nop 0
	v_mul_f32_e32 v67, 0x45800000, v66
	v_cndmask_b32_e32 v66, v66, v67, vcc
	v_pk_mul_f32 v[48:49], v[48:49], v[66:67] op_sel_hi:[1,0]
	v_pk_mul_f32 v[20:21], v[20:21], v[66:67] op_sel_hi:[1,0]
	v_pk_mul_f32 v[50:51], v[50:51], v[66:67] op_sel_hi:[1,0]
	v_pk_mul_f32 v[22:23], v[22:23], v[66:67] op_sel_hi:[1,0]
	v_pk_mul_f32 v[52:53], v[52:53], v[66:67] op_sel_hi:[1,0]
	v_pk_mul_f32 v[16:17], v[16:17], v[66:67] op_sel_hi:[1,0]
	v_pk_mul_f32 v[54:55], v[54:55], v[66:67] op_sel_hi:[1,0]
	v_pk_mul_f32 v[18:19], v[18:19], v[66:67] op_sel_hi:[1,0]
	v_pk_mul_f32 v[12:13], v[12:13], v[48:49]
	v_pk_mul_f32 v[14:15], v[14:15], v[20:21]
	v_pk_mul_f32 v[8:9], v[8:9], v[50:51]
	v_pk_mul_f32 v[10:11], v[10:11], v[22:23]
	v_pk_mul_f32 v[4:5], v[4:5], v[52:53]
	v_pk_mul_f32 v[6:7], v[16:17], v[6:7]
	v_pk_mul_f32 v[0:1], v[54:55], v[0:1]
	v_pk_mul_f32 v[2:3], v[18:19], v[2:3]
	v_pk_mul_f32 v[12:13], v[12:13], v[82:83]
	v_pk_mul_f32 v[14:15], v[14:15], v[56:57]
	v_pk_mul_f32 v[8:9], v[8:9], v[84:85]
	v_pk_mul_f32 v[10:11], v[10:11], v[58:59]
	v_pk_mul_f32 v[4:5], v[4:5], v[86:87]
	v_pk_mul_f32 v[6:7], v[6:7], v[34:35]
	v_pk_mul_f32 v[16:17], v[0:1], v[88:89]
	v_pk_mul_f32 v[18:19], v[2:3], v[36:37]
	v_cvt_pk_bf16_f32 v0, v12, v13
	v_cvt_pk_bf16_f32 v1, v14, v15
	v_cvt_pk_bf16_f32 v2, v8, v9
	v_cvt_pk_bf16_f32 v3, v10, v11
	v_cvt_pk_bf16_f32 v4, v4, v5
	v_cvt_pk_bf16_f32 v5, v6, v7
	v_cvt_pk_bf16_f32 v6, v16, v17
	v_cvt_pk_bf16_f32 v7, v18, v19
	global_store_dwordx4 v[60:61], v[0:3], off
	global_store_dwordx4 v[60:61], v[4:7], off offset:16
	global_load_dwordx4 v[0:3], v[62:63], off
	s_nop 0
	global_load_dwordx4 v[4:7], v[64:65], off
	global_load_dwordx4 v[8:11], v[62:63], off offset:16
	global_load_dwordx4 v[12:15], v[64:65], off offset:16
	global_load_dwordx4 v[16:19], v[32:33], off
	global_load_dwordx4 v[20:23], v[32:33], off offset:16
	global_load_dwordx4 v[34:37], v[28:29], off offset:48
	global_load_dwordx4 v[48:51], v[28:29], off offset:32
	global_load_dwordx4 v[52:55], v[28:29], off offset:16
	global_load_dwordx4 v[56:59], v[28:29], off
	s_cmp_lg_u64 s[18:19], 0
	s_cbranch_scc1 .Lcmb_pf_last
	s_mov_b32 s98, 0xf8000000
	s_mov_b32 s99, -1
	v_lshl_add_u64 v[204:205], v[30:31], 0, s[98:99]
	v_lshl_add_u64 v[206:207], v[30:31], 0, s[10:11]
	global_load_dwordx4 v[200:203], v[30:31], off
	global_load_dwordx4 v[200:203], v[30:31], off offset:16
	global_load_dwordx4 v[200:203], v[204:205], off
	global_load_dwordx4 v[200:203], v[204:205], off offset:16
	global_load_dwordx4 v[200:203], v[206:207], off
	global_load_dwordx4 v[200:203], v[206:207], off offset:16
	s_branch .Lcmb_pf_done
.Lcmb_pf_last:
	global_load_dwordx4 v[200:203], v[62:63], off
	global_load_dwordx4 v[200:203], v[62:63], off offset:16
	global_load_dwordx4 v[200:203], v[64:65], off
	global_load_dwordx4 v[200:203], v[64:65], off offset:16
	global_load_dwordx4 v[200:203], v[32:33], off
	global_load_dwordx4 v[200:203], v[32:33], off offset:16
.Lcmb_pf_done:
	s_waitcnt vmcnt(15)
	v_lshlrev_b32_e32 v60, 16, v0
	s_waitcnt vmcnt(14)
	v_lshlrev_b32_e32 v62, 16, v4
	v_and_b32_e32 v61, 0xffff0000, v0
	v_and_b32_e32 v63, 0xffff0000, v4
	v_lshlrev_b32_e32 v0, 16, v1
	v_lshlrev_b32_e32 v4, 16, v5
	v_and_b32_e32 v1, 0xffff0000, v1
	v_and_b32_e32 v5, 0xffff0000, v5
	v_lshlrev_b32_e32 v64, 16, v2
	v_lshlrev_b32_e32 v66, 16, v6
	v_and_b32_e32 v65, 0xffff0000, v2
	v_and_b32_e32 v67, 0xffff0000, v6
	v_lshlrev_b32_e32 v2, 16, v3
	v_lshlrev_b32_e32 v6, 16, v7
	v_and_b32_e32 v3, 0xffff0000, v3
	v_and_b32_e32 v7, 0xffff0000, v7
	s_waitcnt vmcnt(13)
	v_lshlrev_b32_e32 v68, 16, v8
	s_waitcnt vmcnt(12)
	v_lshlrev_b32_e32 v70, 16, v12
	v_and_b32_e32 v69, 0xffff0000, v8
	v_and_b32_e32 v71, 0xffff0000, v12
	v_lshlrev_b32_e32 v8, 16, v9
	v_lshlrev_b32_e32 v12, 16, v13
	v_and_b32_e32 v9, 0xffff0000, v9
	v_and_b32_e32 v13, 0xffff0000, v13
	v_lshlrev_b32_e32 v72, 16, v10
	v_lshlrev_b32_e32 v74, 16, v14
	v_and_b32_e32 v73, 0xffff0000, v10
	v_and_b32_e32 v75, 0xffff0000, v14
	v_lshlrev_b32_e32 v10, 16, v11
	v_lshlrev_b32_e32 v14, 16, v15
	v_and_b32_e32 v11, 0xffff0000, v11
	v_and_b32_e32 v15, 0xffff0000, v15
	v_pk_add_f32 v[10:11], v[10:11], v[14:15]
	v_pk_add_f32 v[14:15], v[72:73], v[74:75]
	v_pk_add_f32 v[8:9], v[8:9], v[12:13]
	v_pk_add_f32 v[12:13], v[68:69], v[70:71]
	v_pk_add_f32 v[2:3], v[2:3], v[6:7]
	v_pk_add_f32 v[6:7], v[64:65], v[66:67]
	v_pk_add_f32 v[0:1], v[0:1], v[4:5]
	v_pk_add_f32 v[4:5], v[60:61], v[62:63]
	v_mov_b32_e32 v62, v15
	v_mov_b32_e32 v63, v11
	v_mov_b32_e32 v66, v13
	v_mov_b32_e32 v67, v9
	v_mov_b32_e32 v70, v7
	v_mov_b32_e32 v71, v3
	v_pk_mul_f32 v[72:73], v[0:1], v[0:1]
	v_pk_mul_f32 v[74:75], v[4:5], v[4:5]
	v_mov_b32_e32 v60, v14
	v_mov_b32_e32 v61, v10
	v_mov_b32_e32 v64, v12
	v_mov_b32_e32 v65, v8
	v_mov_b32_e32 v68, v6
	v_mov_b32_e32 v69, v2
	v_pk_mul_f32 v[62:63], v[62:63], v[62:63]
	v_pk_mul_f32 v[66:67], v[66:67], v[66:67]
	v_pk_mul_f32 v[70:71], v[70:71], v[70:71]
	v_add_f32_e32 v72, v72, v73
	v_add_f32_e32 v73, v74, v75
	v_pk_fma_f32 v[60:61], v[60:61], v[60:61], v[62:63]
	v_pk_fma_f32 v[62:63], v[64:65], v[64:65], v[66:67]
	v_pk_fma_f32 v[64:65], v[68:69], v[68:69], v[70:71]
	v_add_f32_e32 v66, v73, v72
	v_add_f32_e32 v64, v66, v64
	v_add_f32_e32 v64, v64, v65
	v_add_f32_e32 v62, v64, v62
	v_add_f32_e32 v62, v62, v63
	v_add_f32_e32 v60, v62, v60
	v_add_f32_e32 v60, v60, v61
	ds_bpermute_b32 v61, v44, v60
	s_waitcnt vmcnt(11)
	v_lshlrev_b32_e32 v76, 16, v16
	v_and_b32_e32 v77, 0xffff0000, v16
	v_lshlrev_b32_e32 v16, 16, v17
	v_and_b32_e32 v17, 0xffff0000, v17
	s_waitcnt lgkmcnt(0)
	v_add_f32_e32 v60, v60, v61
	ds_bpermute_b32 v61, v45, v60
	v_lshlrev_b32_e32 v78, 16, v18
	v_and_b32_e32 v79, 0xffff0000, v18
	v_lshlrev_b32_e32 v18, 16, v19
	v_and_b32_e32 v19, 0xffff0000, v19
	s_waitcnt lgkmcnt(0)
	v_add_f32_e32 v60, v60, v61
	ds_bpermute_b32 v61, v46, v60
	s_waitcnt vmcnt(10)
	v_lshlrev_b32_e32 v80, 16, v20
	v_and_b32_e32 v81, 0xffff0000, v20
	v_lshlrev_b32_e32 v20, 16, v21
	v_and_b32_e32 v21, 0xffff0000, v21
	s_waitcnt lgkmcnt(0)
	v_add_f32_e32 v60, v60, v61
	ds_bpermute_b32 v61, v47, v60
	v_lshlrev_b32_e32 v82, 16, v22
	v_and_b32_e32 v83, 0xffff0000, v22
	v_lshlrev_b32_e32 v22, 16, v23
	v_and_b32_e32 v23, 0xffff0000, v23
	s_waitcnt lgkmcnt(0)
	v_add_f32_e32 v60, v60, v61
	v_fmamk_f32 v60, v60, 0x3b800000, v27
	v_mul_f32_e32 v61, 0x4b800000, v60
	v_cmp_gt_f32_e32 vcc, s24, v60
	s_nop 1
	v_cndmask_b32_e32 v60, v60, v61, vcc
	v_rsq_f32_e32 v60, v60
	s_nop 0
	v_mul_f32_e32 v61, 0x45800000, v60
	v_cndmask_b32_e32 v60, v60, v61, vcc
	v_pk_mul_f32 v[4:5], v[4:5], v[60:61] op_sel_hi:[1,0]
	v_pk_mul_f32 v[0:1], v[0:1], v[60:61] op_sel_hi:[1,0]
	v_pk_mul_f32 v[6:7], v[6:7], v[60:61] op_sel_hi:[1,0]
	v_pk_mul_f32 v[2:3], v[2:3], v[60:61] op_sel_hi:[1,0]
	v_pk_mul_f32 v[12:13], v[12:13], v[60:61] op_sel_hi:[1,0]
	v_pk_mul_f32 v[8:9], v[8:9], v[60:61] op_sel_hi:[1,0]
	v_pk_mul_f32 v[14:15], v[14:15], v[60:61] op_sel_hi:[1,0]
	v_pk_mul_f32 v[10:11], v[10:11], v[60:61] op_sel_hi:[1,0]
	s_waitcnt vmcnt(6)
	v_pk_mul_f32 v[4:5], v[56:57], v[4:5]
	v_pk_mul_f32 v[0:1], v[58:59], v[0:1]
	v_pk_mul_f32 v[6:7], v[52:53], v[6:7]
	v_pk_mul_f32 v[2:3], v[54:55], v[2:3]
	v_pk_mul_f32 v[12:13], v[48:49], v[12:13]
	v_pk_mul_f32 v[8:9], v[8:9], v[50:51]
	v_pk_mul_f32 v[14:15], v[14:15], v[34:35]
	v_pk_mul_f32 v[10:11], v[10:11], v[36:37]
	v_pk_mul_f32 v[4:5], v[4:5], v[76:77]
	v_pk_mul_f32 v[16:17], v[0:1], v[16:17]
	v_pk_mul_f32 v[6:7], v[6:7], v[78:79]
	v_pk_mul_f32 v[18:19], v[2:3], v[18:19]
	v_pk_mul_f32 v[12:13], v[12:13], v[80:81]
	v_pk_mul_f32 v[8:9], v[8:9], v[20:21]
	v_pk_mul_f32 v[14:15], v[14:15], v[82:83]
	v_pk_mul_f32 v[10:11], v[10:11], v[22:23]
	v_cvt_pk_bf16_f32 v0, v4, v5
	v_cvt_pk_bf16_f32 v1, v16, v17
	v_cvt_pk_bf16_f32 v2, v6, v7
	v_cvt_pk_bf16_f32 v3, v18, v19
	v_cvt_pk_bf16_f32 v4, v12, v13
	v_cvt_pk_bf16_f32 v5, v8, v9
	v_cvt_pk_bf16_f32 v6, v14, v15
	v_cvt_pk_bf16_f32 v7, v10, v11
	global_store_dwordx4 v[32:33], v[0:3], off
	global_store_dwordx4 v[32:33], v[4:7], off offset:16
	s_andn2_b64 exec, exec, s[18:19]
	s_cbranch_execnz .LBB0_1218
	s_branch .LBB0_1215
.LBB0_1219:
	s_waitcnt vmcnt(0)
	s_barrier
	s_and_saveexec_b64 s[6:7], s[92:93]
	s_cbranch_execz .LBB0_1225
	s_mov_b64 s[10:11], exec
	v_mbcnt_lo_u32_b32 v0, s10, 0
	v_mbcnt_hi_u32_b32 v0, s11, v0
	v_cmp_eq_u32_e32 vcc, 0, v0
	buffer_wbl2 sc1
	s_waitcnt vmcnt(0)
	buffer_inv sc1
	s_and_saveexec_b64 s[8:9], vcc
	s_cbranch_execz .LBB0_1222
	s_bcnt1_i32_b64 s3, s[10:11]
	v_mov_b32_e32 v0, 0
	v_mov_b32_e32 v1, s3
	global_atomic_add v0, v1, s[36:37]

.LBB0_1227:
	s_or_b64 exec, exec, s[14:15]
	v_mov_b32_e32 v141, v148
	s_add_i32 s28, s28, s50
	v_and_b32_e32 v128, 15, v141
	v_ashrrev_i32_e32 v130, 2, v141
	v_lshrrev_b32_e32 v131, 1, v141
	v_and_b32_e32 v140, 0xffffffc0, v130
	v_or_b32_e32 v130, s10, v128
	v_and_b32_e32 v131, 0x60, v131
	v_lshrrev_b32_e32 v132, 2, v141
	v_add_u32_e32 v130, v130, v140
	v_and_or_b32 v149, v132, 12, v131
	v_or_b32_e32 v132, s12, v149
	v_ashrrev_i32_e32 v131, 31, v130
	v_ashrrev_i32_e32 v133, 31, v132
	v_lshlrev_b64 v[134:135], 12, v[130:131]
	v_lshl_add_u64 v[134:135], s[52:53], 0, v[134:135]
	v_lshlrev_b64 v[132:133], 1, v[132:133]
	v_lshl_add_u64 v[136:137], v[134:135], 0, v[132:133]
	v_or_b32_e32 v134, 16, v130
	v_ashrrev_i32_e32 v135, 31, v134
	v_lshlrev_b64 v[134:135], 12, v[134:135]
	v_lshl_add_u64 v[134:135], s[52:53], 0, v[134:135]
	global_load_dwordx2 v[142:143], v[136:137], off
	global_load_dwordx2 v[144:145], v[136:137], off offset:2048
	global_load_dwordx2 v[146:147], v[136:137], off offset:2080
	global_load_dwordx2 v[152:153], v[136:137], off offset:32
	v_lshl_add_u64 v[138:139], v[134:135], 0, v[132:133]
	global_load_dwordx2 v[154:155], v[138:139], off
	global_load_dwordx2 v[156:157], v[138:139], off offset:2048
	global_load_dwordx2 v[158:159], v[138:139], off offset:2080
	global_load_dwordx2 v[160:161], v[138:139], off offset:32
	v_or_b32_e32 v131, v140, v128
	v_mul_lo_u32 v131, v131, s26
	v_lshl_add_u32 v140, v149, 1, v131
	v_or_b32_e32 v134, 32, v130
	v_add_u32_e32 v131, 0x1000, v140
	v_ashrrev_i32_e32 v135, 31, v134
	v_lshlrev_b64 v[134:135], 12, v[134:135]
	v_lshl_add_u64 v[134:135], s[52:53], 0, v[134:135]
	v_lshl_add_u64 v[134:135], v[134:135], 0, v[132:133]
	s_add_i32 s27, s27, s50
	s_waitcnt vmcnt(0)
	v_lshlrev_b32_e32 v162, 16, v142
	v_lshlrev_b32_e32 v164, 16, v144
	v_and_b32_e32 v163, 0xffff0000, v142
	v_and_b32_e32 v165, 0xffff0000, v144
	v_lshlrev_b32_e32 v142, 16, v143
	v_lshlrev_b32_e32 v144, 16, v145
	v_and_b32_e32 v143, 0xffff0000, v143
	v_and_b32_e32 v145, 0xffff0000, v145
	v_lshlrev_b32_e32 v166, 16, v152
	v_lshlrev_b32_e32 v168, 16, v146
	v_and_b32_e32 v167, 0xffff0000, v152
	v_and_b32_e32 v169, 0xffff0000, v146
	v_lshlrev_b32_e32 v152, 16, v153
	v_lshlrev_b32_e32 v146, 16, v147
	v_and_b32_e32 v153, 0xffff0000, v153
	v_and_b32_e32 v147, 0xffff0000, v147
	v_pk_fma_f32 v[122:123], v[122:123], v[144:145], v[142:143]
	v_pk_fma_f32 v[126:127], v[126:127], v[146:147], v[152:153]
	v_lshlrev_b32_e32 v142, 16, v154
	v_lshlrev_b32_e32 v144, 16, v156
	v_and_b32_e32 v143, 0xffff0000, v154
	v_and_b32_e32 v145, 0xffff0000, v156
	v_lshlrev_b32_e32 v146, 16, v155
	v_lshlrev_b32_e32 v152, 16, v157
	v_and_b32_e32 v147, 0xffff0000, v155
	v_and_b32_e32 v153, 0xffff0000, v157
	v_lshlrev_b32_e32 v154, 16, v160
	v_lshlrev_b32_e32 v156, 16, v158
	v_and_b32_e32 v155, 0xffff0000, v160
	v_and_b32_e32 v157, 0xffff0000, v158
	v_lshlrev_b32_e32 v160, 16, v161
	v_lshlrev_b32_e32 v158, 16, v159
	v_and_b32_e32 v161, 0xffff0000, v161
	v_and_b32_e32 v159, 0xffff0000, v159
	v_pk_fma_f32 v[112:113], v[112:113], v[144:145], v[142:143]
	v_pk_fma_f32 v[114:115], v[114:115], v[152:153], v[146:147]
	v_pk_fma_f32 v[116:117], v[116:117], v[156:157], v[154:155]
	v_pk_fma_f32 v[118:119], v[118:119], v[158:159], v[160:161]
	v_cvt_pk_bf16_f32 v112, v112, v113
	v_cvt_pk_bf16_f32 v113, v114, v115
	v_cvt_pk_bf16_f32 v114, v116, v117
	v_cvt_pk_bf16_f32 v115, v118, v119
	v_pk_fma_f32 v[120:121], v[120:121], v[164:165], v[162:163]
	v_pk_fma_f32 v[124:125], v[124:125], v[168:169], v[166:167]
	ds_write2_b64 v131, v[112:113], v[114:115] offset0:32 offset1:36
	v_or_b32_e32 v112, 48, v130
	v_cvt_pk_bf16_f32 v120, v120, v121
	v_cvt_pk_bf16_f32 v121, v122, v123
	v_cvt_pk_bf16_f32 v122, v124, v125
	v_cvt_pk_bf16_f32 v123, v126, v127
	v_ashrrev_i32_e32 v113, 31, v112
	ds_write2_b64 v140, v[120:121], v[122:123] offset1:4
	v_lshlrev_b64 v[112:113], 12, v[112:113]
	v_lshl_add_u64 v[112:113], s[52:53], 0, v[112:113]
	global_load_dwordx2 v[122:123], v[134:135], off
	global_load_dwordx2 v[124:125], v[134:135], off offset:2048
	global_load_dwordx2 v[126:127], v[134:135], off offset:2080
	global_load_dwordx2 v[142:143], v[134:135], off offset:32
	v_lshl_add_u64 v[118:119], v[112:113], 0, v[132:133]
	global_load_dwordx2 v[144:145], v[118:119], off
	global_load_dwordx2 v[146:147], v[118:119], off offset:2048
	global_load_dwordx2 v[152:153], v[118:119], off offset:2080
	global_load_dwordx2 v[154:155], v[118:119], off offset:32
	v_lshlrev_b32_e32 v112, 3, v141
	v_ashrrev_i32_e32 v120, 4, v141
	v_lshlrev_b32_e32 v113, 4, v141
	v_add_u32_e32 v114, 0x200, v141
	v_lshlrev_b32_e32 v156, 4, v128
	v_and_or_b32 v116, v112, 64, s12
	v_and_b32_e32 v128, 0x70, v113
	v_ashrrev_i32_e32 v121, 4, v114
	v_mad_u64_u32 v[112:113], s[12:13], v120, s26, v[156:157]
	v_mad_u64_u32 v[114:115], s[12:13], v121, s26, v[156:157]
	v_add_u32_e32 v113, 0x2000, v140
	v_add_u32_e32 v158, s10, v120
	v_add_u32_e32 v115, 0x3000, v140
	v_ashrrev_i32_e32 v159, 31, v158
	v_ashrrev_i32_e32 v117, 31, v116
	v_lshlrev_b64 v[158:159], 11, v[158:159]
	v_lshlrev_b64 v[116:117], 1, v[116:117]
	v_add_u32_e32 v160, s10, v121
	v_ashrrev_i32_e32 v161, 31, v160
	s_waitcnt vmcnt(7)
	v_lshlrev_b32_e32 v162, 16, v122
	s_waitcnt vmcnt(6)
	v_lshlrev_b32_e32 v164, 16, v124
	v_and_b32_e32 v163, 0xffff0000, v122
	v_and_b32_e32 v165, 0xffff0000, v124
	v_lshlrev_b32_e32 v122, 16, v123
	v_lshlrev_b32_e32 v124, 16, v125
	v_and_b32_e32 v123, 0xffff0000, v123
	v_and_b32_e32 v125, 0xffff0000, v125
	s_waitcnt vmcnt(4)
	v_lshlrev_b32_e32 v166, 16, v142
	v_lshlrev_b32_e32 v168, 16, v126
	v_and_b32_e32 v167, 0xffff0000, v142
	v_and_b32_e32 v169, 0xffff0000, v126
	v_lshlrev_b32_e32 v142, 16, v143
	v_lshlrev_b32_e32 v126, 16, v127
	v_and_b32_e32 v143, 0xffff0000, v143
	v_and_b32_e32 v127, 0xffff0000, v127
	s_waitcnt vmcnt(3)
	v_lshlrev_b32_e32 v170, 16, v144
	s_waitcnt vmcnt(2)
	v_lshlrev_b32_e32 v172, 16, v146
	v_and_b32_e32 v171, 0xffff0000, v144
	v_and_b32_e32 v173, 0xffff0000, v146
	v_lshlrev_b32_e32 v144, 16, v145
	v_lshlrev_b32_e32 v146, 16, v147
	v_and_b32_e32 v145, 0xffff0000, v145
	v_and_b32_e32 v147, 0xffff0000, v147
	s_waitcnt vmcnt(0)
	v_lshlrev_b32_e32 v174, 16, v154
	v_lshlrev_b32_e32 v176, 16, v152
	v_and_b32_e32 v175, 0xffff0000, v154
	v_and_b32_e32 v177, 0xffff0000, v152
	v_lshlrev_b32_e32 v154, 16, v155
	v_lshlrev_b32_e32 v152, 16, v153
	v_and_b32_e32 v155, 0xffff0000, v155
	v_and_b32_e32 v153, 0xffff0000, v153
	v_pk_fma_f32 v[96:97], v[96:97], v[164:165], v[162:163]
	v_pk_fma_f32 v[98:99], v[98:99], v[124:125], v[122:123]
	v_pk_fma_f32 v[100:101], v[100:101], v[168:169], v[166:167]
	v_pk_fma_f32 v[102:103], v[102:103], v[126:127], v[142:143]
	v_pk_fma_f32 v[104:105], v[104:105], v[172:173], v[170:171]
	v_pk_fma_f32 v[106:107], v[106:107], v[146:147], v[144:145]
	v_pk_fma_f32 v[108:109], v[108:109], v[176:177], v[174:175]
	v_pk_fma_f32 v[110:111], v[110:111], v[152:153], v[154:155]
	v_cvt_pk_bf16_f32 v96, v96, v97
	v_cvt_pk_bf16_f32 v97, v98, v99
	v_cvt_pk_bf16_f32 v98, v100, v101
	v_cvt_pk_bf16_f32 v99, v102, v103
	v_cvt_pk_bf16_f32 v100, v104, v105
	v_cvt_pk_bf16_f32 v101, v106, v107
	v_cvt_pk_bf16_f32 v102, v108, v109
	v_cvt_pk_bf16_f32 v103, v110, v111
	ds_write2_b64 v113, v[96:97], v[98:99] offset0:64 offset1:68
	ds_write2_b64 v115, v[100:101], v[102:103] offset0:96 offset1:100
	s_waitcnt lgkmcnt(0)
	s_barrier
	ds_read_b128 v[96:99], v112
	ds_read_b128 v[104:107], v114
	v_lshl_add_u64 v[100:101], s[56:57], 0, v[158:159]
	v_lshl_add_u64 v[100:101], v[100:101], 0, v[116:117]
	v_lshl_add_u64 v[100:101], v[100:101], 0, v[128:129]
	s_waitcnt lgkmcnt(1)
	global_store_dwordx4 v[100:101], v[96:99], off sc1
	s_nop 1
	v_lshlrev_b64 v[96:97], 11, v[160:161]
	v_lshl_add_u64 v[96:97], s[56:57], 0, v[96:97]
	v_lshl_add_u64 v[96:97], v[96:97], 0, v[116:117]
	v_lshl_add_u64 v[102:103], v[96:97], 0, v[128:129]
	v_add_u32_e32 v96, 0x400, v141
	v_ashrrev_i32_e32 v108, 4, v96
	v_add_u32_e32 v96, s10, v108
	v_ashrrev_i32_e32 v97, 31, v96
	v_lshlrev_b64 v[96:97], 11, v[96:97]
	v_lshl_add_u64 v[96:97], s[56:57], 0, v[96:97]
	v_lshl_add_u64 v[96:97], v[96:97], 0, v[116:117]
	s_waitcnt lgkmcnt(0)
	global_store_dwordx4 v[102:103], v[104:107], off sc1
	s_nop 1
	v_lshl_add_u64 v[104:105], v[96:97], 0, v[128:129]
	v_mad_u64_u32 v[96:97], s[12:13], v108, s26, v[156:157]
	v_add_u32_e32 v97, 0x600, v141
	v_ashrrev_i32_e32 v97, 4, v97
	v_mad_u64_u32 v[98:99], s[12:13], v97, s26, v[156:157]
	v_add_u32_e32 v106, s10, v97
	ds_read_b128 v[122:125], v96
	ds_read_b128 v[142:145], v98
	v_ashrrev_i32_e32 v107, 31, v106
	v_lshlrev_b64 v[106:107], 11, v[106:107]
	v_lshl_add_u64 v[106:107], s[56:57], 0, v[106:107]
	v_lshl_add_u64 v[106:107], v[106:107], 0, v[116:117]
	v_lshl_add_u64 v[106:107], v[106:107], 0, v[128:129]
	s_waitcnt lgkmcnt(1)
	global_store_dwordx4 v[104:105], v[122:125], off sc1
	s_waitcnt lgkmcnt(0)
	global_store_dwordx4 v[106:107], v[142:145], off sc1
	s_barrier
	global_load_dwordx2 v[110:111], v[136:137], off offset:256
	global_load_dwordx2 v[122:123], v[136:137], off offset:2304
	global_load_dwordx2 v[124:125], v[136:137], off offset:2336
	global_load_dwordx2 v[126:127], v[136:137], off offset:288
	s_nop 0
	global_load_dwordx2 v[136:137], v[138:139], off offset:2304
	global_load_dwordx2 v[142:143], v[138:139], off offset:256
	global_load_dwordx2 v[144:145], v[138:139], off offset:288
	s_nop 0
	global_load_dwordx2 v[138:139], v[138:139], off offset:2336
	s_bitset1_b32 s10, 7
	s_cmpk_lt_i32 s28, 0x400
	s_waitcnt vmcnt(7)
	v_lshlrev_b32_e32 v146, 16, v110
	s_waitcnt vmcnt(6)
	v_lshlrev_b32_e32 v152, 16, v122
	v_and_b32_e32 v147, 0xffff0000, v110
	v_and_b32_e32 v153, 0xffff0000, v122
	v_lshlrev_b32_e32 v110, 16, v111
	v_lshlrev_b32_e32 v122, 16, v123
	v_and_b32_e32 v111, 0xffff0000, v111
	v_and_b32_e32 v123, 0xffff0000, v123
	s_waitcnt vmcnt(4)
	v_lshlrev_b32_e32 v154, 16, v126
	v_lshlrev_b32_e32 v156, 16, v124
	v_and_b32_e32 v155, 0xffff0000, v126
	v_and_b32_e32 v157, 0xffff0000, v124
	v_lshlrev_b32_e32 v126, 16, v127
	v_lshlrev_b32_e32 v124, 16, v125
	v_and_b32_e32 v127, 0xffff0000, v127
	v_and_b32_e32 v125, 0xffff0000, v125
	s_waitcnt vmcnt(2)
	v_lshlrev_b32_e32 v158, 16, v142
	v_lshlrev_b32_e32 v160, 16, v136
	v_and_b32_e32 v159, 0xffff0000, v142
	v_and_b32_e32 v161, 0xffff0000, v136
	v_lshlrev_b32_e32 v142, 16, v143
	v_lshlrev_b32_e32 v136, 16, v137
	v_and_b32_e32 v143, 0xffff0000, v143
	v_and_b32_e32 v137, 0xffff0000, v137
	s_waitcnt vmcnt(1)
	v_lshlrev_b32_e32 v162, 16, v144
	s_waitcnt vmcnt(0)
	v_lshlrev_b32_e32 v164, 16, v138
	v_and_b32_e32 v163, 0xffff0000, v144
	v_and_b32_e32 v165, 0xffff0000, v138
	v_lshlrev_b32_e32 v144, 16, v145
	v_lshlrev_b32_e32 v138, 16, v139
	v_and_b32_e32 v145, 0xffff0000, v145
	v_pk_fma_f32 v[84:85], v[84:85], v[152:153], v[146:147]
	v_pk_fma_f32 v[86:87], v[86:87], v[122:123], v[110:111]
	v_pk_fma_f32 v[88:89], v[88:89], v[156:157], v[154:155]
	v_pk_fma_f32 v[90:91], v[90:91], v[124:125], v[126:127]
	v_and_b32_e32 v139, 0xffff0000, v139
	v_pk_fma_f32 v[92:93], v[92:93], v[160:161], v[158:159]
	v_pk_fma_f32 v[94:95], v[94:95], v[136:137], v[142:143]
	v_pk_fma_f32 v[80:81], v[80:81], v[164:165], v[162:163]
	v_cvt_pk_bf16_f32 v84, v84, v85
	v_cvt_pk_bf16_f32 v85, v86, v87
	v_cvt_pk_bf16_f32 v86, v88, v89
	v_cvt_pk_bf16_f32 v87, v90, v91
	v_pk_fma_f32 v[82:83], v[82:83], v[138:139], v[144:145]
	ds_write2_b64 v140, v[84:85], v[86:87] offset1:4
	v_cvt_pk_bf16_f32 v84, v92, v93
	v_cvt_pk_bf16_f32 v85, v94, v95
	v_cvt_pk_bf16_f32 v80, v80, v81
	v_cvt_pk_bf16_f32 v81, v82, v83
	ds_write2_b64 v131, v[84:85], v[80:81] offset0:32 offset1:36
	global_load_dwordx2 v[80:81], v[134:135], off offset:256
	global_load_dwordx2 v[82:83], v[134:135], off offset:2304
	global_load_dwordx2 v[84:85], v[134:135], off offset:2336
	global_load_dwordx2 v[86:87], v[134:135], off offset:288
	global_load_dwordx2 v[88:89], v[118:119], off offset:2304
	global_load_dwordx2 v[90:91], v[118:119], off offset:256
	global_load_dwordx2 v[92:93], v[118:119], off offset:288
	global_load_dwordx2 v[94:95], v[118:119], off offset:2336
	v_add_u32_e32 v110, 0x80, v130
	v_ashrrev_i32_e32 v111, 31, v110
	v_lshlrev_b64 v[110:111], 12, v[110:111]
	v_lshl_add_u64 v[110:111], s[52:53], 0, v[110:111]
	s_waitcnt vmcnt(7)
	v_lshlrev_b32_e32 v118, 16, v80
	s_waitcnt vmcnt(6)
	v_lshlrev_b32_e32 v122, 16, v82
	v_and_b32_e32 v119, 0xffff0000, v80
	v_and_b32_e32 v123, 0xffff0000, v82
	v_lshlrev_b32_e32 v80, 16, v81
	v_lshlrev_b32_e32 v82, 16, v83
	v_and_b32_e32 v81, 0xffff0000, v81
	v_and_b32_e32 v83, 0xffff0000, v83
	s_waitcnt vmcnt(4)
	v_lshlrev_b32_e32 v124, 16, v86
	v_lshlrev_b32_e32 v126, 16, v84
	v_and_b32_e32 v125, 0xffff0000, v86
	v_and_b32_e32 v127, 0xffff0000, v84
	v_lshlrev_b32_e32 v86, 16, v87
	v_lshlrev_b32_e32 v84, 16, v85
	v_and_b32_e32 v87, 0xffff0000, v87
	v_and_b32_e32 v85, 0xffff0000, v85
	s_waitcnt vmcnt(2)
	v_lshlrev_b32_e32 v134, 16, v90
	v_lshlrev_b32_e32 v136, 16, v88
	v_and_b32_e32 v135, 0xffff0000, v90
	v_and_b32_e32 v137, 0xffff0000, v88
	v_lshlrev_b32_e32 v90, 16, v91
	v_lshlrev_b32_e32 v88, 16, v89
	v_and_b32_e32 v91, 0xffff0000, v91
	v_and_b32_e32 v89, 0xffff0000, v89
	s_waitcnt vmcnt(1)
	v_lshlrev_b32_e32 v138, 16, v92
	s_waitcnt vmcnt(0)
	v_lshlrev_b32_e32 v142, 16, v94
	v_and_b32_e32 v139, 0xffff0000, v92
	v_and_b32_e32 v143, 0xffff0000, v94
	v_lshlrev_b32_e32 v92, 16, v93
	v_lshlrev_b32_e32 v94, 16, v95
	v_and_b32_e32 v93, 0xffff0000, v93
	v_and_b32_e32 v95, 0xffff0000, v95
	v_pk_fma_f32 v[64:65], v[64:65], v[122:123], v[118:119]
	v_pk_fma_f32 v[66:67], v[66:67], v[82:83], v[80:81]
	v_pk_fma_f32 v[68:69], v[68:69], v[126:127], v[124:125]
	v_pk_fma_f32 v[70:71], v[70:71], v[84:85], v[86:87]
	v_pk_fma_f32 v[72:73], v[72:73], v[136:137], v[134:135]
	v_pk_fma_f32 v[74:75], v[74:75], v[88:89], v[90:91]
	v_pk_fma_f32 v[76:77], v[76:77], v[142:143], v[138:139]
	v_pk_fma_f32 v[78:79], v[78:79], v[94:95], v[92:93]
	v_cvt_pk_bf16_f32 v64, v64, v65
	v_cvt_pk_bf16_f32 v65, v66, v67
	v_cvt_pk_bf16_f32 v66, v68, v69
	v_cvt_pk_bf16_f32 v67, v70, v71
	v_cvt_pk_bf16_f32 v68, v72, v73
	v_cvt_pk_bf16_f32 v69, v74, v75
	v_cvt_pk_bf16_f32 v70, v76, v77
	v_cvt_pk_bf16_f32 v71, v78, v79
	ds_write2_b64 v113, v[64:65], v[66:67] offset0:64 offset1:68
	ds_write2_b64 v115, v[68:69], v[70:71] offset0:96 offset1:100
	s_waitcnt lgkmcnt(0)
	s_barrier
	ds_read_b128 v[68:71], v112
	ds_read_b128 v[72:75], v114
	ds_read_b128 v[76:79], v96
	ds_read_b128 v[80:83], v98
	v_add_u32_e32 v64, 0x90, v130
	v_ashrrev_i32_e32 v65, 31, v64
	v_lshlrev_b64 v[64:65], 12, v[64:65]
	v_lshl_add_u64 v[66:67], v[110:111], 0, v[132:133]
	v_lshl_add_u64 v[64:65], s[52:53], 0, v[64:65]
	s_waitcnt lgkmcnt(3)
	global_store_dwordx4 v[100:101], v[68:71], off offset:256 sc1
	s_waitcnt lgkmcnt(2)
	global_store_dwordx4 v[102:103], v[72:75], off offset:256 sc1
	s_waitcnt lgkmcnt(1)
	global_store_dwordx4 v[104:105], v[76:79], off offset:256 sc1
	s_waitcnt lgkmcnt(0)
	global_store_dwordx4 v[106:107], v[80:83], off offset:256 sc1
	s_barrier
	global_load_dwordx2 v[70:71], v[66:67], off
	global_load_dwordx2 v[72:73], v[66:67], off offset:2048
	global_load_dwordx2 v[74:75], v[66:67], off offset:2080
	global_load_dwordx2 v[76:77], v[66:67], off offset:32
	v_lshl_add_u64 v[68:69], v[64:65], 0, v[132:133]
	global_load_dwordx2 v[78:79], v[68:69], off
	global_load_dwordx2 v[80:81], v[68:69], off offset:2048
	global_load_dwordx2 v[82:83], v[68:69], off offset:2080
	global_load_dwordx2 v[84:85], v[68:69], off offset:32
	v_add_u32_e32 v64, 0xa0, v130
	v_ashrrev_i32_e32 v65, 31, v64
	v_lshlrev_b64 v[64:65], 12, v[64:65]
	v_lshl_add_u64 v[64:65], s[52:53], 0, v[64:65]
	v_lshl_add_u64 v[64:65], v[64:65], 0, v[132:133]
	s_waitcnt vmcnt(7)
	v_lshlrev_b32_e32 v86, 16, v70
	s_waitcnt vmcnt(6)
	v_lshlrev_b32_e32 v88, 16, v72
	v_and_b32_e32 v87, 0xffff0000, v70
	v_and_b32_e32 v89, 0xffff0000, v72
	v_lshlrev_b32_e32 v70, 16, v71
	v_lshlrev_b32_e32 v72, 16, v73
	v_and_b32_e32 v71, 0xffff0000, v71
	v_and_b32_e32 v73, 0xffff0000, v73
	s_waitcnt vmcnt(4)
	v_lshlrev_b32_e32 v90, 16, v76
	v_lshlrev_b32_e32 v92, 16, v74
	v_and_b32_e32 v91, 0xffff0000, v76
	v_and_b32_e32 v93, 0xffff0000, v74
	v_lshlrev_b32_e32 v76, 16, v77
	v_lshlrev_b32_e32 v74, 16, v75
	v_and_b32_e32 v77, 0xffff0000, v77
	v_and_b32_e32 v75, 0xffff0000, v75
	s_waitcnt vmcnt(3)
	v_lshlrev_b32_e32 v94, 16, v78
	s_waitcnt vmcnt(2)
	v_lshlrev_b32_e32 v100, 16, v80
	v_and_b32_e32 v95, 0xffff0000, v78
	v_and_b32_e32 v101, 0xffff0000, v80
	v_lshlrev_b32_e32 v78, 16, v79
	v_lshlrev_b32_e32 v80, 16, v81
	v_and_b32_e32 v79, 0xffff0000, v79
	v_and_b32_e32 v81, 0xffff0000, v81
	s_waitcnt vmcnt(0)
	v_lshlrev_b32_e32 v102, 16, v84
	v_lshlrev_b32_e32 v104, 16, v82
	v_and_b32_e32 v103, 0xffff0000, v84
	v_and_b32_e32 v105, 0xffff0000, v82
	v_lshlrev_b32_e32 v84, 16, v85
	v_lshlrev_b32_e32 v82, 16, v83
	v_and_b32_e32 v85, 0xffff0000, v85
	v_and_b32_e32 v83, 0xffff0000, v83
	v_pk_fma_f32 v[48:49], v[48:49], v[88:89], v[86:87]
	v_pk_fma_f32 v[50:51], v[50:51], v[72:73], v[70:71]
	v_pk_fma_f32 v[52:53], v[52:53], v[92:93], v[90:91]
	v_pk_fma_f32 v[54:55], v[54:55], v[74:75], v[76:77]
	v_pk_fma_f32 v[56:57], v[56:57], v[100:101], v[94:95]
	v_pk_fma_f32 v[58:59], v[58:59], v[80:81], v[78:79]
	v_pk_fma_f32 v[60:61], v[60:61], v[104:105], v[102:103]
	v_pk_fma_f32 v[62:63], v[62:63], v[82:83], v[84:85]
	v_cvt_pk_bf16_f32 v48, v48, v49
	v_cvt_pk_bf16_f32 v49, v50, v51
	v_cvt_pk_bf16_f32 v50, v52, v53
	v_cvt_pk_bf16_f32 v51, v54, v55
	v_cvt_pk_bf16_f32 v52, v56, v57
	v_cvt_pk_bf16_f32 v53, v58, v59
	v_cvt_pk_bf16_f32 v54, v60, v61
	v_cvt_pk_bf16_f32 v55, v62, v63
	ds_write2_b64 v140, v[48:49], v[50:51] offset1:4
	ds_write2_b64 v131, v[52:53], v[54:55] offset0:32 offset1:36
	v_add_u32_e32 v48, 0xb0, v130
	v_ashrrev_i32_e32 v49, 31, v48
	v_lshlrev_b64 v[48:49], 12, v[48:49]
	v_lshl_add_u64 v[48:49], s[52:53], 0, v[48:49]
	global_load_dwordx2 v[56:57], v[64:65], off
	global_load_dwordx2 v[58:59], v[64:65], off offset:2048
	global_load_dwordx2 v[60:61], v[64:65], off offset:2080
	global_load_dwordx2 v[62:63], v[64:65], off offset:32
	v_lshl_add_u64 v[54:55], v[48:49], 0, v[132:133]
	global_load_dwordx2 v[70:71], v[54:55], off
	global_load_dwordx2 v[72:73], v[54:55], off offset:2048
	global_load_dwordx2 v[74:75], v[54:55], off offset:2080
	global_load_dwordx2 v[76:77], v[54:55], off offset:32
	v_add_u32_e32 v48, s10, v120
	v_ashrrev_i32_e32 v49, 31, v48
	v_add_u32_e32 v50, s10, v121
	v_add_u32_e32 v52, s10, v108
	v_add_u32_e32 v78, s10, v97
	v_lshlrev_b64 v[48:49], 11, v[48:49]
	v_ashrrev_i32_e32 v51, 31, v50
	v_ashrrev_i32_e32 v53, 31, v52
	v_ashrrev_i32_e32 v79, 31, v78
	v_lshl_add_u64 v[48:49], s[56:57], 0, v[48:49]
	v_lshlrev_b64 v[50:51], 11, v[50:51]
	v_lshlrev_b64 v[52:53], 11, v[52:53]
	v_lshlrev_b64 v[78:79], 11, v[78:79]
	v_lshl_add_u64 v[48:49], v[48:49], 0, v[116:117]
	v_lshl_add_u64 v[50:51], s[56:57], 0, v[50:51]
	v_lshl_add_u64 v[52:53], s[56:57], 0, v[52:53]
	v_lshl_add_u64 v[78:79], s[56:57], 0, v[78:79]
	v_lshl_add_u64 v[48:49], v[48:49], 0, v[128:129]
	v_lshl_add_u64 v[50:51], v[50:51], 0, v[116:117]
	v_lshl_add_u64 v[52:53], v[52:53], 0, v[116:117]
	v_lshl_add_u64 v[78:79], v[78:79], 0, v[116:117]
	v_lshl_add_u64 v[50:51], v[50:51], 0, v[128:129]
	v_lshl_add_u64 v[52:53], v[52:53], 0, v[128:129]
	s_waitcnt vmcnt(7)
	v_lshlrev_b32_e32 v80, 16, v56
	s_waitcnt vmcnt(6)
	v_lshlrev_b32_e32 v82, 16, v58
	v_and_b32_e32 v81, 0xffff0000, v56
	v_and_b32_e32 v83, 0xffff0000, v58
	v_lshlrev_b32_e32 v56, 16, v57
	v_lshlrev_b32_e32 v58, 16, v59
	v_and_b32_e32 v57, 0xffff0000, v57
	v_and_b32_e32 v59, 0xffff0000, v59
	s_waitcnt vmcnt(4)
	v_lshlrev_b32_e32 v84, 16, v62
	v_lshlrev_b32_e32 v86, 16, v60
	v_and_b32_e32 v85, 0xffff0000, v62
	v_and_b32_e32 v87, 0xffff0000, v60
	v_lshlrev_b32_e32 v62, 16, v63
	v_lshlrev_b32_e32 v60, 16, v61
	v_and_b32_e32 v63, 0xffff0000, v63
	v_and_b32_e32 v61, 0xffff0000, v61
	s_waitcnt vmcnt(3)
	v_lshlrev_b32_e32 v88, 16, v70
	s_waitcnt vmcnt(2)
	v_lshlrev_b32_e32 v90, 16, v72
	v_and_b32_e32 v89, 0xffff0000, v70
	v_and_b32_e32 v91, 0xffff0000, v72
	v_lshlrev_b32_e32 v70, 16, v71
	v_lshlrev_b32_e32 v72, 16, v73
	v_and_b32_e32 v71, 0xffff0000, v71
	v_and_b32_e32 v73, 0xffff0000, v73
	s_waitcnt vmcnt(0)
	v_lshlrev_b32_e32 v92, 16, v76
	v_lshlrev_b32_e32 v94, 16, v74
	v_and_b32_e32 v93, 0xffff0000, v76
	v_and_b32_e32 v95, 0xffff0000, v74
	v_lshlrev_b32_e32 v76, 16, v77
	v_lshlrev_b32_e32 v74, 16, v75
	v_and_b32_e32 v77, 0xffff0000, v77
	v_and_b32_e32 v75, 0xffff0000, v75
	v_pk_fma_f32 v[32:33], v[32:33], v[82:83], v[80:81]
	v_pk_fma_f32 v[34:35], v[34:35], v[58:59], v[56:57]
	v_pk_fma_f32 v[36:37], v[36:37], v[86:87], v[84:85]
	v_pk_fma_f32 v[38:39], v[38:39], v[60:61], v[62:63]
	v_pk_fma_f32 v[40:41], v[40:41], v[90:91], v[88:89]
	v_pk_fma_f32 v[42:43], v[42:43], v[72:73], v[70:71]
	v_pk_fma_f32 v[44:45], v[44:45], v[94:95], v[92:93]
	v_pk_fma_f32 v[46:47], v[46:47], v[74:75], v[76:77]
	v_cvt_pk_bf16_f32 v32, v32, v33
	v_cvt_pk_bf16_f32 v33, v34, v35
	v_cvt_pk_bf16_f32 v34, v36, v37
	v_cvt_pk_bf16_f32 v35, v38, v39
	v_cvt_pk_bf16_f32 v36, v40, v41
	v_cvt_pk_bf16_f32 v37, v42, v43
	v_cvt_pk_bf16_f32 v38, v44, v45
	v_cvt_pk_bf16_f32 v39, v46, v47
	ds_write2_b64 v113, v[32:33], v[34:35] offset0:64 offset1:68
	ds_write2_b64 v115, v[36:37], v[38:39] offset0:96 offset1:100
	s_waitcnt lgkmcnt(0)
	s_barrier
	ds_read_b128 v[34:37], v112
	ds_read_b128 v[38:41], v114
	ds_read_b128 v[42:45], v96
	ds_read_b128 v[56:59], v98
	v_lshl_add_u64 v[32:33], v[78:79], 0, v[128:129]
	s_waitcnt lgkmcnt(3)
	global_store_dwordx4 v[48:49], v[34:37], off sc1
	s_waitcnt lgkmcnt(2)
	global_store_dwordx4 v[50:51], v[38:41], off sc1
	s_waitcnt lgkmcnt(1)
	global_store_dwordx4 v[52:53], v[42:45], off sc1
	s_waitcnt lgkmcnt(0)
	global_store_dwordx4 v[32:33], v[56:59], off sc1
	s_barrier
	global_load_dwordx2 v[34:35], v[66:67], off offset:256
	global_load_dwordx2 v[36:37], v[66:67], off offset:2304
	global_load_dwordx2 v[38:39], v[66:67], off offset:2336
	global_load_dwordx2 v[40:41], v[66:67], off offset:288
	global_load_dwordx2 v[42:43], v[68:69], off offset:2304
	global_load_dwordx2 v[44:45], v[68:69], off offset:256
	global_load_dwordx2 v[46:47], v[68:69], off offset:288
	global_load_dwordx2 v[56:57], v[68:69], off offset:2336
	s_waitcnt vmcnt(7)
	v_lshlrev_b32_e32 v58, 16, v34
	s_waitcnt vmcnt(6)
	v_lshlrev_b32_e32 v60, 16, v36
	v_and_b32_e32 v59, 0xffff0000, v34
	v_and_b32_e32 v61, 0xffff0000, v36
	v_lshlrev_b32_e32 v34, 16, v35
	v_lshlrev_b32_e32 v36, 16, v37
	v_and_b32_e32 v35, 0xffff0000, v35
	v_and_b32_e32 v37, 0xffff0000, v37
	s_waitcnt vmcnt(4)
	v_lshlrev_b32_e32 v62, 16, v40
	v_lshlrev_b32_e32 v66, 16, v38
	v_and_b32_e32 v63, 0xffff0000, v40
	v_and_b32_e32 v67, 0xffff0000, v38
	v_lshlrev_b32_e32 v40, 16, v41
	v_lshlrev_b32_e32 v38, 16, v39
	v_and_b32_e32 v41, 0xffff0000, v41
	v_and_b32_e32 v39, 0xffff0000, v39
	s_waitcnt vmcnt(2)
	v_lshlrev_b32_e32 v68, 16, v44
	v_lshlrev_b32_e32 v70, 16, v42
	v_and_b32_e32 v69, 0xffff0000, v44
	v_and_b32_e32 v71, 0xffff0000, v42
	v_lshlrev_b32_e32 v44, 16, v45
	v_lshlrev_b32_e32 v42, 16, v43
	v_and_b32_e32 v45, 0xffff0000, v45
	v_and_b32_e32 v43, 0xffff0000, v43
	s_waitcnt vmcnt(1)
	v_lshlrev_b32_e32 v72, 16, v46
	s_waitcnt vmcnt(0)
	v_lshlrev_b32_e32 v74, 16, v56
	v_and_b32_e32 v73, 0xffff0000, v46
	v_and_b32_e32 v75, 0xffff0000, v56
	v_lshlrev_b32_e32 v46, 16, v47
	v_lshlrev_b32_e32 v56, 16, v57
	v_and_b32_e32 v47, 0xffff0000, v47
	v_and_b32_e32 v57, 0xffff0000, v57
	v_pk_fma_f32 v[20:21], v[20:21], v[60:61], v[58:59]
	v_pk_fma_f32 v[22:23], v[22:23], v[36:37], v[34:35]
	v_pk_fma_f32 v[24:25], v[24:25], v[66:67], v[62:63]
	v_pk_fma_f32 v[26:27], v[26:27], v[38:39], v[40:41]
	v_pk_fma_f32 v[28:29], v[28:29], v[70:71], v[68:69]
	v_pk_fma_f32 v[30:31], v[30:31], v[42:43], v[44:45]
	v_pk_fma_f32 v[16:17], v[16:17], v[74:75], v[72:73]
	v_pk_fma_f32 v[18:19], v[18:19], v[56:57], v[46:47]
	v_cvt_pk_bf16_f32 v20, v20, v21
	v_cvt_pk_bf16_f32 v21, v22, v23
	v_cvt_pk_bf16_f32 v22, v24, v25
	v_cvt_pk_bf16_f32 v23, v26, v27
	v_cvt_pk_bf16_f32 v24, v28, v29
	v_cvt_pk_bf16_f32 v25, v30, v31
	v_cvt_pk_bf16_f32 v16, v16, v17
	v_cvt_pk_bf16_f32 v17, v18, v19
	ds_write2_b64 v140, v[20:21], v[22:23] offset1:4
	ds_write2_b64 v131, v[24:25], v[16:17] offset0:32 offset1:36
	global_load_dwordx2 v[16:17], v[64:65], off offset:256
	global_load_dwordx2 v[18:19], v[64:65], off offset:2304
	global_load_dwordx2 v[20:21], v[64:65], off offset:2336
	global_load_dwordx2 v[22:23], v[64:65], off offset:288
	global_load_dwordx2 v[24:25], v[54:55], off offset:2304
	global_load_dwordx2 v[26:27], v[54:55], off offset:256
	global_load_dwordx2 v[28:29], v[54:55], off offset:288
	global_load_dwordx2 v[30:31], v[54:55], off offset:2336
	s_waitcnt vmcnt(7)
	v_lshlrev_b32_e32 v34, 16, v16
	s_waitcnt vmcnt(6)
	v_lshlrev_b32_e32 v36, 16, v18
	v_and_b32_e32 v35, 0xffff0000, v16
	v_and_b32_e32 v37, 0xffff0000, v18
	v_lshlrev_b32_e32 v16, 16, v17
	v_lshlrev_b32_e32 v18, 16, v19
	v_and_b32_e32 v17, 0xffff0000, v17
	v_and_b32_e32 v19, 0xffff0000, v19
	s_waitcnt vmcnt(4)
	v_lshlrev_b32_e32 v38, 16, v22
	v_lshlrev_b32_e32 v40, 16, v20
	v_and_b32_e32 v39, 0xffff0000, v22
	v_and_b32_e32 v41, 0xffff0000, v20
	v_lshlrev_b32_e32 v22, 16, v23
	v_lshlrev_b32_e32 v20, 16, v21
	v_and_b32_e32 v23, 0xffff0000, v23
	v_and_b32_e32 v21, 0xffff0000, v21
	s_waitcnt vmcnt(2)
	v_lshlrev_b32_e32 v42, 16, v26
	v_lshlrev_b32_e32 v44, 16, v24
	v_and_b32_e32 v43, 0xffff0000, v26
	v_and_b32_e32 v45, 0xffff0000, v24
	v_lshlrev_b32_e32 v26, 16, v27
	v_lshlrev_b32_e32 v24, 16, v25
	v_and_b32_e32 v27, 0xffff0000, v27
	v_and_b32_e32 v25, 0xffff0000, v25
	s_waitcnt vmcnt(1)
	v_lshlrev_b32_e32 v46, 16, v28
	s_waitcnt vmcnt(0)
	v_lshlrev_b32_e32 v54, 16, v30
	v_and_b32_e32 v47, 0xffff0000, v28
	v_and_b32_e32 v55, 0xffff0000, v30
	v_lshlrev_b32_e32 v28, 16, v29
	v_lshlrev_b32_e32 v30, 16, v31
	v_and_b32_e32 v29, 0xffff0000, v29
	v_and_b32_e32 v31, 0xffff0000, v31
	v_pk_fma_f32 v[0:1], v[0:1], v[36:37], v[34:35]
	v_pk_fma_f32 v[2:3], v[2:3], v[18:19], v[16:17]
	v_pk_fma_f32 v[4:5], v[4:5], v[40:41], v[38:39]
	v_pk_fma_f32 v[6:7], v[6:7], v[20:21], v[22:23]
	v_pk_fma_f32 v[8:9], v[8:9], v[44:45], v[42:43]
	v_pk_fma_f32 v[10:11], v[10:11], v[24:25], v[26:27]
	v_pk_fma_f32 v[12:13], v[12:13], v[54:55], v[46:47]
	v_pk_fma_f32 v[14:15], v[14:15], v[30:31], v[28:29]
	v_cvt_pk_bf16_f32 v0, v0, v1
	v_cvt_pk_bf16_f32 v1, v2, v3
	v_cvt_pk_bf16_f32 v2, v4, v5
	v_cvt_pk_bf16_f32 v3, v6, v7
	v_cvt_pk_bf16_f32 v4, v8, v9
	v_cvt_pk_bf16_f32 v5, v10, v11
	v_cvt_pk_bf16_f32 v6, v12, v13
	v_cvt_pk_bf16_f32 v7, v14, v15
	ds_write2_b64 v113, v[0:1], v[2:3] offset0:64 offset1:68
	ds_write2_b64 v115, v[4:5], v[6:7] offset0:96 offset1:100
	s_waitcnt lgkmcnt(0)
	s_barrier
	ds_read_b128 v[0:3], v112
	ds_read_b128 v[4:7], v114
	ds_read_b128 v[8:11], v96
	ds_read_b128 v[12:15], v98
	s_waitcnt lgkmcnt(3)
	global_store_dwordx4 v[48:49], v[0:3], off offset:256 sc1
	s_waitcnt lgkmcnt(2)
	global_store_dwordx4 v[50:51], v[4:7], off offset:256 sc1
	s_waitcnt lgkmcnt(1)
	global_store_dwordx4 v[52:53], v[8:11], off offset:256 sc1
	s_waitcnt lgkmcnt(0)
	global_store_dwordx4 v[32:33], v[12:15], off offset:256 sc1
	s_barrier
	s_cbranch_scc0 .LBB0_1234

.LBB0_1242:
	s_or_b64 exec, exec, s[14:15]
	v_mov_b32_e32 v135, v148
	v_cvt_pk_bf16_f32 v124, v124, v125
	v_and_b32_e32 v130, 15, v135
	v_lshrrev_b32_e32 v128, 2, v135
	v_and_or_b32 v131, v128, s24, v130
	v_lshrrev_b32_e32 v128, 1, v135
	v_and_b32_e32 v128, 24, v128
	v_and_or_b32 v128, v135, s25, v128
	v_lshlrev_b32_e32 v132, 3, v135
	v_and_or_b32 v132, v132, 64, s12
	v_lshlrev_b32_e32 v134, 4, v130
	v_mad_u64_u32 v[130:131], s[12:13], v131, s26, v[128:129]
	v_cvt_pk_bf16_f32 v125, v126, v127
	v_cvt_pk_bf16_f32 v120, v120, v121
	v_cvt_pk_bf16_f32 v121, v122, v123
	ds_write2_b64 v130, v[124:125], v[120:121] offset1:4
	v_cvt_pk_bf16_f32 v116, v116, v117
	v_cvt_pk_bf16_f32 v117, v118, v119
	v_cvt_pk_bf16_f32 v112, v112, v113
	v_cvt_pk_bf16_f32 v113, v114, v115
	v_add_u32_e32 v120, 0x1000, v130
	ds_write2_b64 v120, v[116:117], v[112:113] offset0:32 offset1:36
	v_cvt_pk_bf16_f32 v100, v100, v101
	v_cvt_pk_bf16_f32 v101, v102, v103
	v_cvt_pk_bf16_f32 v96, v96, v97
	v_cvt_pk_bf16_f32 v97, v98, v99
	v_add_u32_e32 v122, 0x3000, v130
	v_ashrrev_i32_e32 v123, 4, v135
	ds_write2_b64 v122, v[100:101], v[96:97] offset0:96 offset1:100
	v_add_u32_e32 v96, s10, v123
	v_ashrrev_i32_e32 v97, 31, v96
	v_ashrrev_i32_e32 v133, 31, v132
	v_lshlrev_b64 v[96:97], 11, v[96:97]
	v_cvt_pk_bf16_f32 v104, v104, v105
	v_cvt_pk_bf16_f32 v105, v106, v107
	v_lshl_add_u64 v[96:97], s[66:67], 0, v[96:97]
	v_lshlrev_b64 v[106:107], 1, v[132:133]
	v_lshlrev_b32_e32 v98, 4, v135
	v_cvt_pk_bf16_f32 v108, v108, v109
	v_cvt_pk_bf16_f32 v109, v110, v111
	v_add_u32_e32 v121, 0x2000, v130
	v_lshl_add_u64 v[96:97], v[96:97], 0, v[106:107]
	v_and_b32_e32 v128, 0x70, v98
	ds_write2_b64 v121, v[108:109], v[104:105] offset0:64 offset1:68
	v_lshl_add_u64 v[108:109], v[96:97], 0, v[128:129]
	v_mad_u64_u32 v[96:97], s[12:13], v123, s26, v[134:135]
	s_waitcnt vmcnt(0) lgkmcnt(0)
	s_barrier
	ds_read_b128 v[98:101], v96
	v_add_u32_e32 v97, 0x200, v135
	v_ashrrev_i32_e32 v97, 4, v97
	v_mad_u64_u32 v[110:111], s[12:13], v97, s26, v[134:135]
	ds_read_b128 v[102:105], v110
	s_waitcnt lgkmcnt(1)
	global_store_dwordx4 v[108:109], v[98:101], off sc1
	v_cvt_pk_bf16_f32 v92, v92, v93
	v_cvt_pk_bf16_f32 v93, v94, v95
	v_add_u32_e32 v98, s10, v97
	v_ashrrev_i32_e32 v99, 31, v98
	v_lshlrev_b64 v[98:99], 11, v[98:99]
	v_lshl_add_u64 v[98:99], s[66:67], 0, v[98:99]
	v_lshl_add_u64 v[98:99], v[98:99], 0, v[106:107]
	v_lshl_add_u64 v[112:113], v[98:99], 0, v[128:129]
	v_add_u32_e32 v98, 0x400, v135
	v_ashrrev_i32_e32 v111, 4, v98
	v_add_u32_e32 v98, s10, v111
	v_ashrrev_i32_e32 v99, 31, v98
	v_lshlrev_b64 v[98:99], 11, v[98:99]
	v_lshl_add_u64 v[98:99], s[66:67], 0, v[98:99]
	v_lshl_add_u64 v[98:99], v[98:99], 0, v[106:107]
	v_mad_u64_u32 v[116:117], s[12:13], v111, s26, v[134:135]
	v_lshl_add_u64 v[114:115], v[98:99], 0, v[128:129]
	ds_read_b128 v[98:101], v116
	s_waitcnt lgkmcnt(1)
	global_store_dwordx4 v[112:113], v[102:105], off sc1
	v_cvt_pk_bf16_f32 v88, v88, v89
	v_cvt_pk_bf16_f32 v89, v90, v91
	v_add_u32_e32 v102, 0x600, v135
	v_ashrrev_i32_e32 v117, 4, v102
	v_mad_u64_u32 v[118:119], s[12:13], v117, s26, v[134:135]
	ds_read_b128 v[102:105], v118
	s_waitcnt lgkmcnt(1)
	global_store_dwordx4 v[114:115], v[98:101], off sc1
	v_cvt_pk_bf16_f32 v84, v84, v85
	v_cvt_pk_bf16_f32 v85, v86, v87
	v_add_u32_e32 v98, s10, v117
	v_ashrrev_i32_e32 v99, 31, v98
	v_lshlrev_b64 v[98:99], 11, v[98:99]
	v_lshl_add_u64 v[98:99], s[66:67], 0, v[98:99]
	v_lshl_add_u64 v[98:99], v[98:99], 0, v[106:107]
	v_lshl_add_u64 v[98:99], v[98:99], 0, v[128:129]
	v_cvt_pk_bf16_f32 v80, v80, v81
	v_cvt_pk_bf16_f32 v81, v82, v83
	s_waitcnt lgkmcnt(0)
	global_store_dwordx4 v[98:99], v[102:105], off sc1
	s_barrier
	ds_write2_b64 v130, v[92:93], v[88:89] offset1:4
	ds_write2_b64 v120, v[84:85], v[80:81] offset0:32 offset1:36
	v_cvt_pk_bf16_f32 v76, v76, v77
	v_cvt_pk_bf16_f32 v77, v78, v79
	v_cvt_pk_bf16_f32 v72, v72, v73
	v_cvt_pk_bf16_f32 v73, v74, v75
	v_cvt_pk_bf16_f32 v68, v68, v69
	v_cvt_pk_bf16_f32 v69, v70, v71
	v_cvt_pk_bf16_f32 v64, v64, v65
	v_cvt_pk_bf16_f32 v65, v66, v67
	ds_write2_b64 v121, v[76:77], v[72:73] offset0:64 offset1:68
	ds_write2_b64 v122, v[68:69], v[64:65] offset0:96 offset1:100
	s_waitcnt lgkmcnt(0)
	s_barrier
	ds_read_b128 v[64:67], v96
	ds_read_b128 v[68:71], v110
	ds_read_b128 v[72:75], v116
	ds_read_b128 v[76:79], v118
	v_cvt_pk_bf16_f32 v60, v60, v61
	v_cvt_pk_bf16_f32 v61, v62, v63
	v_cvt_pk_bf16_f32 v56, v56, v57
	v_cvt_pk_bf16_f32 v57, v58, v59
	v_cvt_pk_bf16_f32 v52, v52, v53
	v_cvt_pk_bf16_f32 v53, v54, v55
	v_cvt_pk_bf16_f32 v48, v48, v49
	v_cvt_pk_bf16_f32 v49, v50, v51
	s_waitcnt lgkmcnt(3)
	global_store_dwordx4 v[108:109], v[64:67], off offset:256 sc1
	s_waitcnt lgkmcnt(2)
	global_store_dwordx4 v[112:113], v[68:71], off offset:256 sc1
	s_waitcnt lgkmcnt(1)
	global_store_dwordx4 v[114:115], v[72:75], off offset:256 sc1
	s_waitcnt lgkmcnt(0)
	global_store_dwordx4 v[98:99], v[76:79], off offset:256 sc1
	s_barrier
	s_bitset1_b32 s10, 7
	ds_write2_b64 v130, v[60:61], v[56:57] offset1:4
	ds_write2_b64 v120, v[52:53], v[48:49] offset0:32 offset1:36
	v_cvt_pk_bf16_f32 v36, v36, v37
	v_cvt_pk_bf16_f32 v37, v38, v39
	v_cvt_pk_bf16_f32 v32, v32, v33
	v_cvt_pk_bf16_f32 v33, v34, v35
	v_cvt_pk_bf16_f32 v44, v44, v45
	v_cvt_pk_bf16_f32 v45, v46, v47
	v_cvt_pk_bf16_f32 v40, v40, v41
	v_cvt_pk_bf16_f32 v41, v42, v43
	ds_write2_b64 v122, v[36:37], v[32:33] offset0:96 offset1:100
	v_add_u32_e32 v32, s10, v123
	ds_write2_b64 v121, v[44:45], v[40:41] offset0:64 offset1:68
	v_ashrrev_i32_e32 v33, 31, v32
	s_waitcnt lgkmcnt(0)
	s_barrier
	v_lshlrev_b64 v[36:37], 11, v[32:33]
	ds_read_b128 v[32:35], v96
	v_lshl_add_u64 v[36:37], s[66:67], 0, v[36:37]
	v_lshl_add_u64 v[36:37], v[36:37], 0, v[106:107]
	v_lshl_add_u64 v[40:41], v[36:37], 0, v[128:129]
	ds_read_b128 v[36:39], v110
	s_waitcnt lgkmcnt(1)
	global_store_dwordx4 v[40:41], v[32:35], off sc1
	v_cvt_pk_bf16_f32 v28, v28, v29
	v_cvt_pk_bf16_f32 v29, v30, v31
	v_add_u32_e32 v32, s10, v97
	v_ashrrev_i32_e32 v33, 31, v32
	v_lshlrev_b64 v[32:33], 11, v[32:33]
	v_lshl_add_u64 v[32:33], s[66:67], 0, v[32:33]
	v_lshl_add_u64 v[32:33], v[32:33], 0, v[106:107]
	v_lshl_add_u64 v[42:43], v[32:33], 0, v[128:129]
	v_add_u32_e32 v32, s10, v111
	v_ashrrev_i32_e32 v33, 31, v32
	s_waitcnt lgkmcnt(0)
	global_store_dwordx4 v[42:43], v[36:39], off sc1
	v_cvt_pk_bf16_f32 v24, v24, v25
	v_cvt_pk_bf16_f32 v25, v26, v27
	v_lshlrev_b64 v[36:37], 11, v[32:33]
	ds_read_b128 v[32:35], v116
	v_lshl_add_u64 v[36:37], s[66:67], 0, v[36:37]
	v_lshl_add_u64 v[36:37], v[36:37], 0, v[106:107]
	v_lshl_add_u64 v[44:45], v[36:37], 0, v[128:129]
	ds_read_b128 v[36:39], v118
	s_waitcnt lgkmcnt(1)
	global_store_dwordx4 v[44:45], v[32:35], off sc1
	v_cvt_pk_bf16_f32 v20, v20, v21
	v_cvt_pk_bf16_f32 v21, v22, v23
	v_add_u32_e32 v32, s10, v117
	v_ashrrev_i32_e32 v33, 31, v32
	v_lshlrev_b64 v[32:33], 11, v[32:33]
	v_lshl_add_u64 v[32:33], s[66:67], 0, v[32:33]
	v_lshl_add_u64 v[32:33], v[32:33], 0, v[106:107]
	v_lshl_add_u64 v[32:33], v[32:33], 0, v[128:129]
	v_cvt_pk_bf16_f32 v16, v16, v17
	v_cvt_pk_bf16_f32 v17, v18, v19
	s_waitcnt lgkmcnt(0)
	global_store_dwordx4 v[32:33], v[36:39], off sc1
	s_barrier
	ds_write2_b64 v130, v[28:29], v[24:25] offset1:4
	ds_write2_b64 v120, v[20:21], v[16:17] offset0:32 offset1:36
	v_cvt_pk_bf16_f32 v12, v12, v13
	v_cvt_pk_bf16_f32 v13, v14, v15
	v_cvt_pk_bf16_f32 v8, v8, v9
	v_cvt_pk_bf16_f32 v9, v10, v11
	v_cvt_pk_bf16_f32 v4, v4, v5
	v_cvt_pk_bf16_f32 v5, v6, v7
	v_cvt_pk_bf16_f32 v0, v0, v1
	v_cvt_pk_bf16_f32 v1, v2, v3
	ds_write2_b64 v121, v[12:13], v[8:9] offset0:64 offset1:68
	ds_write2_b64 v122, v[4:5], v[0:1] offset0:96 offset1:100
	s_waitcnt lgkmcnt(0)
	s_barrier
	ds_read_b128 v[0:3], v96
	ds_read_b128 v[4:7], v110
	ds_read_b128 v[8:11], v116
	ds_read_b128 v[12:15], v118
	s_add_i32 s27, s27, s50
	s_cmpk_lt_i32 s27, 0x400
	s_waitcnt lgkmcnt(3)
	global_store_dwordx4 v[40:41], v[0:3], off offset:256 sc1
	s_waitcnt lgkmcnt(2)
	global_store_dwordx4 v[42:43], v[4:7], off offset:256 sc1
	s_waitcnt lgkmcnt(1)
	global_store_dwordx4 v[44:45], v[8:11], off offset:256 sc1
	s_waitcnt lgkmcnt(0)
	global_store_dwordx4 v[32:33], v[12:15], off offset:256 sc1
	s_barrier
	s_cbranch_scc0 .LBB0_1249

.LBB0_1274:
	s_or_b64 exec, exec, s[12:13]
	v_mov_b32_e32 v133, v148
	v_max_f32_e32 v120, v120, v120
	v_and_b32_e32 v131, 15, v133
	v_lshrrev_b32_e32 v128, 2, v133
	v_max_f32_e32 v121, v121, v121
	v_and_or_b32 v136, v128, s24, v131
	v_lshrrev_b32_e32 v128, 1, v133
	v_max_f32_e32 v120, 0, v120
	v_max_f32_e32 v121, 0, v121
	v_and_b32_e32 v128, 24, v128
	v_max_f32_e32 v124, v124, v124
	v_max_f32_e32 v125, v125, v125
	v_max_f32_e32 v126, v126, v126
	v_max_f32_e32 v127, v127, v127
	v_pk_mul_f32 v[134:135], v[120:121], v[120:121]
	v_max_f32_e32 v120, v122, v122
	v_max_f32_e32 v121, v123, v123
	v_max_f32_e32 v116, v116, v116
	v_max_f32_e32 v117, v117, v117
	v_max_f32_e32 v118, v118, v118
	v_max_f32_e32 v119, v119, v119
	v_max_f32_e32 v112, v112, v112
	v_max_f32_e32 v113, v113, v113
	v_max_f32_e32 v114, v114, v114
	v_max_f32_e32 v115, v115, v115
	v_and_or_b32 v128, v133, s25, v128
	v_lshlrev_b32_e32 v130, 3, v133
	v_max_f32_e32 v124, 0, v124
	v_max_f32_e32 v125, 0, v125
	v_max_f32_e32 v126, 0, v126
	v_max_f32_e32 v127, 0, v127
	v_max_f32_e32 v120, 0, v120
	v_max_f32_e32 v121, 0, v121
	v_max_f32_e32 v116, 0, v116
	v_max_f32_e32 v117, 0, v117
	v_max_f32_e32 v118, 0, v118
	v_max_f32_e32 v119, 0, v119
	v_max_f32_e32 v112, 0, v112
	v_max_f32_e32 v113, 0, v113
	v_max_f32_e32 v114, 0, v114
	v_max_f32_e32 v115, 0, v115
	v_max_f32_e32 v104, v104, v104
	v_max_f32_e32 v105, v105, v105
	v_max_f32_e32 v106, v106, v106
	v_max_f32_e32 v107, v107, v107
	v_max_f32_e32 v100, v100, v100
	v_max_f32_e32 v101, v101, v101
	v_max_f32_e32 v102, v102, v102
	v_max_f32_e32 v103, v103, v103
	v_max_f32_e32 v96, v96, v96
	v_max_f32_e32 v97, v97, v97
	v_max_f32_e32 v98, v98, v98
	v_max_f32_e32 v99, v99, v99
	v_and_or_b32 v130, v130, 64, s10
	v_pk_mul_f32 v[124:125], v[124:125], v[124:125]
	v_pk_mul_f32 v[126:127], v[126:127], v[126:127]
	v_pk_mul_f32 v[122:123], v[120:121], v[120:121]
	v_mad_u64_u32 v[120:121], s[10:11], v136, s26, v[128:129]
	v_pk_mul_f32 v[116:117], v[116:117], v[116:117]
	v_pk_mul_f32 v[118:119], v[118:119], v[118:119]
	v_pk_mul_f32 v[112:113], v[112:113], v[112:113]
	v_pk_mul_f32 v[114:115], v[114:115], v[114:115]
	v_max_f32_e32 v104, 0, v104
	v_max_f32_e32 v105, 0, v105
	v_max_f32_e32 v106, 0, v106
	v_max_f32_e32 v107, 0, v107
	v_max_f32_e32 v100, 0, v100
	v_max_f32_e32 v101, 0, v101
	v_max_f32_e32 v102, 0, v102
	v_max_f32_e32 v103, 0, v103
	v_max_f32_e32 v96, 0, v96
	v_max_f32_e32 v97, 0, v97
	v_max_f32_e32 v98, 0, v98
	v_max_f32_e32 v99, 0, v99
	v_cvt_pk_bf16_f32 v124, v124, v125
	v_cvt_pk_bf16_f32 v125, v126, v127
	v_cvt_pk_bf16_f32 v126, v134, v135
	v_cvt_pk_bf16_f32 v127, v122, v123
	v_cvt_pk_bf16_f32 v116, v116, v117
	v_cvt_pk_bf16_f32 v117, v118, v119
	v_cvt_pk_bf16_f32 v118, v112, v113
	v_cvt_pk_bf16_f32 v119, v114, v115
	v_add_u32_e32 v112, 0x1000, v120
	v_pk_mul_f32 v[104:105], v[104:105], v[104:105]
	v_pk_mul_f32 v[106:107], v[106:107], v[106:107]
	v_pk_mul_f32 v[100:101], v[100:101], v[100:101]
	v_pk_mul_f32 v[102:103], v[102:103], v[102:103]
	v_pk_mul_f32 v[96:97], v[96:97], v[96:97]
	v_pk_mul_f32 v[98:99], v[98:99], v[98:99]
	ds_write2_b64 v120, v[124:125], v[126:127] offset1:4
	ds_write2_b64 v112, v[116:117], v[118:119] offset0:32 offset1:36
	v_max_f32_e32 v108, v108, v108
	v_max_f32_e32 v109, v109, v109
	v_max_f32_e32 v110, v110, v110
	v_max_f32_e32 v111, v111, v111
	v_cvt_pk_bf16_f32 v104, v104, v105
	v_cvt_pk_bf16_f32 v105, v106, v107
	v_cvt_pk_bf16_f32 v100, v100, v101
	v_cvt_pk_bf16_f32 v101, v102, v103
	v_cvt_pk_bf16_f32 v96, v96, v97
	v_cvt_pk_bf16_f32 v97, v98, v99
	v_add_u32_e32 v107, 0x3000, v120
	v_ashrrev_i32_e32 v113, 4, v133
	v_max_f32_e32 v108, 0, v108
	v_max_f32_e32 v109, 0, v109
	v_max_f32_e32 v110, 0, v110
	v_max_f32_e32 v111, 0, v111
	ds_write2_b64 v107, v[100:101], v[96:97] offset0:96 offset1:100
	v_add_u32_e32 v96, s8, v113
	v_pk_mul_f32 v[108:109], v[108:109], v[108:109]
	v_pk_mul_f32 v[110:111], v[110:111], v[110:111]
	v_ashrrev_i32_e32 v97, 31, v96
	v_lshlrev_b32_e32 v132, 4, v131
	v_cvt_pk_bf16_f32 v108, v108, v109
	v_cvt_pk_bf16_f32 v109, v110, v111
	v_add_u32_e32 v106, 0x2000, v120
	v_ashrrev_i32_e32 v131, 31, v130
	v_lshlrev_b64 v[96:97], 13, v[96:97]
	ds_write2_b64 v106, v[108:109], v[104:105] offset0:64 offset1:68
	v_lshl_add_u64 v[96:97], s[62:63], 0, v[96:97]
	v_lshlrev_b64 v[104:105], 1, v[130:131]
	v_lshlrev_b32_e32 v98, 4, v133
	v_lshl_add_u64 v[96:97], v[96:97], 0, v[104:105]
	v_and_b32_e32 v128, 0x70, v98
	v_lshl_add_u64 v[118:119], v[96:97], 0, v[128:129]
	v_mad_u64_u32 v[96:97], s[10:11], v113, s26, v[132:133]
	s_waitcnt vmcnt(0) lgkmcnt(0)
	s_barrier
	ds_read_b128 v[100:103], v96
	v_add_u32_e32 v97, 0x200, v133
	v_ashrrev_i32_e32 v97, 4, v97
	v_mad_u64_u32 v[98:99], s[10:11], v97, s26, v[132:133]
	ds_read_b128 v[108:111], v98
	s_waitcnt lgkmcnt(1)
	global_store_dwordx4 v[118:119], v[100:103], off sc1
	v_add_u32_e32 v99, 0x400, v133
	v_ashrrev_i32_e32 v99, 4, v99
	v_add_u32_e32 v100, s8, v97
	v_ashrrev_i32_e32 v101, 31, v100
	v_lshlrev_b64 v[100:101], 13, v[100:101]
	v_lshl_add_u64 v[100:101], s[62:63], 0, v[100:101]
	v_lshl_add_u64 v[100:101], v[100:101], 0, v[104:105]
	v_lshl_add_u64 v[122:123], v[100:101], 0, v[128:129]
	v_add_u32_e32 v100, s8, v99
	v_ashrrev_i32_e32 v101, 31, v100
	v_lshlrev_b64 v[100:101], 13, v[100:101]
	v_lshl_add_u64 v[100:101], s[62:63], 0, v[100:101]
	v_lshl_add_u64 v[100:101], v[100:101], 0, v[104:105]
	v_lshl_add_u64 v[124:125], v[100:101], 0, v[128:129]
	v_mad_u64_u32 v[100:101], s[10:11], v99, s26, v[132:133]
	s_waitcnt lgkmcnt(0)
	global_store_dwordx4 v[122:123], v[108:111], off sc1
	ds_read_b128 v[108:111], v100
	v_add_u32_e32 v101, 0x600, v133
	v_ashrrev_i32_e32 v101, 4, v101
	v_mad_u64_u32 v[102:103], s[10:11], v101, s26, v[132:133]
	ds_read_b128 v[114:117], v102
	s_waitcnt lgkmcnt(1)
	global_store_dwordx4 v[124:125], v[108:111], off sc1
	v_max_f32_e32 v92, v92, v92
	v_max_f32_e32 v93, v93, v93
	v_add_u32_e32 v108, s8, v101
	v_ashrrev_i32_e32 v109, 31, v108
	v_lshlrev_b64 v[108:109], 13, v[108:109]
	v_max_f32_e32 v94, v94, v94
	v_max_f32_e32 v95, v95, v95
	v_max_f32_e32 v88, v88, v88
	v_max_f32_e32 v89, v89, v89
	v_max_f32_e32 v90, v90, v90
	v_max_f32_e32 v91, v91, v91
	v_max_f32_e32 v84, v84, v84
	v_max_f32_e32 v85, v85, v85
	v_max_f32_e32 v86, v86, v86
	v_max_f32_e32 v87, v87, v87
	v_max_f32_e32 v80, v80, v80
	v_max_f32_e32 v81, v81, v81
	v_max_f32_e32 v82, v82, v82
	v_max_f32_e32 v83, v83, v83
	v_lshl_add_u64 v[108:109], s[62:63], 0, v[108:109]
	v_max_f32_e32 v92, 0, v92
	v_max_f32_e32 v93, 0, v93
	v_max_f32_e32 v94, 0, v94
	v_max_f32_e32 v95, 0, v95
	v_max_f32_e32 v88, 0, v88
	v_max_f32_e32 v89, 0, v89
	v_max_f32_e32 v90, 0, v90
	v_max_f32_e32 v91, 0, v91
	v_max_f32_e32 v84, 0, v84
	v_max_f32_e32 v85, 0, v85
	v_max_f32_e32 v86, 0, v86
	v_max_f32_e32 v87, 0, v87
	v_max_f32_e32 v80, 0, v80
	v_max_f32_e32 v81, 0, v81
	v_max_f32_e32 v82, 0, v82
	v_max_f32_e32 v83, 0, v83
	v_max_f32_e32 v76, v76, v76
	v_max_f32_e32 v77, v77, v77
	v_max_f32_e32 v78, v78, v78
	v_max_f32_e32 v79, v79, v79
	v_max_f32_e32 v72, v72, v72
	v_max_f32_e32 v73, v73, v73
	v_max_f32_e32 v74, v74, v74
	v_max_f32_e32 v75, v75, v75
	v_max_f32_e32 v68, v68, v68
	v_max_f32_e32 v69, v69, v69
	v_max_f32_e32 v70, v70, v70
	v_max_f32_e32 v71, v71, v71
	v_max_f32_e32 v64, v64, v64
	v_max_f32_e32 v65, v65, v65
	v_max_f32_e32 v66, v66, v66
	v_max_f32_e32 v67, v67, v67
	v_lshl_add_u64 v[108:109], v[108:109], 0, v[104:105]
	v_pk_mul_f32 v[92:93], v[92:93], v[92:93]
	v_pk_mul_f32 v[94:95], v[94:95], v[94:95]
	v_pk_mul_f32 v[88:89], v[88:89], v[88:89]
	v_pk_mul_f32 v[90:91], v[90:91], v[90:91]
	v_pk_mul_f32 v[84:85], v[84:85], v[84:85]
	v_pk_mul_f32 v[86:87], v[86:87], v[86:87]
	v_pk_mul_f32 v[80:81], v[80:81], v[80:81]
	v_pk_mul_f32 v[82:83], v[82:83], v[82:83]
	v_max_f32_e32 v76, 0, v76
	v_max_f32_e32 v77, 0, v77
	v_max_f32_e32 v78, 0, v78
	v_max_f32_e32 v79, 0, v79
	v_max_f32_e32 v72, 0, v72
	v_max_f32_e32 v73, 0, v73
	v_max_f32_e32 v74, 0, v74
	v_max_f32_e32 v75, 0, v75
	v_max_f32_e32 v68, 0, v68
	v_max_f32_e32 v69, 0, v69
	v_max_f32_e32 v70, 0, v70
	v_max_f32_e32 v71, 0, v71
	v_max_f32_e32 v64, 0, v64
	v_max_f32_e32 v65, 0, v65
	v_max_f32_e32 v66, 0, v66
	v_max_f32_e32 v67, 0, v67
	v_lshl_add_u64 v[108:109], v[108:109], 0, v[128:129]
	v_cvt_pk_bf16_f32 v92, v92, v93
	v_cvt_pk_bf16_f32 v93, v94, v95
	v_cvt_pk_bf16_f32 v88, v88, v89
	v_cvt_pk_bf16_f32 v89, v90, v91
	v_cvt_pk_bf16_f32 v84, v84, v85
	v_cvt_pk_bf16_f32 v85, v86, v87
	v_cvt_pk_bf16_f32 v80, v80, v81
	v_cvt_pk_bf16_f32 v81, v82, v83
	v_pk_mul_f32 v[76:77], v[76:77], v[76:77]
	v_pk_mul_f32 v[78:79], v[78:79], v[78:79]
	v_pk_mul_f32 v[72:73], v[72:73], v[72:73]
	v_pk_mul_f32 v[74:75], v[74:75], v[74:75]
	v_pk_mul_f32 v[68:69], v[68:69], v[68:69]
	v_pk_mul_f32 v[70:71], v[70:71], v[70:71]
	v_pk_mul_f32 v[64:65], v[64:65], v[64:65]
	v_pk_mul_f32 v[66:67], v[66:67], v[66:67]
	s_waitcnt lgkmcnt(0)
	global_store_dwordx4 v[108:109], v[114:117], off sc1
	s_barrier
	ds_write2_b64 v120, v[92:93], v[88:89] offset1:4
	ds_write2_b64 v112, v[84:85], v[80:81] offset0:32 offset1:36
	v_cvt_pk_bf16_f32 v76, v76, v77
	v_cvt_pk_bf16_f32 v77, v78, v79
	v_cvt_pk_bf16_f32 v72, v72, v73
	v_cvt_pk_bf16_f32 v73, v74, v75
	v_cvt_pk_bf16_f32 v68, v68, v69
	v_cvt_pk_bf16_f32 v69, v70, v71
	v_cvt_pk_bf16_f32 v64, v64, v65
	v_cvt_pk_bf16_f32 v65, v66, v67
	ds_write2_b64 v106, v[76:77], v[72:73] offset0:64 offset1:68
	ds_write2_b64 v107, v[68:69], v[64:65] offset0:96 offset1:100
	s_waitcnt lgkmcnt(0)
	s_barrier
	ds_read_b128 v[64:67], v96
	ds_read_b128 v[68:71], v98
	ds_read_b128 v[72:75], v100
	ds_read_b128 v[76:79], v102
	v_max_f32_e32 v60, v60, v60
	v_max_f32_e32 v61, v61, v61
	v_max_f32_e32 v62, v62, v62
	v_max_f32_e32 v63, v63, v63
	v_max_f32_e32 v56, v56, v56
	v_max_f32_e32 v57, v57, v57
	v_max_f32_e32 v58, v58, v58
	v_max_f32_e32 v59, v59, v59
	v_max_f32_e32 v52, v52, v52
	v_max_f32_e32 v53, v53, v53
	v_max_f32_e32 v54, v54, v54
	v_max_f32_e32 v55, v55, v55
	v_max_f32_e32 v48, v48, v48
	v_max_f32_e32 v49, v49, v49
	v_max_f32_e32 v50, v50, v50
	v_max_f32_e32 v51, v51, v51
	v_max_f32_e32 v60, 0, v60
	v_max_f32_e32 v61, 0, v61
	v_max_f32_e32 v62, 0, v62
	v_max_f32_e32 v63, 0, v63
	v_max_f32_e32 v56, 0, v56
	v_max_f32_e32 v57, 0, v57
	v_max_f32_e32 v58, 0, v58
	v_max_f32_e32 v59, 0, v59
	v_max_f32_e32 v52, 0, v52
	v_max_f32_e32 v53, 0, v53
	v_max_f32_e32 v54, 0, v54
	v_max_f32_e32 v55, 0, v55
	v_max_f32_e32 v48, 0, v48
	v_max_f32_e32 v49, 0, v49
	v_max_f32_e32 v50, 0, v50
	v_max_f32_e32 v51, 0, v51
	v_max_f32_e32 v36, v36, v36
	v_max_f32_e32 v37, v37, v37
	v_max_f32_e32 v38, v38, v38
	v_max_f32_e32 v39, v39, v39
	v_max_f32_e32 v32, v32, v32
	v_max_f32_e32 v33, v33, v33
	v_max_f32_e32 v34, v34, v34
	v_max_f32_e32 v35, v35, v35
	v_pk_mul_f32 v[60:61], v[60:61], v[60:61]
	v_pk_mul_f32 v[62:63], v[62:63], v[62:63]
	v_pk_mul_f32 v[56:57], v[56:57], v[56:57]
	v_pk_mul_f32 v[58:59], v[58:59], v[58:59]
	v_pk_mul_f32 v[52:53], v[52:53], v[52:53]
	v_pk_mul_f32 v[54:55], v[54:55], v[54:55]
	v_pk_mul_f32 v[48:49], v[48:49], v[48:49]
	v_pk_mul_f32 v[50:51], v[50:51], v[50:51]
	v_max_f32_e32 v44, v44, v44
	v_max_f32_e32 v45, v45, v45
	v_max_f32_e32 v46, v46, v46
	v_max_f32_e32 v47, v47, v47
	v_max_f32_e32 v40, v40, v40
	v_max_f32_e32 v41, v41, v41
	v_max_f32_e32 v42, v42, v42
	v_max_f32_e32 v43, v43, v43
	v_max_f32_e32 v36, 0, v36
	v_max_f32_e32 v37, 0, v37
	v_max_f32_e32 v38, 0, v38
	v_max_f32_e32 v39, 0, v39
	v_max_f32_e32 v32, 0, v32
	v_max_f32_e32 v33, 0, v33
	v_max_f32_e32 v34, 0, v34
	v_max_f32_e32 v35, 0, v35
	v_cvt_pk_bf16_f32 v60, v60, v61
	v_cvt_pk_bf16_f32 v61, v62, v63
	v_cvt_pk_bf16_f32 v56, v56, v57
	v_cvt_pk_bf16_f32 v57, v58, v59
	v_cvt_pk_bf16_f32 v52, v52, v53
	v_cvt_pk_bf16_f32 v53, v54, v55
	v_cvt_pk_bf16_f32 v48, v48, v49
	v_cvt_pk_bf16_f32 v49, v50, v51
	v_max_f32_e32 v44, 0, v44
	v_max_f32_e32 v45, 0, v45
	v_max_f32_e32 v46, 0, v46
	v_max_f32_e32 v47, 0, v47
	v_max_f32_e32 v40, 0, v40
	v_max_f32_e32 v41, 0, v41
	v_max_f32_e32 v42, 0, v42
	v_max_f32_e32 v43, 0, v43
	v_pk_mul_f32 v[36:37], v[36:37], v[36:37]
	v_pk_mul_f32 v[38:39], v[38:39], v[38:39]
	v_pk_mul_f32 v[32:33], v[32:33], v[32:33]
	v_pk_mul_f32 v[34:35], v[34:35], v[34:35]
	s_waitcnt lgkmcnt(3)
	global_store_dwordx4 v[118:119], v[64:67], off offset:256 sc1
	s_waitcnt lgkmcnt(2)
	global_store_dwordx4 v[122:123], v[68:71], off offset:256 sc1
	s_waitcnt lgkmcnt(1)
	global_store_dwordx4 v[124:125], v[72:75], off offset:256 sc1
	s_waitcnt lgkmcnt(0)
	global_store_dwordx4 v[108:109], v[76:79], off offset:256 sc1
	s_barrier
	s_bitset1_b32 s8, 7
	ds_write2_b64 v120, v[60:61], v[56:57] offset1:4
	ds_write2_b64 v112, v[52:53], v[48:49] offset0:32 offset1:36
	v_pk_mul_f32 v[44:45], v[44:45], v[44:45]
	v_pk_mul_f32 v[46:47], v[46:47], v[46:47]
	v_pk_mul_f32 v[40:41], v[40:41], v[40:41]
	v_pk_mul_f32 v[42:43], v[42:43], v[42:43]
	v_cvt_pk_bf16_f32 v36, v36, v37
	v_cvt_pk_bf16_f32 v37, v38, v39
	v_cvt_pk_bf16_f32 v32, v32, v33
	v_cvt_pk_bf16_f32 v33, v34, v35
	v_cvt_pk_bf16_f32 v44, v44, v45
	v_cvt_pk_bf16_f32 v45, v46, v47
	v_cvt_pk_bf16_f32 v40, v40, v41
	v_cvt_pk_bf16_f32 v41, v42, v43
	ds_write2_b64 v107, v[36:37], v[32:33] offset0:96 offset1:100
	v_add_u32_e32 v32, s8, v113
	ds_write2_b64 v106, v[44:45], v[40:41] offset0:64 offset1:68
	v_ashrrev_i32_e32 v33, 31, v32
	s_waitcnt lgkmcnt(0)
	s_barrier
	v_lshlrev_b64 v[36:37], 13, v[32:33]
	ds_read_b128 v[32:35], v96
	v_lshl_add_u64 v[36:37], s[62:63], 0, v[36:37]
	v_lshl_add_u64 v[36:37], v[36:37], 0, v[104:105]
	v_lshl_add_u64 v[40:41], v[36:37], 0, v[128:129]
	ds_read_b128 v[36:39], v98
	s_waitcnt lgkmcnt(1)
	global_store_dwordx4 v[40:41], v[32:35], off sc1
	v_max_f32_e32 v28, v28, v28
	v_max_f32_e32 v29, v29, v29
	v_add_u32_e32 v32, s8, v97
	v_ashrrev_i32_e32 v33, 31, v32
	v_lshlrev_b64 v[32:33], 13, v[32:33]
	v_lshl_add_u64 v[32:33], s[62:63], 0, v[32:33]
	v_lshl_add_u64 v[32:33], v[32:33], 0, v[104:105]
	v_lshl_add_u64 v[42:43], v[32:33], 0, v[128:129]
	v_add_u32_e32 v32, s8, v99
	v_ashrrev_i32_e32 v33, 31, v32
	s_waitcnt lgkmcnt(0)
	global_store_dwordx4 v[42:43], v[36:39], off sc1
	v_max_f32_e32 v30, v30, v30
	v_max_f32_e32 v31, v31, v31
	v_lshlrev_b64 v[36:37], 13, v[32:33]
	ds_read_b128 v[32:35], v100
	v_lshl_add_u64 v[36:37], s[62:63], 0, v[36:37]
	v_lshl_add_u64 v[36:37], v[36:37], 0, v[104:105]
	v_lshl_add_u64 v[44:45], v[36:37], 0, v[128:129]
	ds_read_b128 v[36:39], v102
	s_waitcnt lgkmcnt(1)
	global_store_dwordx4 v[44:45], v[32:35], off sc1
	v_max_f32_e32 v24, v24, v24
	v_max_f32_e32 v25, v25, v25
	v_add_u32_e32 v32, s8, v101
	v_ashrrev_i32_e32 v33, 31, v32
	v_lshlrev_b64 v[32:33], 13, v[32:33]
	v_max_f32_e32 v26, v26, v26
	v_max_f32_e32 v27, v27, v27
	v_max_f32_e32 v20, v20, v20
	v_max_f32_e32 v21, v21, v21
	v_max_f32_e32 v22, v22, v22
	v_max_f32_e32 v23, v23, v23
	v_max_f32_e32 v16, v16, v16
	v_max_f32_e32 v17, v17, v17
	v_max_f32_e32 v18, v18, v18
	v_max_f32_e32 v19, v19, v19
	v_lshl_add_u64 v[32:33], s[62:63], 0, v[32:33]
	v_max_f32_e32 v28, 0, v28
	v_max_f32_e32 v29, 0, v29
	v_max_f32_e32 v30, 0, v30
	v_max_f32_e32 v31, 0, v31
	v_max_f32_e32 v24, 0, v24
	v_max_f32_e32 v25, 0, v25
	v_max_f32_e32 v26, 0, v26
	v_max_f32_e32 v27, 0, v27
	v_max_f32_e32 v20, 0, v20
	v_max_f32_e32 v21, 0, v21
	v_max_f32_e32 v22, 0, v22
	v_max_f32_e32 v23, 0, v23
	v_max_f32_e32 v16, 0, v16
	v_max_f32_e32 v17, 0, v17
	v_max_f32_e32 v18, 0, v18
	v_max_f32_e32 v19, 0, v19
	v_max_f32_e32 v12, v12, v12
	v_max_f32_e32 v13, v13, v13
	v_max_f32_e32 v14, v14, v14
	v_max_f32_e32 v15, v15, v15
	v_max_f32_e32 v8, v8, v8
	v_max_f32_e32 v9, v9, v9
	v_max_f32_e32 v10, v10, v10
	v_max_f32_e32 v11, v11, v11
	v_max_f32_e32 v4, v4, v4
	v_max_f32_e32 v5, v5, v5
	v_max_f32_e32 v6, v6, v6
	v_max_f32_e32 v7, v7, v7
	v_max_f32_e32 v0, v0, v0
	v_max_f32_e32 v1, v1, v1
	v_max_f32_e32 v2, v2, v2
	v_max_f32_e32 v3, v3, v3
	v_lshl_add_u64 v[32:33], v[32:33], 0, v[104:105]
	v_pk_mul_f32 v[28:29], v[28:29], v[28:29]
	v_pk_mul_f32 v[30:31], v[30:31], v[30:31]
	v_pk_mul_f32 v[24:25], v[24:25], v[24:25]
	v_pk_mul_f32 v[26:27], v[26:27], v[26:27]
	v_pk_mul_f32 v[20:21], v[20:21], v[20:21]
	v_pk_mul_f32 v[22:23], v[22:23], v[22:23]
	v_pk_mul_f32 v[16:17], v[16:17], v[16:17]
	v_pk_mul_f32 v[18:19], v[18:19], v[18:19]
	v_max_f32_e32 v12, 0, v12
	v_max_f32_e32 v13, 0, v13
	v_max_f32_e32 v14, 0, v14
	v_max_f32_e32 v15, 0, v15
	v_max_f32_e32 v8, 0, v8
	v_max_f32_e32 v9, 0, v9
	v_max_f32_e32 v10, 0, v10
	v_max_f32_e32 v11, 0, v11
	v_max_f32_e32 v4, 0, v4
	v_max_f32_e32 v5, 0, v5
	v_max_f32_e32 v6, 0, v6
	v_max_f32_e32 v7, 0, v7
	v_max_f32_e32 v0, 0, v0
	v_max_f32_e32 v1, 0, v1
	v_max_f32_e32 v2, 0, v2
	v_max_f32_e32 v3, 0, v3
	v_lshl_add_u64 v[32:33], v[32:33], 0, v[128:129]
	v_cvt_pk_bf16_f32 v28, v28, v29
	v_cvt_pk_bf16_f32 v29, v30, v31
	v_cvt_pk_bf16_f32 v24, v24, v25
	v_cvt_pk_bf16_f32 v25, v26, v27
	v_cvt_pk_bf16_f32 v20, v20, v21
	v_cvt_pk_bf16_f32 v21, v22, v23
	v_cvt_pk_bf16_f32 v16, v16, v17
	v_cvt_pk_bf16_f32 v17, v18, v19
	v_pk_mul_f32 v[12:13], v[12:13], v[12:13]
	v_pk_mul_f32 v[14:15], v[14:15], v[14:15]
	v_pk_mul_f32 v[8:9], v[8:9], v[8:9]
	v_pk_mul_f32 v[10:11], v[10:11], v[10:11]
	v_pk_mul_f32 v[4:5], v[4:5], v[4:5]
	v_pk_mul_f32 v[6:7], v[6:7], v[6:7]
	v_pk_mul_f32 v[0:1], v[0:1], v[0:1]
	v_pk_mul_f32 v[2:3], v[2:3], v[2:3]
	s_waitcnt lgkmcnt(0)
	global_store_dwordx4 v[32:33], v[36:39], off sc1
	s_barrier
	ds_write2_b64 v120, v[28:29], v[24:25] offset1:4
	ds_write2_b64 v112, v[20:21], v[16:17] offset0:32 offset1:36
	v_cvt_pk_bf16_f32 v12, v12, v13
	v_cvt_pk_bf16_f32 v13, v14, v15
	v_cvt_pk_bf16_f32 v8, v8, v9
	v_cvt_pk_bf16_f32 v9, v10, v11
	v_cvt_pk_bf16_f32 v4, v4, v5
	v_cvt_pk_bf16_f32 v5, v6, v7
	v_cvt_pk_bf16_f32 v0, v0, v1
	v_cvt_pk_bf16_f32 v1, v2, v3
	ds_write2_b64 v106, v[12:13], v[8:9] offset0:64 offset1:68
	ds_write2_b64 v107, v[4:5], v[0:1] offset0:96 offset1:100
	s_waitcnt lgkmcnt(0)
	s_barrier
	ds_read_b128 v[0:3], v96
	ds_read_b128 v[4:7], v98
	ds_read_b128 v[8:11], v100
	ds_read_b128 v[12:15], v102
	s_add_i32 s28, s28, s50
	s_add_i32 s27, s27, s50
	s_cmpk_lt_i32 s28, 0x1000
	s_waitcnt lgkmcnt(3)
	global_store_dwordx4 v[40:41], v[0:3], off offset:256 sc1
	s_waitcnt lgkmcnt(2)
	global_store_dwordx4 v[42:43], v[4:7], off offset:256 sc1
	s_waitcnt lgkmcnt(1)
	global_store_dwordx4 v[44:45], v[8:11], off offset:256 sc1
	s_waitcnt lgkmcnt(0)
	global_store_dwordx4 v[32:33], v[12:15], off offset:256 sc1
	s_barrier
	s_cbranch_scc0 .LBB0_1281

.LBB0_1289:
	s_or_b64 exec, exec, s[10:11]
	v_mov_b32_e32 v135, v148
	v_cvt_pk_bf16_f32 v124, v124, v125
	v_and_b32_e32 v130, 15, v135
	v_lshrrev_b32_e32 v128, 2, v135
	v_and_or_b32 v131, v128, s20, v130
	v_lshrrev_b32_e32 v128, 1, v135
	v_and_b32_e32 v128, 24, v128
	v_and_or_b32 v128, v135, s21, v128
	v_lshlrev_b32_e32 v132, 3, v135
	v_and_or_b32 v132, v132, 64, s8
	v_lshlrev_b32_e32 v134, 4, v130
	v_mad_u64_u32 v[130:131], s[8:9], v131, s22, v[128:129]
	v_cvt_pk_bf16_f32 v125, v126, v127
	v_cvt_pk_bf16_f32 v120, v120, v121
	v_cvt_pk_bf16_f32 v121, v122, v123
	ds_write2_b64 v130, v[124:125], v[120:121] offset1:4
	v_cvt_pk_bf16_f32 v116, v116, v117
	v_cvt_pk_bf16_f32 v117, v118, v119
	v_cvt_pk_bf16_f32 v112, v112, v113
	v_cvt_pk_bf16_f32 v113, v114, v115
	v_add_u32_e32 v120, 0x1000, v130
	ds_write2_b64 v120, v[116:117], v[112:113] offset0:32 offset1:36
	v_cvt_pk_bf16_f32 v100, v100, v101
	v_cvt_pk_bf16_f32 v101, v102, v103
	v_cvt_pk_bf16_f32 v96, v96, v97
	v_cvt_pk_bf16_f32 v97, v98, v99
	v_add_u32_e32 v122, 0x3000, v130
	v_ashrrev_i32_e32 v123, 4, v135
	ds_write2_b64 v122, v[100:101], v[96:97] offset0:96 offset1:100
	v_add_u32_e32 v96, s6, v123
	v_ashrrev_i32_e32 v97, 31, v96
	v_ashrrev_i32_e32 v133, 31, v132
	v_lshlrev_b64 v[96:97], 11, v[96:97]
	v_cvt_pk_bf16_f32 v104, v104, v105
	v_cvt_pk_bf16_f32 v105, v106, v107
	v_lshl_add_u64 v[96:97], s[56:57], 0, v[96:97]
	v_lshlrev_b64 v[106:107], 1, v[132:133]
	v_lshlrev_b32_e32 v98, 4, v135
	v_cvt_pk_bf16_f32 v108, v108, v109
	v_cvt_pk_bf16_f32 v109, v110, v111
	v_add_u32_e32 v121, 0x2000, v130
	v_lshl_add_u64 v[96:97], v[96:97], 0, v[106:107]
	v_and_b32_e32 v128, 0x70, v98
	ds_write2_b64 v121, v[108:109], v[104:105] offset0:64 offset1:68
	v_lshl_add_u64 v[108:109], v[96:97], 0, v[128:129]
	v_mad_u64_u32 v[96:97], s[8:9], v123, s22, v[134:135]
	s_waitcnt vmcnt(0) lgkmcnt(0)
	s_barrier
	ds_read_b128 v[98:101], v96
	v_add_u32_e32 v97, 0x200, v135
	v_ashrrev_i32_e32 v97, 4, v97
	v_mad_u64_u32 v[110:111], s[8:9], v97, s22, v[134:135]
	ds_read_b128 v[102:105], v110
	s_waitcnt lgkmcnt(1)
	global_store_dwordx4 v[108:109], v[98:101], off sc1
	v_cvt_pk_bf16_f32 v92, v92, v93
	v_cvt_pk_bf16_f32 v93, v94, v95
	v_add_u32_e32 v98, s6, v97
	v_ashrrev_i32_e32 v99, 31, v98
	v_lshlrev_b64 v[98:99], 11, v[98:99]
	v_lshl_add_u64 v[98:99], s[56:57], 0, v[98:99]
	v_lshl_add_u64 v[98:99], v[98:99], 0, v[106:107]
	v_lshl_add_u64 v[112:113], v[98:99], 0, v[128:129]
	v_add_u32_e32 v98, 0x400, v135
	v_ashrrev_i32_e32 v111, 4, v98
	v_add_u32_e32 v98, s6, v111
	v_ashrrev_i32_e32 v99, 31, v98
	v_lshlrev_b64 v[98:99], 11, v[98:99]
	v_lshl_add_u64 v[98:99], s[56:57], 0, v[98:99]
	v_lshl_add_u64 v[98:99], v[98:99], 0, v[106:107]
	v_mad_u64_u32 v[116:117], s[8:9], v111, s22, v[134:135]
	v_lshl_add_u64 v[114:115], v[98:99], 0, v[128:129]
	ds_read_b128 v[98:101], v116
	s_waitcnt lgkmcnt(1)
	global_store_dwordx4 v[112:113], v[102:105], off sc1
	v_cvt_pk_bf16_f32 v88, v88, v89
	v_cvt_pk_bf16_f32 v89, v90, v91
	v_add_u32_e32 v102, 0x600, v135
	v_ashrrev_i32_e32 v117, 4, v102
	v_mad_u64_u32 v[118:119], s[8:9], v117, s22, v[134:135]
	ds_read_b128 v[102:105], v118
	s_waitcnt lgkmcnt(1)
	global_store_dwordx4 v[114:115], v[98:101], off sc1
	v_cvt_pk_bf16_f32 v84, v84, v85
	v_cvt_pk_bf16_f32 v85, v86, v87
	v_add_u32_e32 v98, s6, v117
	v_ashrrev_i32_e32 v99, 31, v98
	v_lshlrev_b64 v[98:99], 11, v[98:99]
	v_lshl_add_u64 v[98:99], s[56:57], 0, v[98:99]
	v_lshl_add_u64 v[98:99], v[98:99], 0, v[106:107]
	v_lshl_add_u64 v[98:99], v[98:99], 0, v[128:129]
	v_cvt_pk_bf16_f32 v80, v80, v81
	v_cvt_pk_bf16_f32 v81, v82, v83
	s_waitcnt lgkmcnt(0)
	global_store_dwordx4 v[98:99], v[102:105], off sc1
	s_barrier
	ds_write2_b64 v130, v[92:93], v[88:89] offset1:4
	ds_write2_b64 v120, v[84:85], v[80:81] offset0:32 offset1:36
	v_cvt_pk_bf16_f32 v76, v76, v77
	v_cvt_pk_bf16_f32 v77, v78, v79
	v_cvt_pk_bf16_f32 v72, v72, v73
	v_cvt_pk_bf16_f32 v73, v74, v75
	v_cvt_pk_bf16_f32 v68, v68, v69
	v_cvt_pk_bf16_f32 v69, v70, v71
	v_cvt_pk_bf16_f32 v64, v64, v65
	v_cvt_pk_bf16_f32 v65, v66, v67
	ds_write2_b64 v121, v[76:77], v[72:73] offset0:64 offset1:68
	ds_write2_b64 v122, v[68:69], v[64:65] offset0:96 offset1:100
	s_waitcnt lgkmcnt(0)
	s_barrier
	ds_read_b128 v[64:67], v96
	ds_read_b128 v[68:71], v110
	ds_read_b128 v[72:75], v116
	ds_read_b128 v[76:79], v118
	v_cvt_pk_bf16_f32 v60, v60, v61
	v_cvt_pk_bf16_f32 v61, v62, v63
	v_cvt_pk_bf16_f32 v56, v56, v57
	v_cvt_pk_bf16_f32 v57, v58, v59
	v_cvt_pk_bf16_f32 v52, v52, v53
	v_cvt_pk_bf16_f32 v53, v54, v55
	v_cvt_pk_bf16_f32 v48, v48, v49
	v_cvt_pk_bf16_f32 v49, v50, v51
	s_waitcnt lgkmcnt(3)
	global_store_dwordx4 v[108:109], v[64:67], off offset:256 sc1
	s_waitcnt lgkmcnt(2)
	global_store_dwordx4 v[112:113], v[68:71], off offset:256 sc1
	s_waitcnt lgkmcnt(1)
	global_store_dwordx4 v[114:115], v[72:75], off offset:256 sc1
	s_waitcnt lgkmcnt(0)
	global_store_dwordx4 v[98:99], v[76:79], off offset:256 sc1
	s_barrier
	s_bitset1_b32 s6, 7
	ds_write2_b64 v130, v[60:61], v[56:57] offset1:4
	ds_write2_b64 v120, v[52:53], v[48:49] offset0:32 offset1:36
	v_cvt_pk_bf16_f32 v36, v36, v37
	v_cvt_pk_bf16_f32 v37, v38, v39
	v_cvt_pk_bf16_f32 v32, v32, v33
	v_cvt_pk_bf16_f32 v33, v34, v35
	v_cvt_pk_bf16_f32 v44, v44, v45
	v_cvt_pk_bf16_f32 v45, v46, v47
	v_cvt_pk_bf16_f32 v40, v40, v41
	v_cvt_pk_bf16_f32 v41, v42, v43
	ds_write2_b64 v122, v[36:37], v[32:33] offset0:96 offset1:100
	v_add_u32_e32 v32, s6, v123
	ds_write2_b64 v121, v[44:45], v[40:41] offset0:64 offset1:68
	v_ashrrev_i32_e32 v33, 31, v32
	s_waitcnt lgkmcnt(0)
	s_barrier
	v_lshlrev_b64 v[36:37], 11, v[32:33]
	ds_read_b128 v[32:35], v96
	v_lshl_add_u64 v[36:37], s[56:57], 0, v[36:37]
	v_lshl_add_u64 v[36:37], v[36:37], 0, v[106:107]
	v_lshl_add_u64 v[40:41], v[36:37], 0, v[128:129]
	ds_read_b128 v[36:39], v110
	s_waitcnt lgkmcnt(1)
	global_store_dwordx4 v[40:41], v[32:35], off sc1
	v_cvt_pk_bf16_f32 v28, v28, v29
	v_cvt_pk_bf16_f32 v29, v30, v31
	v_add_u32_e32 v32, s6, v97
	v_ashrrev_i32_e32 v33, 31, v32
	v_lshlrev_b64 v[32:33], 11, v[32:33]
	v_lshl_add_u64 v[32:33], s[56:57], 0, v[32:33]
	v_lshl_add_u64 v[32:33], v[32:33], 0, v[106:107]
	v_lshl_add_u64 v[42:43], v[32:33], 0, v[128:129]
	v_add_u32_e32 v32, s6, v111
	v_ashrrev_i32_e32 v33, 31, v32
	s_waitcnt lgkmcnt(0)
	global_store_dwordx4 v[42:43], v[36:39], off sc1
	v_cvt_pk_bf16_f32 v24, v24, v25
	v_cvt_pk_bf16_f32 v25, v26, v27
	v_lshlrev_b64 v[36:37], 11, v[32:33]
	ds_read_b128 v[32:35], v116
	v_lshl_add_u64 v[36:37], s[56:57], 0, v[36:37]
	v_lshl_add_u64 v[36:37], v[36:37], 0, v[106:107]
	v_lshl_add_u64 v[44:45], v[36:37], 0, v[128:129]
	ds_read_b128 v[36:39], v118
	s_waitcnt lgkmcnt(1)
	global_store_dwordx4 v[44:45], v[32:35], off sc1
	v_cvt_pk_bf16_f32 v20, v20, v21
	v_cvt_pk_bf16_f32 v21, v22, v23
	v_add_u32_e32 v32, s6, v117
	v_ashrrev_i32_e32 v33, 31, v32
	v_lshlrev_b64 v[32:33], 11, v[32:33]
	v_lshl_add_u64 v[32:33], s[56:57], 0, v[32:33]
	v_lshl_add_u64 v[32:33], v[32:33], 0, v[106:107]
	v_lshl_add_u64 v[32:33], v[32:33], 0, v[128:129]
	v_cvt_pk_bf16_f32 v16, v16, v17
	v_cvt_pk_bf16_f32 v17, v18, v19
	s_waitcnt lgkmcnt(0)
	global_store_dwordx4 v[32:33], v[36:39], off sc1
	s_barrier
	ds_write2_b64 v130, v[28:29], v[24:25] offset1:4
	ds_write2_b64 v120, v[20:21], v[16:17] offset0:32 offset1:36
	v_cvt_pk_bf16_f32 v12, v12, v13
	v_cvt_pk_bf16_f32 v13, v14, v15
	v_cvt_pk_bf16_f32 v8, v8, v9
	v_cvt_pk_bf16_f32 v9, v10, v11
	v_cvt_pk_bf16_f32 v4, v4, v5
	v_cvt_pk_bf16_f32 v5, v6, v7
	v_cvt_pk_bf16_f32 v0, v0, v1
	v_cvt_pk_bf16_f32 v1, v2, v3
	ds_write2_b64 v121, v[12:13], v[8:9] offset0:64 offset1:68
	ds_write2_b64 v122, v[4:5], v[0:1] offset0:96 offset1:100
	s_waitcnt lgkmcnt(0)
	s_barrier
	ds_read_b128 v[0:3], v96
	ds_read_b128 v[4:7], v110
	ds_read_b128 v[8:11], v116
	ds_read_b128 v[12:15], v118
	s_add_i32 s23, s23, s50
	s_cmpk_lt_i32 s23, 0x400
	s_waitcnt lgkmcnt(3)
	global_store_dwordx4 v[40:41], v[0:3], off offset:256 sc1
	s_waitcnt lgkmcnt(2)
	global_store_dwordx4 v[42:43], v[4:7], off offset:256 sc1
	s_waitcnt lgkmcnt(1)
	global_store_dwordx4 v[44:45], v[8:11], off offset:256 sc1
	s_waitcnt lgkmcnt(0)
	global_store_dwordx4 v[32:33], v[12:15], off offset:256 sc1
	s_barrier
	s_cbranch_scc0 .LBB0_1296

	.amdhsa_kernel _Z14fwd_megakernel6Params
		.amdhsa_group_segment_fixed_size 147712
		.amdhsa_private_segment_fixed_size 0
		.amdhsa_kernarg_size 464
		.amdhsa_user_sgpr_count 2
		.amdhsa_user_sgpr_dispatch_ptr 0
		.amdhsa_user_sgpr_queue_ptr 0
		.amdhsa_user_sgpr_kernarg_segment_ptr 1
		.amdhsa_user_sgpr_dispatch_id 0
		.amdhsa_user_sgpr_kernarg_preload_length 0
		.amdhsa_user_sgpr_kernarg_preload_offset 0
		.amdhsa_user_sgpr_private_segment_size 0
		.amdhsa_uses_dynamic_stack 0
		.amdhsa_enable_private_segment 0
		.amdhsa_system_sgpr_workgroup_id_x 1
		.amdhsa_system_sgpr_workgroup_id_y 0
		.amdhsa_system_sgpr_workgroup_id_z 0
		.amdhsa_system_sgpr_workgroup_info 0
		.amdhsa_system_vgpr_workitem_id 2
		.amdhsa_next_free_vgpr 256
		.amdhsa_next_free_sgpr 102
		.amdhsa_accum_offset 256
		.amdhsa_reserve_vcc 1
		.amdhsa_float_round_mode_32 0
		.amdhsa_float_round_mode_16_64 0
		.amdhsa_float_denorm_mode_32 3
		.amdhsa_float_denorm_mode_16_64 3
		.amdhsa_dx10_clamp 1
		.amdhsa_ieee_mode 1
		.amdhsa_fp16_overflow 0
		.amdhsa_tg_split 0
		.amdhsa_exception_fp_ieee_invalid_op 0
		.amdhsa_exception_fp_denorm_src 0
		.amdhsa_exception_fp_ieee_div_zero 0
		.amdhsa_exception_fp_ieee_overflow 0
		.amdhsa_exception_fp_ieee_underflow 0
		.amdhsa_exception_fp_ieee_inexact 0
		.amdhsa_exception_int_div_zero 0
	.end_amdhsa_kernel

amdhsa.kernels:
  - .agpr_count:     0
    .args:
      - .offset:         0
        .size:           208
        .value_kind:     by_value
      - .offset:         208
        .size:           4
        .value_kind:     hidden_block_count_x
      - .offset:         212
        .size:           4
        .value_kind:     hidden_block_count_y
      - .offset:         216
        .size:           4
        .value_kind:     hidden_block_count_z
      - .offset:         220
        .size:           2
        .value_kind:     hidden_group_size_x
      - .offset:         222
        .size:           2
        .value_kind:     hidden_group_size_y
      - .offset:         224
        .size:           2
        .value_kind:     hidden_group_size_z
      - .offset:         226
        .size:           2
        .value_kind:     hidden_remainder_x
      - .offset:         228
        .size:           2
        .value_kind:     hidden_remainder_y
      - .offset:         230
        .size:           2
        .value_kind:     hidden_remainder_z
      - .offset:         248
        .size:           8
        .value_kind:     hidden_global_offset_x
      - .offset:         256
        .size:           8
        .value_kind:     hidden_global_offset_y
      - .offset:         264
        .size:           8
        .value_kind:     hidden_global_offset_z
      - .offset:         272
        .size:           2
        .value_kind:     hidden_grid_dims
      - .offset:         296
        .size:           8
        .value_kind:     hidden_multigrid_sync_arg
    .group_segment_fixed_size: 147712
    .kernarg_segment_align: 8
    .kernarg_segment_size: 464
    .language:       OpenCL C
    .language_version:
      - 2
      - 0
    .max_flat_workgroup_size: 512
    .name:           _Z14fwd_megakernel6Params
    .private_segment_fixed_size: 0
    .sgpr_count:     108
    .sgpr_spill_count: 45
    .symbol:         _Z14fwd_megakernel6Params.kd
    .uniform_work_group_size: 1
    .uses_dynamic_stack: false
    .vgpr_count:     256
    .vgpr_spill_count: 0
    .wavefront_size: 64
